# software-pipelined outproj gate K-loop (double-buffered fragments, ks1 MFMAs deferred past barrier) + flat->global for wide accesses, on top of rotated 8x4 loops
# speedup vs baseline: 1.0246x; 1.0246x over previous
; DI void phase_prep(const Params& P, int l, char* shm) {
;     ...
;         float* d = tile + kk * 65 + n4;
;         d[0] = v.x; d[1] = v.y; d[2] = v.z; d[3] = v.w;
;       }
;       __syncthreads();
;       {
;         int nl = tid >> 3, k8 = (tid & 7) * 8;
;         const float* s = tile + k8 * 65 + nl;
;         i32x4 o;
;         o[0] = (int)pack2(s[0], s[65]);
;         o[1] = (int)pack2(s[130], s[195]);
;         o[2] = (int)pack2(s[260], s[325]);
;         o[3] = (int)pack2(s[390], s[455]);
;         *(i32x4*)(J.dst + (size_t)(tn * 64 + nl) * J.K + tk * 64 + k8) = o;
;       }
;       __syncthreads();
.LBB0_27:
	s_or_b64 exec, exec, s[60:61]
	s_waitcnt vmcnt(0)
	ds_write2_b32 v15, v0, v1 offset1:1
	ds_write2_b32 v15, v2, v3 offset0:2 offset1:3
	s_waitcnt lgkmcnt(0)
	s_barrier
	ds_read2_b32 v[0:1], v11 offset1:65
	ds_read2_b32 v[2:3], v11 offset0:130 offset1:195
	ds_read2_b32 v[4:5], v16 offset0:134 offset1:199
	s_ashr_i32 s59, s58, 31
	s_add_i32 s90, s90, s72
	s_waitcnt lgkmcnt(2)
	v_cvt_pk_bf16_f32 v0, v0, v1
	s_waitcnt lgkmcnt(1)
	v_cvt_pk_bf16_f32 v1, v2, v3
	ds_read2_b32 v[2:3], v16 offset0:4 offset1:69
	s_cmpk_gt_i32 s90, 0xe0f
	s_waitcnt lgkmcnt(0)
	v_cvt_pk_bf16_f32 v2, v2, v3
	v_cvt_pk_bf16_f32 v3, v4, v5
	v_add_u32_e32 v4, s4, v10
	v_ashrrev_i32_e32 v7, 31, v4
	v_mad_u64_u32 v[4:5], s[4:5], v4, s97, 0
	v_mov_b32_e32 v6, v5
	v_mad_u64_u32 v[6:7], s[4:5], v7, s97, v[6:7]
	v_mov_b32_e32 v5, v6
	v_lshl_add_u64 v[4:5], v[4:5], 1, s[10:11]
	v_lshl_add_u64 v[4:5], s[58:59], 1, v[4:5]
	v_lshl_add_u64 v[4:5], v[4:5], 0, v[132:133]
	global_store_dwordx4 v[4:5], v[0:3], off
	s_waitcnt lgkmcnt(0)
	s_barrier
	s_cbranch_scc1 .LBB0_98

; DI void phase_prep(const Params& P, int l, char* shm) {
;     ...
;     for (int i = gtid; i < T_TOK * 256 / 8; i += gn) {
;       float4 a = *(const float4*)(src + (size_t)i * 8), b = *(const float4*)(src + (size_t)i * 8 + 4);
;       i32x4 o;
;       o[0] = (int)pack2(a.x, a.y); o[1] = (int)pack2(a.z, a.w); o[2] = (int)pack2(b.x, b.y); o[3] = (int)pack2(b.z, b.w);
;       *(i32x4*)(dst + (size_t)i * 8) = o;
;     }
.LBB0_110:
	global_load_dwordx4 v[6:9], v[4:5], off offset:-16
	global_load_dwordx4 v[10:13], v[4:5], off
	v_add_u32_e32 v0, s4, v0
	v_cmp_lt_i32_e32 vcc, s29, v0
	v_lshl_add_u64 v[4:5], v[4:5], 0, s[8:9]
	s_or_b64 s[10:11], vcc, s[10:11]
	s_waitcnt vmcnt(0)
	v_cvt_pk_bf16_f32 v6, v6, v7
	v_cvt_pk_bf16_f32 v7, v8, v9
	v_cvt_pk_bf16_f32 v8, v10, v11
	v_cvt_pk_bf16_f32 v9, v12, v13
	global_store_dwordx4 v[2:3], v[6:9], off
	v_lshl_add_u64 v[2:3], v[2:3], 0, s[0:1]
	s_andn2_b64 exec, exec, s[10:11]
	s_cbranch_execnz .LBB0_110

; DI void phase_rope(const Params& P) {
;     ...
;   for (int i = gtid; i < T_TOK * 32; i += gn) {
;     const int t = i >> 5, f = i & 31;
;     const float freq = exp2f(-(float)f * (13.287712379549449f / 32.f));
;     const float ang = (float)P.pos[t] * freq;
;     tab[i] = make_float2(cosf(ang), sinf(ang));
;   }
.LBB0_114:
	s_or_b64 exec, exec, s[0:1]
	v_mul_f32_e32 v8, v7, v7
	v_fmamk_f32 v9, v8, 0xb94c1982, v202
	v_fmaak_f32 v9, v8, v9, 0xbe2aaa9d
	v_mul_f32_e32 v9, v8, v9
	v_fmac_f32_e32 v7, v7, v9
	v_fmamk_f32 v9, v8, 0x37d75334, v203
	v_fmaak_f32 v9, v8, v9, 0x3d2aabf7
	v_fmaak_f32 v9, v8, v9, 0xbf000004
	v_fma_f32 v8, v8, v9, 1.0
	v_and_b32_e32 v9, 1, v6
	v_cmp_eq_u32_e32 vcc, 0, v9
	v_lshlrev_b32_e32 v6, 30, v6
	s_brev_b32 s0, 1
	v_cndmask_b32_e64 v7, -v7, v8, vcc
	v_bitop3_b32 v6, v6, v7, s0 bitop3:0x6c
	v_mul_f32_e32 v7, v11, v11
	v_fmamk_f32 v8, v7, 0xb94c1982, v202
	v_fmaak_f32 v8, v7, v8, 0xbe2aaa9d
	v_mul_f32_e32 v8, v7, v8
	v_fmac_f32_e32 v11, v11, v8
	v_fmamk_f32 v8, v7, 0x37d75334, v203
	v_fmaak_f32 v8, v7, v8, 0x3d2aabf7
	v_fmaak_f32 v8, v7, v8, 0xbf000004
	v_fma_f32 v7, v7, v8, 1.0
	v_and_b32_e32 v8, 1, v10
	v_cmp_eq_u32_e32 vcc, 0, v8
	v_lshlrev_b32_e32 v8, 30, v10
	v_and_b32_e32 v8, 0x80000000, v8
	v_xor_b32_e32 v5, v5, v1
	v_cndmask_b32_e32 v7, v7, v11, vcc
	v_xor_b32_e32 v5, v5, v8
	s_movk_i32 s0, 0x1f8
	v_xor_b32_e32 v5, v5, v7
	v_cmp_class_f32_e64 vcc, v1, s0
	v_add_u32_e32 v0, s80, v0
	v_readlane_b32 s0, v252, 6
	v_cndmask_b32_e32 v6, v207, v6, vcc
	v_cndmask_b32_e32 v7, v207, v5, vcc
	v_add_co_u32_e32 v8, vcc, -4, v2
	v_readlane_b32 s1, v252, 7
	s_nop 0
	v_addc_co_u32_e32 v9, vcc, -1, v3, vcc
	v_cmp_lt_i32_e32 vcc, s29, v0
	s_or_b64 s[10:11], vcc, s[10:11]
	v_lshl_add_u64 v[2:3], v[2:3], 0, s[0:1]
	global_store_dwordx2 v[8:9], v[6:7], off
	s_andn2_b64 exec, exec, s[10:11]
	s_cbranch_execz .LBB0_123

; DI void phase_norm(const float* xin, u16* hb) {
;     ...
;   for (int t = gw; t < T_TOK; t += nw) {
;     const float* r = xin + (size_t)t * DM;
;     float4 v[4];
;     float ss = 0.f;
; #pragma unroll
;     for (int i = 0; i < 4; ++i) {
;       v[i] = *(const float4*)(r + i * 256 + lane * 4);
;       ss += v[i].x * v[i].x + v[i].y * v[i].y + v[i].z * v[i].z + v[i].w * v[i].w;
;     }
; #pragma unroll
;     for (int o = 32; o > 0; o >>= 1) ss += __shfl_xor(ss, o);
;     const float rs = rsqrtf(ss * (1.f / DM) + EPS);
; #pragma unroll
;     for (int i = 0; i < 4; ++i) {
;       u32x2 o = {pack2(v[i].x * rs, v[i].y * rs), pack2(v[i].z * rs, v[i].w * rs)};
;       *(u32x2*)(hb + (size_t)t * DM + i * 256 + lane * 4) = o;
;     }
;   }
.LBB0_126:
	global_load_dwordx4 v[12:15], v[4:5], off
	global_load_dwordx4 v[16:19], v[4:5], off offset:1024
	v_add_u32_e32 v0, s84, v0
	s_waitcnt vmcnt(0) lgkmcnt(0)
	v_mov_b32_e32 v26, v13
	v_mov_b32_e32 v27, v17
	v_mov_b32_e32 v24, v12
	v_mov_b32_e32 v25, v16
	v_pk_mul_f32 v[26:27], v[26:27], v[26:27]
	v_mov_b32_e32 v20, v14
	v_mov_b32_e32 v21, v18
	v_pk_fma_f32 v[24:25], v[24:25], v[24:25], v[26:27]
	v_mov_b32_e32 v22, v15
	v_mov_b32_e32 v23, v19
	v_pk_fma_f32 v[20:21], v[20:21], v[20:21], v[24:25]
	s_nop 0
	v_pk_fma_f32 v[28:29], v[22:23], v[22:23], v[20:21]
	global_load_dwordx4 v[20:23], v[4:5], off offset:2048
	global_load_dwordx4 v[24:27], v[4:5], off offset:3072
	v_add_f32_e32 v1, v28, v29
	v_lshl_add_u64 v[4:5], v[4:5], 0, s[14:15]
	s_waitcnt vmcnt(0) lgkmcnt(0)
	v_mov_b32_e32 v36, v21
	v_mov_b32_e32 v37, v25
	v_mov_b32_e32 v34, v20
	v_mov_b32_e32 v35, v24
	v_pk_mul_f32 v[36:37], v[36:37], v[36:37]
	v_mov_b32_e32 v30, v22
	v_mov_b32_e32 v31, v26
	v_pk_fma_f32 v[34:35], v[34:35], v[34:35], v[36:37]
	v_mov_b32_e32 v32, v23
	v_mov_b32_e32 v33, v27
	v_pk_fma_f32 v[30:31], v[30:31], v[30:31], v[34:35]
	s_nop 0
	v_pk_fma_f32 v[30:31], v[32:33], v[32:33], v[30:31]
	s_nop 0
	v_add_f32_e32 v1, v1, v30
	v_add_f32_e32 v1, v1, v31
	ds_bpermute_b32 v28, v6, v1
	s_waitcnt lgkmcnt(0)
	v_add_f32_e32 v1, v1, v28
	ds_bpermute_b32 v28, v7, v1
	s_waitcnt lgkmcnt(0)
	v_add_f32_e32 v1, v1, v28
	ds_bpermute_b32 v28, v8, v1
	s_waitcnt lgkmcnt(0)
	v_add_f32_e32 v1, v1, v28
	ds_bpermute_b32 v28, v9, v1
	s_waitcnt lgkmcnt(0)
	v_add_f32_e32 v1, v1, v28
	ds_bpermute_b32 v28, v10, v1
	s_waitcnt lgkmcnt(0)
	v_add_f32_e32 v1, v1, v28
	ds_bpermute_b32 v28, v11, v1
	s_waitcnt lgkmcnt(0)
	v_add_f32_e32 v1, v1, v28
	v_fmamk_f32 v1, v1, 0x3a800000, v134
	v_cmp_gt_f32_e32 vcc, s33, v1
	v_mul_f32_e32 v28, 0x4b800000, v1
	s_nop 0
	v_cndmask_b32_e32 v1, v1, v28, vcc
	v_rsq_f32_e32 v1, v1
	s_nop 0
	v_mul_f32_e32 v28, 0x45800000, v1
	v_cndmask_b32_e32 v28, v1, v28, vcc
	v_pk_mul_f32 v[12:13], v[12:13], v[28:29] op_sel_hi:[1,0]
	v_pk_mul_f32 v[14:15], v[14:15], v[28:29] op_sel_hi:[1,0]
	v_cvt_pk_bf16_f32 v12, v12, v13
	v_cvt_pk_bf16_f32 v13, v14, v15
	global_store_dwordx2 v[2:3], v[12:13], off
	v_pk_mul_f32 v[12:13], v[16:17], v[28:29] op_sel_hi:[1,0]
	v_pk_mul_f32 v[14:15], v[18:19], v[28:29] op_sel_hi:[1,0]
	v_cvt_pk_bf16_f32 v12, v12, v13
	v_cvt_pk_bf16_f32 v13, v14, v15
	global_store_dwordx2 v[2:3], v[12:13], off offset:512
	v_pk_mul_f32 v[12:13], v[20:21], v[28:29] op_sel_hi:[1,0]
	v_pk_mul_f32 v[14:15], v[22:23], v[28:29] op_sel_hi:[1,0]
	v_cvt_pk_bf16_f32 v12, v12, v13
	v_cvt_pk_bf16_f32 v13, v14, v15
	global_store_dwordx2 v[2:3], v[12:13], off offset:1024
	v_pk_mul_f32 v[12:13], v[24:25], v[28:29] op_sel_hi:[1,0]
	v_pk_mul_f32 v[14:15], v[26:27], v[28:29] op_sel_hi:[1,0]
	v_cvt_pk_bf16_f32 v12, v12, v13
	v_cvt_pk_bf16_f32 v13, v14, v15
	v_cmp_lt_i32_e32 vcc, s60, v0
	global_store_dwordx2 v[2:3], v[12:13], off offset:1536
	v_lshl_add_u64 v[2:3], v[2:3], 0, s[12:13]
	s_or_b64 s[4:5], vcc, s[4:5]
	s_andn2_b64 exec, exec, s[4:5]
	s_cbranch_execnz .LBB0_126

; DI int tid_() { int t = threadIdx.x; asm volatile("" : "+v"(t)); return t; }
; template <int MODE>
; DI void phase_inproj(const Params& P, char* shm) {
;     ...
;     for (int i = 0; i < 16; ++i) {
;       const int chunk = tid_() + i * 512, row = chunk >> 5, c8 = (chunk & 31) * 8;
;       const i32x4 v = *(const i32x4*)(shm + row * 528 + c8 * 2);
;       const int gcol = bcol + c8;
;       u16* d = nullptr;
;       if (MODE == 0) {
;         if (gcol < 448) d = (u16*)(P.ws + OFF_PROJC) + (size_t)(brow + row) * 448 + gcol;
;         else if (gcol >= 512) d = (u16*)(P.ws + OFF_ACTC) + (size_t)(brow + row) * 512 + (gcol - 512);
;       } else if (MODE == 1) {
;         if (gcol < 1024) d = (u16*)(P.ws + OFF_PROJD) + (size_t)(brow + row) * 1024 + gcol;
;         else if (gcol < 1536) {
;           const int c2 = gcol - c8 - 1024 + row;
;           const int b = brow >> 13, s0 = brow & 8191;
;           d = (u16*)(P.ws + OFF_VTD) + ((size_t)((b * 4 + (c2 >> 7)) * 128 + (c2 & 127))) * SEQ + s0 + c8;
;         } else d = (u16*)(P.ws + OFF_ACTD) + (size_t)(brow + row) * 512 + (gcol - 1536);
;       } else if (MODE == 2) {
;         if (gcol < 1024) d = (u16*)(P.ws + OFF_PROJA) + (size_t)(brow + row) * 1024 + gcol;
;         else d = (u16*)(P.ws + OFF_ACTA) + (size_t)(brow + row) * 512 + (gcol - 1024);
;       } else {
;         if (gcol < 512) d = (u16*)(P.ws + OFF_PROJB) + (size_t)(brow + row) * 512 + gcol;
;         else d = (u16*)(P.ws + OFF_ACTB) + (size_t)(brow + row) * 512 + (gcol - 512);
;       }
;       if (d) *(i32x4*)d = v;
;     }
.LBB0_217:
	s_waitcnt lgkmcnt(0)
	global_store_dwordx4 v[4:5], v[0:3], off

; DI int tid_() { int t = threadIdx.x; asm volatile("" : "+v"(t)); return t; }
; template <int MODE>
; DI void phase_inproj(const Params& P, char* shm) {
;     ...
;     for (int i = 0; i < 16; ++i) {
;       const int chunk = tid_() + i * 512, row = chunk >> 5, c8 = (chunk & 31) * 8;
;       const i32x4 v = *(const i32x4*)(shm + row * 528 + c8 * 2);
;       const int gcol = bcol + c8;
;       u16* d = nullptr;
;       if (MODE == 0) {
;         if (gcol < 448) d = (u16*)(P.ws + OFF_PROJC) + (size_t)(brow + row) * 448 + gcol;
;         else if (gcol >= 512) d = (u16*)(P.ws + OFF_ACTC) + (size_t)(brow + row) * 512 + (gcol - 512);
;       } else if (MODE == 1) {
;         if (gcol < 1024) d = (u16*)(P.ws + OFF_PROJD) + (size_t)(brow + row) * 1024 + gcol;
;         else if (gcol < 1536) {
;           const int c2 = gcol - c8 - 1024 + row;
;           const int b = brow >> 13, s0 = brow & 8191;
;           d = (u16*)(P.ws + OFF_VTD) + ((size_t)((b * 4 + (c2 >> 7)) * 128 + (c2 & 127))) * SEQ + s0 + c8;
;         } else d = (u16*)(P.ws + OFF_ACTD) + (size_t)(brow + row) * 512 + (gcol - 1536);
;       } else if (MODE == 2) {
;         if (gcol < 1024) d = (u16*)(P.ws + OFF_PROJA) + (size_t)(brow + row) * 1024 + gcol;
;         else d = (u16*)(P.ws + OFF_ACTA) + (size_t)(brow + row) * 512 + (gcol - 1024);
;       } else {
;         if (gcol < 512) d = (u16*)(P.ws + OFF_PROJB) + (size_t)(brow + row) * 512 + gcol;
;         else d = (u16*)(P.ws + OFF_ACTB) + (size_t)(brow + row) * 512 + (gcol - 512);
;       }
;       if (d) *(i32x4*)d = v;
;     }
.LBB0_237:
	s_waitcnt lgkmcnt(0)
	global_store_dwordx4 v[4:5], v[0:3], off
	s_branch .LBB0_213

; DI int tid_() { int t = threadIdx.x; asm volatile("" : "+v"(t)); return t; }
; template <int MODE>
; DI void phase_inproj(const Params& P, char* shm) {
;     ...
; #pragma unroll 4
;     for (int i = 0; i < 16; ++i) {
;       const int chunk = tid_() + i * 512, row = chunk >> 5, c8 = (chunk & 31) * 8;
;       const i32x4 v = *(const i32x4*)(shm + row * 528 + c8 * 2);
;       const int gcol = bcol + c8;
;       u16* d = nullptr;
;       if (MODE == 0) {
;         if (gcol < 448) d = (u16*)(P.ws + OFF_PROJC) + (size_t)(brow + row) * 448 + gcol;
;         else if (gcol >= 512) d = (u16*)(P.ws + OFF_ACTC) + (size_t)(brow + row) * 512 + (gcol - 512);
;       } else if (MODE == 1) {
;         if (gcol < 1024) d = (u16*)(P.ws + OFF_PROJD) + (size_t)(brow + row) * 1024 + gcol;
;         else if (gcol < 1536) {
;           const int c2 = gcol - c8 - 1024 + row;
;           const int b = brow >> 13, s0 = brow & 8191;
;           d = (u16*)(P.ws + OFF_VTD) + ((size_t)((b * 4 + (c2 >> 7)) * 128 + (c2 & 127))) * SEQ + s0 + c8;
;         } else d = (u16*)(P.ws + OFF_ACTD) + (size_t)(brow + row) * 512 + (gcol - 1536);
;       } else if (MODE == 2) {
;         if (gcol < 1024) d = (u16*)(P.ws + OFF_PROJA) + (size_t)(brow + row) * 1024 + gcol;
;         else d = (u16*)(P.ws + OFF_ACTA) + (size_t)(brow + row) * 512 + (gcol - 1024);
;       } else {
;         if (gcol < 512) d = (u16*)(P.ws + OFF_PROJB) + (size_t)(brow + row) * 512 + gcol;
;         else d = (u16*)(P.ws + OFF_ACTB) + (size_t)(brow + row) * 512 + (gcol - 512);
;       }
;       if (d) *(i32x4*)d = v;
;     }
.LBB0_318:
	s_or_b64 exec, exec, s[6:7]
	s_addk_i32 s15, 0x800
	s_cmpk_eq_i32 s15, 0x2000
	s_waitcnt lgkmcnt(0)
	global_store_dwordx4 v[4:5], v[0:3], off
	s_cbranch_scc1 .LBB0_240

; DI int tid_() { int t = threadIdx.x; asm volatile("" : "+v"(t)); return t; }
; template <int MODE>
; DI void phase_inproj(const Params& P, char* shm) {
;     ...
;     for (int i = 0; i < 16; ++i) {
;       const int chunk = tid_() + i * 512, row = chunk >> 5, c8 = (chunk & 31) * 8;
;       const i32x4 v = *(const i32x4*)(shm + row * 528 + c8 * 2);
;       const int gcol = bcol + c8;
;       u16* d = nullptr;
;       if (MODE == 0) {
;         if (gcol < 448) d = (u16*)(P.ws + OFF_PROJC) + (size_t)(brow + row) * 448 + gcol;
;         else if (gcol >= 512) d = (u16*)(P.ws + OFF_ACTC) + (size_t)(brow + row) * 512 + (gcol - 512);
;       } else if (MODE == 1) {
;         if (gcol < 1024) d = (u16*)(P.ws + OFF_PROJD) + (size_t)(brow + row) * 1024 + gcol;
;         else if (gcol < 1536) {
;           const int c2 = gcol - c8 - 1024 + row;
;           const int b = brow >> 13, s0 = brow & 8191;
;           d = (u16*)(P.ws + OFF_VTD) + ((size_t)((b * 4 + (c2 >> 7)) * 128 + (c2 & 127))) * SEQ + s0 + c8;
;         } else d = (u16*)(P.ws + OFF_ACTD) + (size_t)(brow + row) * 512 + (gcol - 1536);
;       } else if (MODE == 2) {
;         if (gcol < 1024) d = (u16*)(P.ws + OFF_PROJA) + (size_t)(brow + row) * 1024 + gcol;
;         else d = (u16*)(P.ws + OFF_ACTA) + (size_t)(brow + row) * 512 + (gcol - 1024);
;       } else {
;         if (gcol < 512) d = (u16*)(P.ws + OFF_PROJB) + (size_t)(brow + row) * 512 + gcol;
;         else d = (u16*)(P.ws + OFF_ACTB) + (size_t)(brow + row) * 512 + (gcol - 512);
;       }
;       if (d) *(i32x4*)d = v;
;     }
.LBB0_324:
.LBB0_325:
	s_andn2_saveexec_b64 s[6:7], s[6:7]
	v_add_u32_e32 v4, s12, v8
	v_ashrrev_i32_e32 v5, 31, v4
	v_lshlrev_b64 v[4:5], 11, v[4:5]
	v_lshl_add_u64 v[4:5], s[10:11], 0, v[4:5]
	v_ashrrev_i32_e32 v7, 31, v6
	v_lshl_add_u64 v[4:5], v[6:7], 1, v[4:5]
	s_or_b64 exec, exec, s[6:7]
	s_waitcnt lgkmcnt(0)
	global_store_dwordx4 v[4:5], v[0:3], off
	v_cndmask_b32_e64 v4, 0, 1, s[0:1]
	v_cmp_ne_u32_e64 s[6:7], 1, v4
	v_mov_b32_e32 v0, v135
	s_nop 0
	v_add_u32_e32 v1, s15, v0
	v_add_u32_e32 v1, 0x200, v1
	v_ashrrev_i32_e32 v6, 5, v1
	v_lshlrev_b32_e32 v0, 3, v0
	v_and_b32_e32 v7, 0xf8, v0
	v_mul_lo_u32 v0, v6, s68
	v_lshl_add_u32 v0, v7, 1, v0
	ds_read_b128 v[0:3], v0
	v_or_b32_e32 v132, s14, v7
	v_cmp_lt_i32_e32 vcc, s91, v132
	s_and_saveexec_b64 s[16:17], vcc
	s_xor_b64 s[16:17], exec, s[16:17]
	s_cbranch_execz .LBB0_333
	s_and_b64 vcc, exec, s[6:7]
	s_mov_b64 s[18:19], -1
	s_cbranch_vccnz .LBB0_330
	v_add_u32_e32 v4, s12, v6
	v_ashrrev_i32_e32 v5, 31, v4
	v_lshlrev_b64 v[4:5], 10, v[4:5]
	v_lshl_add_u64 v[4:5], s[8:9], 0, v[4:5]
	v_lshl_add_u64 v[4:5], v[132:133], 1, v[4:5]
	v_lshl_add_u64 v[4:5], v[4:5], 0, s[44:45]
	s_mov_b64 s[18:19], 0

; DI int tid_() { int t = threadIdx.x; asm volatile("" : "+v"(t)); return t; }
; template <int MODE>
; DI void phase_inproj(const Params& P, char* shm) {
;     ...
;     for (int i = 0; i < 16; ++i) {
;       const int chunk = tid_() + i * 512, row = chunk >> 5, c8 = (chunk & 31) * 8;
;       const i32x4 v = *(const i32x4*)(shm + row * 528 + c8 * 2);
;       const int gcol = bcol + c8;
;       u16* d = nullptr;
;       if (MODE == 0) {
;         if (gcol < 448) d = (u16*)(P.ws + OFF_PROJC) + (size_t)(brow + row) * 448 + gcol;
;         else if (gcol >= 512) d = (u16*)(P.ws + OFF_ACTC) + (size_t)(brow + row) * 512 + (gcol - 512);
;       } else if (MODE == 1) {
;         if (gcol < 1024) d = (u16*)(P.ws + OFF_PROJD) + (size_t)(brow + row) * 1024 + gcol;
;         else if (gcol < 1536) {
;           const int c2 = gcol - c8 - 1024 + row;
;           const int b = brow >> 13, s0 = brow & 8191;
;           d = (u16*)(P.ws + OFF_VTD) + ((size_t)((b * 4 + (c2 >> 7)) * 128 + (c2 & 127))) * SEQ + s0 + c8;
;         } else d = (u16*)(P.ws + OFF_ACTD) + (size_t)(brow + row) * 512 + (gcol - 1536);
;       } else if (MODE == 2) {
;         if (gcol < 1024) d = (u16*)(P.ws + OFF_PROJA) + (size_t)(brow + row) * 1024 + gcol;
;         else d = (u16*)(P.ws + OFF_ACTA) + (size_t)(brow + row) * 512 + (gcol - 1024);
;       } else {
;         if (gcol < 512) d = (u16*)(P.ws + OFF_PROJB) + (size_t)(brow + row) * 512 + gcol;
;         else d = (u16*)(P.ws + OFF_ACTB) + (size_t)(brow + row) * 512 + (gcol - 512);
;       }
;       if (d) *(i32x4*)d = v;
;     }
.LBB0_332:
.LBB0_333:
	s_andn2_saveexec_b64 s[16:17], s[16:17]
	v_add_u32_e32 v4, s12, v6
	v_ashrrev_i32_e32 v5, 31, v4
	v_lshlrev_b64 v[4:5], 11, v[4:5]
	v_lshl_add_u64 v[4:5], s[10:11], 0, v[4:5]
	v_ashrrev_i32_e32 v7, 31, v132
	v_mov_b32_e32 v6, v132
	v_lshl_add_u64 v[4:5], v[6:7], 1, v[4:5]
	s_or_b64 exec, exec, s[16:17]
	s_waitcnt lgkmcnt(0)
	global_store_dwordx4 v[4:5], v[0:3], off
	s_nop 1
	v_mov_b32_e32 v0, v135
	s_nop 0
	v_add_u32_e32 v1, s15, v0
	v_add_u32_e32 v1, 0x400, v1
	v_ashrrev_i32_e32 v6, 5, v1
	v_lshlrev_b32_e32 v0, 3, v0
	v_and_b32_e32 v7, 0xf8, v0
	v_mul_lo_u32 v0, v6, s68
	v_lshl_add_u32 v0, v7, 1, v0
	ds_read_b128 v[0:3], v0
	v_or_b32_e32 v132, s14, v7
	v_cmp_lt_i32_e32 vcc, s91, v132
	s_and_saveexec_b64 s[16:17], vcc
	s_xor_b64 s[16:17], exec, s[16:17]
	s_cbranch_execz .LBB0_341
	s_and_b64 vcc, exec, s[6:7]
	s_mov_b64 s[18:19], -1
	s_cbranch_vccnz .LBB0_338
	v_add_u32_e32 v4, s12, v6
	v_ashrrev_i32_e32 v5, 31, v4
	v_lshlrev_b64 v[4:5], 10, v[4:5]
	v_lshl_add_u64 v[4:5], s[8:9], 0, v[4:5]
	v_lshl_add_u64 v[4:5], v[132:133], 1, v[4:5]
	v_lshl_add_u64 v[4:5], v[4:5], 0, s[44:45]
	s_mov_b64 s[18:19], 0

; DI int tid_() { int t = threadIdx.x; asm volatile("" : "+v"(t)); return t; }
; template <int MODE>
; DI void phase_inproj(const Params& P, char* shm) {
;     ...
;     for (int i = 0; i < 16; ++i) {
;       const int chunk = tid_() + i * 512, row = chunk >> 5, c8 = (chunk & 31) * 8;
;       const i32x4 v = *(const i32x4*)(shm + row * 528 + c8 * 2);
;       const int gcol = bcol + c8;
;       u16* d = nullptr;
;       if (MODE == 0) {
;         if (gcol < 448) d = (u16*)(P.ws + OFF_PROJC) + (size_t)(brow + row) * 448 + gcol;
;         else if (gcol >= 512) d = (u16*)(P.ws + OFF_ACTC) + (size_t)(brow + row) * 512 + (gcol - 512);
;       } else if (MODE == 1) {
;         if (gcol < 1024) d = (u16*)(P.ws + OFF_PROJD) + (size_t)(brow + row) * 1024 + gcol;
;         else if (gcol < 1536) {
;           const int c2 = gcol - c8 - 1024 + row;
;           const int b = brow >> 13, s0 = brow & 8191;
;           d = (u16*)(P.ws + OFF_VTD) + ((size_t)((b * 4 + (c2 >> 7)) * 128 + (c2 & 127))) * SEQ + s0 + c8;
;         } else d = (u16*)(P.ws + OFF_ACTD) + (size_t)(brow + row) * 512 + (gcol - 1536);
;       } else if (MODE == 2) {
;         if (gcol < 1024) d = (u16*)(P.ws + OFF_PROJA) + (size_t)(brow + row) * 1024 + gcol;
;         else d = (u16*)(P.ws + OFF_ACTA) + (size_t)(brow + row) * 512 + (gcol - 1024);
;       } else {
;         if (gcol < 512) d = (u16*)(P.ws + OFF_PROJB) + (size_t)(brow + row) * 512 + gcol;
;         else d = (u16*)(P.ws + OFF_ACTB) + (size_t)(brow + row) * 512 + (gcol - 512);
;       }
;       if (d) *(i32x4*)d = v;
;     }
.LBB0_340:
.LBB0_341:
	s_andn2_saveexec_b64 s[16:17], s[16:17]
	v_add_u32_e32 v4, s12, v6
	v_ashrrev_i32_e32 v5, 31, v4
	v_lshlrev_b64 v[4:5], 11, v[4:5]
	v_lshl_add_u64 v[4:5], s[10:11], 0, v[4:5]
	v_ashrrev_i32_e32 v7, 31, v132
	v_mov_b32_e32 v6, v132
	v_lshl_add_u64 v[4:5], v[6:7], 1, v[4:5]
	s_or_b64 exec, exec, s[16:17]
	s_waitcnt lgkmcnt(0)
	global_store_dwordx4 v[4:5], v[0:3], off
	s_nop 1
	v_mov_b32_e32 v0, v135
	s_nop 0
	v_add_u32_e32 v1, s15, v0
	v_add_u32_e32 v1, 0x600, v1
	v_ashrrev_i32_e32 v6, 5, v1
	v_lshlrev_b32_e32 v0, 3, v0
	v_and_b32_e32 v7, 0xf8, v0
	v_mul_lo_u32 v0, v6, s68
	v_lshl_add_u32 v0, v7, 1, v0
	ds_read_b128 v[0:3], v0
	v_or_b32_e32 v132, s14, v7
	v_cmp_lt_i32_e32 vcc, s91, v132
	s_and_saveexec_b64 s[16:17], vcc
	s_xor_b64 s[16:17], exec, s[16:17]
	s_cbranch_execz .LBB0_349
	s_and_b64 vcc, exec, s[6:7]
	s_mov_b64 s[6:7], -1
	s_cbranch_vccnz .LBB0_346
	v_add_u32_e32 v4, s12, v6
	v_ashrrev_i32_e32 v5, 31, v4
	v_lshlrev_b64 v[4:5], 10, v[4:5]
	v_lshl_add_u64 v[4:5], s[8:9], 0, v[4:5]
	v_lshl_add_u64 v[4:5], v[132:133], 1, v[4:5]
	v_lshl_add_u64 v[4:5], v[4:5], 0, s[44:45]
	s_mov_b64 s[6:7], 0

; DI float bflo(unsigned v) { return __uint_as_float(v << 16); }
; DI float bfhi(unsigned v) { return __uint_as_float(v & 0xffff0000u); }
;     ...
;   for (int it = blockIdx.x; it < 16 * 64; it += gridDim.x) {
;     const int bh = it >> 6, qb = it & 63, b = bh >> 2, h = bh & 3, T0 = qb * 128, t0 = T0 + wid * 16;
;     const u16* Kg = projD + (size_t)(b * SEQ) * 1024 + 512 + h * 128;
;     const u16* Vg = VT + (size_t)(bh * 128) * SEQ;
;     ...
;     const int kb_top = T0 + 64;
;     D_STAGE(0, kb_top);
;     const u16* qp = projD + (size_t)(b * SEQ + t0 + fr) * 1024 + h * 128 + fq * 8;
;     bf16x8 qf[4];
; #pragma unroll
;     for (int ks = 0; ks < 4; ++ks) qf[ks] = *(const bf16x8*)(qp + ks * 32);
;     f32x4 o[8];
; #pragma unroll
;     for (int i = 0; i < 8; ++i) o[i] = f32x4{0.f, 0.f, 0.f, 0.f};
;     float R = 0.f;
;     const int tq = t0 + fr;
;     const int kbw = (t0 >> 6) << 6;
;     int done = 0;
;     asm volatile("s_waitcnt vmcnt(0)" ::: "memory");
;     __syncthreads();
;     ...
;     u16* dp = actD + (size_t)(b * SEQ + t0 + fr) * 512 + h * 128 + fq * 4;
; #pragma unroll
;     for (int dvs = 0; dvs < 8; ++dvs) {
;       u32x2 gz = *(const u32x2*)(dp + dvs * 16);
;       u32x2 ov = {pack2(o[dvs][0] * bflo(gz[0]), o[dvs][1] * bfhi(gz[0])),
;                   pack2(o[dvs][2] * bflo(gz[1]), o[dvs][3] * bfhi(gz[1]))};
;       if (!dry) *(u32x2*)(dp + dvs * 16) = ov;
;     }
.LBB0_367:
	s_or_b64 exec, exec, s[66:67]
	v_lshlrev_b64 v[28:29], 10, v[72:73]
	v_lshl_add_u64 v[28:29], s[4:5], 0, v[28:29]
	s_lshl_b32 s74, s58, 1
	v_lshl_add_u64 v[28:29], v[28:29], 0, s[74:75]
	v_mov_b32_e32 v71, v133
	v_lshl_add_u64 v[28:29], v[28:29], 0, v[70:71]
	global_load_dwordx2 v[30:31], v[28:29], off
	s_add_i32 s57, s57, s72
	s_cmpk_lt_i32 s57, 0x400
	s_waitcnt vmcnt(0) lgkmcnt(0)
	v_lshlrev_b32_e32 v32, 16, v30
	v_and_b32_e32 v33, 0xffff0000, v30
	v_pk_mul_f32 v[32:33], v[44:45], v[32:33]
	s_nop 0
	v_cvt_pk_bf16_f32 v30, v32, v33
	v_lshlrev_b32_e32 v32, 16, v31
	v_and_b32_e32 v33, 0xffff0000, v31
	v_pk_mul_f32 v[32:33], v[46:47], v[32:33]
	s_nop 0
	v_cvt_pk_bf16_f32 v31, v32, v33
	global_store_dwordx2 v[28:29], v[30:31], off
	global_load_dwordx2 v[30:31], v[28:29], off offset:32
	s_waitcnt vmcnt(0) lgkmcnt(0)
	v_lshlrev_b32_e32 v32, 16, v30
	v_and_b32_e32 v33, 0xffff0000, v30
	v_lshlrev_b32_e32 v30, 16, v31
	v_and_b32_e32 v31, 0xffff0000, v31
	v_pk_mul_f32 v[24:25], v[24:25], v[32:33]
	v_pk_mul_f32 v[26:27], v[26:27], v[30:31]
	v_cvt_pk_bf16_f32 v24, v24, v25
	v_cvt_pk_bf16_f32 v25, v26, v27
	global_store_dwordx2 v[28:29], v[24:25], off offset:32
	global_load_dwordx2 v[24:25], v[28:29], off offset:64
	s_waitcnt vmcnt(0) lgkmcnt(0)
	v_lshlrev_b32_e32 v26, 16, v24
	v_and_b32_e32 v27, 0xffff0000, v24
	v_lshlrev_b32_e32 v24, 16, v25
	v_and_b32_e32 v25, 0xffff0000, v25
	v_pk_mul_f32 v[20:21], v[20:21], v[26:27]
	v_pk_mul_f32 v[22:23], v[22:23], v[24:25]
	v_cvt_pk_bf16_f32 v20, v20, v21
	v_cvt_pk_bf16_f32 v21, v22, v23
	global_store_dwordx2 v[28:29], v[20:21], off offset:64
	global_load_dwordx2 v[20:21], v[28:29], off offset:96
	s_waitcnt vmcnt(0) lgkmcnt(0)
	v_lshlrev_b32_e32 v22, 16, v20
	v_and_b32_e32 v23, 0xffff0000, v20
	v_lshlrev_b32_e32 v20, 16, v21
	v_and_b32_e32 v21, 0xffff0000, v21
	v_pk_mul_f32 v[16:17], v[16:17], v[22:23]
	v_pk_mul_f32 v[18:19], v[18:19], v[20:21]
	v_cvt_pk_bf16_f32 v16, v16, v17
	v_cvt_pk_bf16_f32 v17, v18, v19
	global_store_dwordx2 v[28:29], v[16:17], off offset:96
	global_load_dwordx2 v[16:17], v[28:29], off offset:128
	s_waitcnt vmcnt(0) lgkmcnt(0)
	v_lshlrev_b32_e32 v18, 16, v16
	v_and_b32_e32 v19, 0xffff0000, v16
	v_lshlrev_b32_e32 v16, 16, v17
	v_and_b32_e32 v17, 0xffff0000, v17
	v_pk_mul_f32 v[12:13], v[12:13], v[18:19]
	v_pk_mul_f32 v[14:15], v[14:15], v[16:17]
	v_cvt_pk_bf16_f32 v12, v12, v13
	v_cvt_pk_bf16_f32 v13, v14, v15
	global_store_dwordx2 v[28:29], v[12:13], off offset:128
	global_load_dwordx2 v[12:13], v[28:29], off offset:160
	s_waitcnt vmcnt(0) lgkmcnt(0)
	v_lshlrev_b32_e32 v14, 16, v12
	v_and_b32_e32 v15, 0xffff0000, v12
	v_lshlrev_b32_e32 v12, 16, v13
	v_and_b32_e32 v13, 0xffff0000, v13
	v_pk_mul_f32 v[8:9], v[8:9], v[14:15]
	v_pk_mul_f32 v[10:11], v[10:11], v[12:13]
	v_cvt_pk_bf16_f32 v8, v8, v9
	v_cvt_pk_bf16_f32 v9, v10, v11
	global_store_dwordx2 v[28:29], v[8:9], off offset:160
	global_load_dwordx2 v[8:9], v[28:29], off offset:192
	s_waitcnt vmcnt(0) lgkmcnt(0)
	v_lshlrev_b32_e32 v10, 16, v8
	v_and_b32_e32 v11, 0xffff0000, v8
	v_lshlrev_b32_e32 v8, 16, v9
	v_and_b32_e32 v9, 0xffff0000, v9
	v_pk_mul_f32 v[4:5], v[4:5], v[10:11]
	v_pk_mul_f32 v[6:7], v[6:7], v[8:9]
	v_cvt_pk_bf16_f32 v4, v4, v5
	v_cvt_pk_bf16_f32 v5, v6, v7
	global_store_dwordx2 v[28:29], v[4:5], off offset:192
	global_load_dwordx2 v[4:5], v[28:29], off offset:224
	s_waitcnt vmcnt(0) lgkmcnt(0)
	v_lshlrev_b32_e32 v6, 16, v4
	v_and_b32_e32 v7, 0xffff0000, v4
	v_lshlrev_b32_e32 v4, 16, v5
	v_and_b32_e32 v5, 0xffff0000, v5
	v_pk_mul_f32 v[0:1], v[0:1], v[6:7]
	v_pk_mul_f32 v[2:3], v[2:3], v[4:5]
	v_cvt_pk_bf16_f32 v0, v0, v1
	v_cvt_pk_bf16_f32 v1, v2, v3
	global_store_dwordx2 v[28:29], v[0:1], off offset:224
	s_waitcnt lgkmcnt(0)
	s_barrier
	s_cbranch_scc0 .LBB0_403
.LBB0_368:
	s_lshl_b32 s10, s57, 7
	s_and_b32 s70, s10, 0x1f80
	s_lshl_b32 s10, s57, 5
	s_and_b32 s10, s10, 0xffffe000
	s_ashr_i32 s11, s10, 31
	s_lshl_b64 s[12:13], s[10:11], 11
	s_add_u32 s11, s0, s12
	s_addc_u32 s13, s1, s13
	s_lshl_b32 s14, s57, 1
	s_and_b32 s58, s14, 0x180
	s_and_b32 s12, s14, 0xffffff80
	s_lshl_b32 s74, s58, 1
	s_add_u32 s14, s11, s74
	s_addc_u32 s15, s13, 0
	s_add_u32 s46, s14, 0x400
	s_addc_u32 s47, s15, 0
	s_lshl_b32 s11, s70, 10
	s_bitset1_b32 s11, 16
	v_add_u32_e32 v0, s11, v78
	v_ashrrev_i32_e32 v1, 31, v0
	v_lshl_add_u64 v[0:1], v[0:1], 1, s[14:15]
	s_mov_b64 s[16:17], 0x400
	s_mov_b32 m0, s55
	v_lshl_add_u64 v[0:1], v[0:1], 0, s[16:17]
	global_load_lds_dwordx4 v[0:1], off
	v_add_u32_e32 v0, s11, v79
	s_ashr_i32 s13, s12, 31
	v_ashrrev_i32_e32 v1, 31, v0
	s_lshl_b64 s[12:13], s[12:13], 14
	v_lshl_add_u64 v[0:1], v[0:1], 1, s[14:15]
	s_add_i32 m0, s55, 0x2000
	v_lshl_add_u64 v[0:1], v[0:1], 0, s[16:17]
	s_add_u32 s64, s52, s12
	s_mov_b32 s71, s75
	global_load_lds_dwordx4 v[0:1], off
	s_addc_u32 s65, s53, s13
	v_lshl_add_u64 v[0:1], s[70:71], 0, v[64:65]
	v_lshl_add_u64 v[0:1], v[0:1], 1, s[64:65]
	s_mov_b64 s[12:13], 0x80
	v_lshl_add_u64 v[0:1], v[0:1], 0, s[12:13]
	s_add_i32 m0, s55, 0x4000
	s_add_i32 s59, s70, s54
	global_load_lds_dwordx4 v[0:1], off
	v_lshl_add_u64 v[0:1], s[70:71], 0, v[66:67]
	s_add_i32 s10, s59, s10
	v_lshl_add_u64 v[0:1], v[0:1], 1, s[64:65]
	v_or_b32_e32 v72, s10, v80
	v_lshl_add_u64 v[0:1], v[0:1], 0, s[12:13]
	s_add_i32 m0, s55, 0x6000
	v_ashrrev_i32_e32 v73, 31, v72
	global_load_lds_dwordx4 v[0:1], off
	v_lshlrev_b64 v[0:1], 11, v[72:73]
	v_lshl_add_u64 v[0:1], s[0:1], 0, v[0:1]
	v_lshl_add_u64 v[0:1], v[0:1], 0, s[74:75]
	v_lshl_add_u64 v[0:1], v[0:1], 0, v[132:133]
	global_load_dwordx4 v[28:31], v[0:1], off
	global_load_dwordx4 v[32:35], v[0:1], off offset:64
	global_load_dwordx4 v[36:39], v[0:1], off offset:128
	global_load_dwordx4 v[40:43], v[0:1], off offset:192
	s_waitcnt vmcnt(0)
	s_lshl_b32 s10, s57, 17
	v_mov_b32_e32 v44, v133
	v_mov_b32_e32 v45, v133
	s_and_b32 s10, s10, 0x7e0000
	v_mov_b32_e32 v46, v133
	v_mov_b32_e32 v47, v133
	v_mov_b64_e32 v[24:25], v[44:45]
	v_mov_b64_e32 v[20:21], v[44:45]
	v_mov_b64_e32 v[16:17], v[44:45]
	v_mov_b64_e32 v[12:13], v[44:45]
	v_mov_b64_e32 v[8:9], v[44:45]
	v_mov_b64_e32 v[4:5], v[44:45]
	v_mov_b64_e32 v[0:1], v[44:45]
	v_or_b32_e32 v71, s59, v80
	s_andn2_b32 s59, s59, 63
	v_or_b32_e32 v86, s70, v68
	v_add_u32_e32 v74, s10, v82
	v_add_u32_e32 v76, s10, v83
	v_add_u32_e32 v87, s70, v84
	v_add_u32_e32 v88, s70, v85
	s_mov_b32 s60, 0
	v_mov_b32_e32 v89, 0
	s_mov_b64 s[66:67], 0
	v_mov_b32_e32 v48, 0
	v_mov_b64_e32 v[26:27], v[46:47]
	v_mov_b64_e32 v[22:23], v[46:47]
	v_mov_b64_e32 v[18:19], v[46:47]
	v_mov_b64_e32 v[14:15], v[46:47]
	v_mov_b64_e32 v[10:11], v[46:47]
	v_mov_b64_e32 v[6:7], v[46:47]
	v_mov_b64_e32 v[2:3], v[46:47]
	s_mov_b32 s61, 0
	s_waitcnt vmcnt(0) lgkmcnt(0)
	s_barrier
	s_branch .LBB0_370

; DI float bflo(unsigned v) { return __uint_as_float(v << 16); }
; DI float bfhi(unsigned v) { return __uint_as_float(v & 0xffff0000u); }
; DI int tid_() { int t = threadIdx.x; asm volatile("" : "+v"(t)); return t; }
; DI void rowscale_prologue(const u16* Ab, int lda, int K, float* rs) {
;   const int tid = tid_(), row = tid >> 1, half = tid & 1;
;   const u16* p = Ab + (long)row * lda + half * (K >> 1);
;   float ss = 0.f;
;   for (int i = 0; i < (K >> 4); ++i) {
;     i32x4 v = *(const i32x4*)(p + i * 8);
; #pragma unroll
;     for (int e = 0; e < 4; ++e) {
;       float a = bflo((unsigned)v[e]), b = bfhi((unsigned)v[e]);
;       ss += a * a + b * b;
;     }
;   }
;   ss += __shfl_xor(ss, 1);
;   if (half == 0) rs[row] = rsqrtf(ss / (float)K + EPS);
.LBB0_406:
	s_ashr_i32 s0, s24, 31
	s_lshr_b32 s0, s0, 29
	s_add_i32 s0, s24, s0
	s_ashr_i32 s1, s0, 3
	s_and_b32 s0, s0, -8
	s_sub_i32 s0, s24, s0
	s_lshr_b32 s4, s0, 31
	s_or_b32 s4, s4, 64
	s_mul_i32 s0, s4, s0
	s_add_i32 s0, s0, s1
	s_ashr_i32 s1, s0, 31
	s_lshr_b32 s1, s1, 27
	s_add_i32 s1, s0, s1
	s_ashr_i32 s4, s1, 5
	s_lshl_b32 s26, s4, 3
	s_sub_i32 s4, 0x80, s26
	s_min_u32 s4, s4, 8
	s_andn2_b32 s1, s1, 31
	s_sub_i32 s5, s0, s1
	v_cvt_f32_ubyte0_e32 v1, s4
	v_cvt_f32_i32_e32 v0, s5
	v_rcp_iflag_f32_e32 v2, v1
	s_ashr_i32 s0, s5, 30
	s_or_b32 s18, s0, 1
	v_mul_f32_e32 v2, v0, v2
	v_trunc_f32_e32 v2, v2
	v_fma_f32 v0, -v2, v1, v0
	v_cvt_i32_f32_e32 v2, v2
	v_cmp_ge_f32_e64 s[0:1], |v0|, v1
	s_and_b64 s[0:1], s[0:1], exec
	s_cselect_b32 s0, s18, 0
	v_readfirstlane_b32 s27, v2
	s_add_i32 s27, s27, s0
	s_mul_i32 s0, s27, s4
	s_sub_i32 s0, s5, s0
	s_sext_i32_i8 s0, s0
	s_add_i32 s26, s26, s0
	s_lshl_b32 s25, s26, 8
	s_mul_i32 s0, s26, 0x38000
	s_mul_hi_i32 s1, s25, 0x380
	s_add_u32 s0, s10, s0
	v_mov_b32_e32 v0, v135
	s_addc_u32 s1, s11, s1
	s_nop 0
	v_ashrrev_i32_e32 v4, 1, v0
	v_and_b32_e32 v5, 1, v0
	v_mov_b64_e32 v[0:1], s[0:1]
	v_mad_i64_i32 v[0:1], s[4:5], v4, s69, v[0:1]
	v_lshlrev_b32_e32 v132, 7, v5
	v_lshl_add_u64 v[0:1], v[0:1], 0, v[132:133]
	global_load_dwordx4 v[6:9], v[0:1], off offset:512
	s_waitcnt vmcnt(0) lgkmcnt(0)
	v_and_b32_e32 v3, 0xffff0000, v6
	v_lshlrev_b32_e32 v2, 16, v6
	v_mul_f32_e32 v3, v3, v3
	v_and_b32_e32 v6, 0xffff0000, v7
	v_fmac_f32_e32 v3, v2, v2
	v_lshlrev_b32_e32 v2, 16, v7
	v_mul_f32_e32 v6, v6, v6
	v_fmac_f32_e32 v6, v2, v2
	v_add_f32_e32 v2, v6, v3
	v_and_b32_e32 v6, 0xffff0000, v8
	v_lshlrev_b32_e32 v3, 16, v8
	v_mul_f32_e32 v6, v6, v6
	v_fmac_f32_e32 v6, v3, v3
	v_add_f32_e32 v2, v6, v2
	v_and_b32_e32 v6, 0xffff0000, v9
	v_lshlrev_b32_e32 v3, 16, v9
	v_mul_f32_e32 v6, v6, v6
	v_fmac_f32_e32 v6, v3, v3
	v_add_f32_e32 v2, v6, v2
	global_load_dwordx4 v[6:9], v[0:1], off offset:528
	s_waitcnt vmcnt(0) lgkmcnt(0)
	v_lshlrev_b32_e32 v3, 16, v6
	v_and_b32_e32 v6, 0xffff0000, v6
	v_mul_f32_e32 v6, v6, v6
	v_fmac_f32_e32 v6, v3, v3
	v_add_f32_e32 v2, v6, v2
	v_and_b32_e32 v6, 0xffff0000, v7
	v_lshlrev_b32_e32 v3, 16, v7
	v_mul_f32_e32 v6, v6, v6
	v_fmac_f32_e32 v6, v3, v3
	v_add_f32_e32 v2, v6, v2
	v_and_b32_e32 v6, 0xffff0000, v8
	v_lshlrev_b32_e32 v3, 16, v8
	v_mul_f32_e32 v6, v6, v6
	v_fmac_f32_e32 v6, v3, v3
	v_add_f32_e32 v2, v6, v2
	v_and_b32_e32 v6, 0xffff0000, v9
	v_lshlrev_b32_e32 v3, 16, v9
	v_mul_f32_e32 v6, v6, v6
	v_fmac_f32_e32 v6, v3, v3
	v_add_f32_e32 v2, v6, v2
	global_load_dwordx4 v[6:9], v[0:1], off offset:544
	s_waitcnt vmcnt(0) lgkmcnt(0)
	v_lshlrev_b32_e32 v3, 16, v6
	v_and_b32_e32 v6, 0xffff0000, v6
	v_mul_f32_e32 v6, v6, v6
	v_fmac_f32_e32 v6, v3, v3
	v_add_f32_e32 v2, v6, v2
	v_and_b32_e32 v6, 0xffff0000, v7
	v_lshlrev_b32_e32 v3, 16, v7
	v_mul_f32_e32 v6, v6, v6
	v_fmac_f32_e32 v6, v3, v3
	v_add_f32_e32 v2, v6, v2
	v_and_b32_e32 v6, 0xffff0000, v8
	v_lshlrev_b32_e32 v3, 16, v8
	v_mul_f32_e32 v6, v6, v6
	v_fmac_f32_e32 v6, v3, v3
	v_add_f32_e32 v2, v6, v2
	v_and_b32_e32 v6, 0xffff0000, v9
	v_lshlrev_b32_e32 v3, 16, v9
	v_mul_f32_e32 v6, v6, v6
	v_fmac_f32_e32 v6, v3, v3
	v_add_f32_e32 v2, v6, v2
	global_load_dwordx4 v[6:9], v[0:1], off offset:560
	s_waitcnt vmcnt(0) lgkmcnt(0)
	v_lshlrev_b32_e32 v3, 16, v6
	v_and_b32_e32 v6, 0xffff0000, v6
	v_mul_f32_e32 v6, v6, v6
	v_fmac_f32_e32 v6, v3, v3
	v_add_f32_e32 v2, v6, v2
	v_and_b32_e32 v6, 0xffff0000, v7
	v_lshlrev_b32_e32 v3, 16, v7
	v_mul_f32_e32 v6, v6, v6
	v_fmac_f32_e32 v6, v3, v3
	v_add_f32_e32 v2, v6, v2
	v_and_b32_e32 v6, 0xffff0000, v8
	v_lshlrev_b32_e32 v3, 16, v8
	v_mul_f32_e32 v6, v6, v6
	v_fmac_f32_e32 v6, v3, v3
	v_add_f32_e32 v2, v6, v2
	v_and_b32_e32 v6, 0xffff0000, v9
	v_lshlrev_b32_e32 v3, 16, v9
	v_mul_f32_e32 v6, v6, v6
	v_fmac_f32_e32 v6, v3, v3
	v_add_f32_e32 v2, v6, v2
	global_load_dwordx4 v[6:9], v[0:1], off offset:576
	s_waitcnt vmcnt(0) lgkmcnt(0)
	v_lshlrev_b32_e32 v3, 16, v6
	v_and_b32_e32 v6, 0xffff0000, v6
	v_mul_f32_e32 v6, v6, v6
	v_fmac_f32_e32 v6, v3, v3
	v_add_f32_e32 v2, v6, v2
	v_and_b32_e32 v6, 0xffff0000, v7
	v_lshlrev_b32_e32 v3, 16, v7
	v_mul_f32_e32 v6, v6, v6
	v_fmac_f32_e32 v6, v3, v3
	v_add_f32_e32 v2, v6, v2
	v_and_b32_e32 v6, 0xffff0000, v8
	v_lshlrev_b32_e32 v3, 16, v8
	v_mul_f32_e32 v6, v6, v6
	v_fmac_f32_e32 v6, v3, v3
	v_add_f32_e32 v2, v6, v2
	v_and_b32_e32 v6, 0xffff0000, v9
	v_lshlrev_b32_e32 v3, 16, v9
	v_mul_f32_e32 v6, v6, v6
	v_fmac_f32_e32 v6, v3, v3
	v_add_f32_e32 v2, v6, v2
	global_load_dwordx4 v[6:9], v[0:1], off offset:592
	s_waitcnt vmcnt(0) lgkmcnt(0)
	v_lshlrev_b32_e32 v3, 16, v6
	v_and_b32_e32 v6, 0xffff0000, v6
	v_mul_f32_e32 v6, v6, v6
	v_fmac_f32_e32 v6, v3, v3
	v_add_f32_e32 v2, v6, v2
	v_and_b32_e32 v6, 0xffff0000, v7
	v_lshlrev_b32_e32 v3, 16, v7
	v_mul_f32_e32 v6, v6, v6
	v_fmac_f32_e32 v6, v3, v3
	v_add_f32_e32 v2, v6, v2
	v_and_b32_e32 v6, 0xffff0000, v8
	v_lshlrev_b32_e32 v3, 16, v8
	v_mul_f32_e32 v6, v6, v6
	v_fmac_f32_e32 v6, v3, v3
	v_add_f32_e32 v2, v6, v2
	v_and_b32_e32 v6, 0xffff0000, v9
	v_lshlrev_b32_e32 v3, 16, v9
	v_mul_f32_e32 v6, v6, v6
	v_fmac_f32_e32 v6, v3, v3
	v_add_f32_e32 v2, v6, v2
	global_load_dwordx4 v[6:9], v[0:1], off offset:608
	s_waitcnt vmcnt(0) lgkmcnt(0)
	v_lshlrev_b32_e32 v3, 16, v6
	v_and_b32_e32 v6, 0xffff0000, v6
	v_mul_f32_e32 v6, v6, v6
	v_fmac_f32_e32 v6, v3, v3
	v_add_f32_e32 v2, v6, v2
	v_and_b32_e32 v6, 0xffff0000, v7
	v_lshlrev_b32_e32 v3, 16, v7
	v_mul_f32_e32 v6, v6, v6
	v_fmac_f32_e32 v6, v3, v3
	v_add_f32_e32 v2, v6, v2
	v_and_b32_e32 v6, 0xffff0000, v8
	v_lshlrev_b32_e32 v3, 16, v8
	v_mul_f32_e32 v6, v6, v6
	v_fmac_f32_e32 v6, v3, v3
	v_add_f32_e32 v2, v6, v2
	v_and_b32_e32 v6, 0xffff0000, v9
	v_lshlrev_b32_e32 v3, 16, v9
	v_mul_f32_e32 v6, v6, v6
	v_fmac_f32_e32 v6, v3, v3
	v_add_f32_e32 v6, v6, v2
	global_load_dwordx4 v[0:3], v[0:1], off offset:624
	s_waitcnt vmcnt(0) lgkmcnt(0)
	v_lshlrev_b32_e32 v7, 16, v0
	v_and_b32_e32 v0, 0xffff0000, v0
	v_mul_f32_e32 v0, v0, v0
	v_fmac_f32_e32 v0, v7, v7
	v_add_f32_e32 v0, v0, v6
	v_lshlrev_b32_e32 v6, 16, v1
	v_and_b32_e32 v1, 0xffff0000, v1
	v_mul_f32_e32 v1, v1, v1
	v_fmac_f32_e32 v1, v6, v6
	v_add_f32_e32 v0, v1, v0
	v_lshlrev_b32_e32 v1, 16, v2
	v_and_b32_e32 v2, 0xffff0000, v2
	v_mul_f32_e32 v2, v2, v2
	v_fmac_f32_e32 v2, v1, v1
	v_add_f32_e32 v0, v2, v0
	v_and_b32_e32 v2, 0xffff0000, v3
	v_lshlrev_b32_e32 v1, 16, v3
	v_mul_f32_e32 v2, v2, v2
	v_fmac_f32_e32 v2, v1, v1
	v_add_f32_e32 v0, v2, v0
	v_and_b32_e32 v2, 64, v204
	v_xor_b32_e32 v1, 1, v204
	v_add_u32_e32 v132, 64, v2
	v_cmp_lt_i32_e32 vcc, v1, v132
	s_nop 1
	v_cndmask_b32_e32 v1, v204, v1, vcc
	v_lshlrev_b32_e32 v162, 2, v1
	ds_bpermute_b32 v1, v162, v0
	v_cmp_eq_u32_e32 vcc, 0, v5
	s_and_saveexec_b64 s[4:5], vcc
	s_cbranch_execz .LBB0_408
; DI void rowscale_prologue(const u16* Ab, int lda, int K, float* rs) {
;     ...
;   ss += __shfl_xor(ss, 1);
;   if (half == 0) rs[row] = rsqrtf(ss / (float)K + EPS);
	s_waitcnt lgkmcnt(0)
	v_add_f32_e32 v0, v0, v1
	v_fmamk_f32 v0, v0, 0x3c000000, v134
	v_mul_f32_e32 v1, 0x4b800000, v0
	v_cmp_gt_f32_e32 vcc, s33, v0
	s_nop 1
	v_cndmask_b32_e32 v0, v0, v1, vcc
	v_rsq_f32_e32 v0, v0
	s_nop 0
	v_mul_f32_e32 v1, 0x45800000, v0
	v_cndmask_b32_e32 v0, v0, v1, vcc
	v_lshl_add_u32 v1, v4, 2, v210
	ds_write_b32 v1, v0

; DI float bflo(unsigned v) { return __uint_as_float(v << 16); }
; DI float bfhi(unsigned v) { return __uint_as_float(v & 0xffff0000u); }
; DI void phase_mla_up(const Params& P, int l, char* shm) {
;     ...
;       for (int i = 0; i < 8; ++i) {
;         const int chunk = tid_() + i * 512, row = chunk >> 4, j16 = chunk & 15, c8 = j16 * 8, t = brow + row;
;         const i32x4 v = *(const i32x4*)(shm + row * 272 + c8 * 2);
;         const u32x2 krr = *(const u32x2*)(projC + (size_t)t * 448 + 384 + j16 * 4);
;         float kv[8], kr[4];
; #pragma unroll
;         for (int e = 0; e < 4; ++e) { kv[2 * e] = bflo((unsigned)v[e]); kv[2 * e + 1] = bfhi((unsigned)v[e]); }
;         kr[0] = bflo(krr[0]); kr[1] = bfhi(krr[0]); kr[2] = bflo(krr[1]); kr[3] = bfhi(krr[1]);
;         float ss = 0.f;
; #pragma unroll
;         for (int e = 0; e < 8; ++e) ss += kv[e] * kv[e];
; #pragma unroll
;         for (int e = 0; e < 4; ++e) ss += kr[e] * kr[e];
;         ss += __shfl_xor(ss, 1); ss += __shfl_xor(ss, 2); ss += __shfl_xor(ss, 4); ss += __shfl_xor(ss, 8);
;         const float r = rsqrtf(ss * (1.f / 192.f) + EPS);
;         u16* kd = (u16*)(P.ws + OFF_KC) + ((size_t)((b * 4 + h) * SEQ + s0 + row)) * 192;
;         const f32x4 g0 = *(const f32x4*)(kng + c8), g1 = *(const f32x4*)(kng + c8 + 4);
;         i32x4 o;
;         o[0] = (int)pack2(kv[0] * r * g0[0], kv[1] * r * g0[1]);
;         o[1] = (int)pack2(kv[2] * r * g0[2], kv[3] * r * g0[3]);
;         o[2] = (int)pack2(kv[4] * r * g1[0], kv[5] * r * g1[1]);
;         o[3] = (int)pack2(kv[6] * r * g1[2], kv[7] * r * g1[3]);
;         *(i32x4*)(kd + c8) = o;
;         const f32x4 gr = *(const f32x4*)(kng + 128 + j16 * 4);
;         const f32x4* rt = (const f32x4*)(P.ws + OFF_ROPE) + (size_t)t * 16 + (j16 & 7) * 2;
;         const f32x4 cs01 = rt[0], cs23 = rt[1];
;         float my[4], ot[4], rv[4];
; #pragma unroll
;         for (int e = 0; e < 4; ++e) { my[e] = kr[e] * r * gr[e]; ot[e] = __shfl_xor(my[e], 8); }
;         const float sgn = (j16 < 8) ? -1.f : 1.f;
;         rv[0] = my[0] * cs01[0] + sgn * ot[0] * cs01[1];
;         rv[1] = my[1] * cs01[2] + sgn * ot[1] * cs01[3];
;         rv[2] = my[2] * cs23[0] + sgn * ot[2] * cs23[1];
;         rv[3] = my[3] * cs23[2] + sgn * ot[3] * cs23[3];
;         u32x2 ro = {pack2(rv[0], rv[1]), pack2(rv[2], rv[3])};
;         *(u32x2*)(kd + 128 + j16 * 4) = ro;
;       }
.LBB0_541:
	v_mov_b32_e32 v5, v135
	v_mov_b64_e32 v[18:19], s[10:11]
	v_add_u32_e32 v6, s5, v5
	v_ashrrev_i32_e32 v6, 4, v6
	v_and_b32_e32 v42, 15, v5
	v_add_u32_e32 v24, s25, v6
	v_lshlrev_b32_e32 v132, 3, v42
	v_mad_i64_i32 v[26:27], s[18:19], v24, s69, v[18:19]
	v_lshlrev_b32_e32 v5, 5, v5
	v_lshlrev_b32_e32 v22, 4, v42
	v_lshlrev_b32_e32 v10, 5, v42
	v_lshl_add_u64 v[26:27], v[26:27], 0, v[132:133]
	v_and_b32_e32 v20, 0xe0, v5
	v_mad_u64_u32 v[14:15], s[18:19], v6, s71, v[22:23]
	v_add_u32_e32 v5, s4, v6
	global_load_dwordx4 v[6:9], v10, s[12:13] offset:16
	s_nop 0
	global_load_dwordx4 v[10:13], v10, s[12:13]
	ds_read_b128 v[14:17], v14
	global_load_dwordx2 v[26:27], v[26:27], off offset:768
	v_ashrrev_i32_e32 v25, 31, v24
	v_lshlrev_b64 v[24:25], 8, v[24:25]
	v_mov_b32_e32 v21, v133
	v_lshl_add_u64 v[24:25], s[16:17], 0, v[24:25]
	s_waitcnt lgkmcnt(0)
	v_lshlrev_b32_e32 v34, 16, v14
	v_and_b32_e32 v35, 0xffff0000, v14
	v_mov_b64_e32 v[0:1], s[14:15]
	v_lshl_add_u64 v[20:21], v[24:25], 0, v[20:21]
	v_lshlrev_b32_e32 v24, 16, v17
	v_and_b32_e32 v25, 0xffff0000, v17
	v_lshlrev_b32_e32 v32, 16, v16
	v_and_b32_e32 v33, 0xffff0000, v16
	v_lshlrev_b32_e32 v16, 16, v15
	v_and_b32_e32 v17, 0xffff0000, v15
	v_pk_mul_f32 v[40:41], v[34:35], v[34:35]
	v_mad_i64_i32 v[28:29], s[18:19], v5, s83, v[0:1]
	v_pk_mul_f32 v[38:39], v[16:17], v[16:17]
	v_add_f32_e32 v5, v40, v41
	v_add_f32_e32 v5, v38, v5
	v_pk_mul_f32 v[36:37], v[32:33], v[32:33]
	v_add_f32_e32 v5, v39, v5
	v_add_f32_e32 v5, v36, v5
	v_pk_mul_f32 v[14:15], v[24:25], v[24:25]
	v_add_f32_e32 v5, v37, v5
	v_add_f32_e32 v5, v14, v5
	v_add_f32_e32 v5, v15, v5
	v_mov_b32_e32 v23, v133
	v_lshl_add_u64 v[30:31], v[28:29], 0, v[22:23]
	s_waitcnt vmcnt(0)
	v_lshlrev_b32_e32 v38, 16, v26
	v_and_b32_e32 v39, 0xffff0000, v26
	v_and_b32_e32 v36, 0xffff0000, v27
	v_lshlrev_b32_e32 v37, 16, v27
	v_pk_mul_f32 v[26:27], v[38:39], v[38:39]
	v_pk_mul_f32 v[14:15], v[36:37], v[36:37]
	v_add_f32_e32 v5, v26, v5
	v_add_f32_e32 v5, v27, v5
	v_add_f32_e32 v5, v15, v5
	v_add_f32_e32 v5, v14, v5
	ds_bpermute_b32 v14, v162, v5
	s_waitcnt lgkmcnt(0)
	v_add_f32_e32 v5, v5, v14
	ds_bpermute_b32 v14, v2, v5
	s_waitcnt lgkmcnt(0)
	v_add_f32_e32 v5, v5, v14
	ds_bpermute_b32 v14, v3, v5
	s_waitcnt lgkmcnt(0)
	v_add_f32_e32 v5, v5, v14
	ds_bpermute_b32 v14, v4, v5
	s_waitcnt lgkmcnt(0)
	v_add_f32_e32 v5, v5, v14
	v_fmamk_f32 v5, v5, 0x3baaaaab, v134
	v_mul_f32_e32 v14, 0x4b800000, v5
	v_cmp_gt_f32_e32 vcc, s33, v5
	s_nop 1
	v_cndmask_b32_e32 v5, v5, v14, vcc
	v_rsq_f32_e32 v5, v5
	s_nop 0
	v_mul_f32_e32 v14, 0x45800000, v5
	v_cndmask_b32_e32 v26, v5, v14, vcc
	v_pk_mul_f32 v[14:15], v[26:27], v[34:35] op_sel_hi:[0,1]
	v_pk_mul_f32 v[16:17], v[26:27], v[16:17] op_sel_hi:[0,1]
	v_pk_mul_f32 v[32:33], v[26:27], v[32:33] op_sel_hi:[0,1]
	v_pk_mul_f32 v[24:25], v[26:27], v[24:25] op_sel_hi:[0,1]
	v_pk_mul_f32 v[10:11], v[10:11], v[14:15]
	v_pk_mul_f32 v[12:13], v[12:13], v[16:17]
	v_pk_mul_f32 v[14:15], v[6:7], v[32:33]
	v_pk_mul_f32 v[16:17], v[8:9], v[24:25]
	v_cvt_pk_bf16_f32 v6, v10, v11
	v_cvt_pk_bf16_f32 v7, v12, v13
	v_cvt_pk_bf16_f32 v8, v14, v15
	v_cvt_pk_bf16_f32 v9, v16, v17
	global_store_dwordx4 v[30:31], v[6:9], off
	global_load_dwordx4 v[6:9], v22, s[12:13] offset:512
	s_nop 0
	global_load_dwordx4 v[10:13], v[20:21], off
	global_load_dwordx4 v[14:17], v[20:21], off offset:16
	v_pk_mul_f32 v[24:25], v[26:27], v[38:39] op_sel_hi:[0,1]
	v_pk_mul_f32 v[26:27], v[26:27], v[36:37] op_sel_hi:[0,1]
	v_cmp_gt_u32_e32 vcc, 8, v42
	v_mov_b32_e32 v5, v135
	v_lshl_add_u64 v[22:23], v[28:29], 0, v[132:133]
	v_cndmask_b32_e64 v20, 1.0, -1.0, vcc
	s_waitcnt vmcnt(0)
	v_pk_mul_f32 v[6:7], v[6:7], v[24:25]
	v_pk_mul_f32 v[8:9], v[8:9], v[26:27] op_sel:[0,1] op_sel_hi:[1,0]
	s_waitcnt lgkmcnt(0)
	v_mov_b32_e32 v24, v10
	v_mov_b32_e32 v25, v12
	v_mov_b32_e32 v12, v11
	v_mov_b32_e32 v10, v14
	v_mov_b32_e32 v11, v16
	v_mov_b32_e32 v16, v15
	ds_bpermute_b32 v14, v4, v6
	ds_bpermute_b32 v15, v4, v7
	ds_bpermute_b32 v26, v4, v8
	ds_bpermute_b32 v27, v4, v9
	v_pk_mul_f32 v[6:7], v[24:25], v[6:7]
	v_pk_mul_f32 v[8:9], v[10:11], v[8:9]
	s_waitcnt lgkmcnt(2)
	v_pk_mul_f32 v[10:11], v[20:21], v[14:15] op_sel_hi:[0,1]
	v_pk_fma_f32 v[6:7], v[12:13], v[10:11], v[6:7]
	s_waitcnt lgkmcnt(0)
	v_pk_mul_f32 v[14:15], v[20:21], v[26:27] op_sel_hi:[0,1]
	v_pk_fma_f32 v[8:9], v[16:17], v[14:15], v[8:9]
	v_cvt_pk_bf16_f32 v6, v6, v7
	v_cvt_pk_bf16_f32 v7, v8, v9
	global_store_dwordx2 v[22:23], v[6:7], off offset:256
	v_mov_b32_e32 v23, v133
	v_add_u32_e32 v6, s5, v5
	v_add_u32_e32 v6, 0x200, v6
	v_ashrrev_i32_e32 v16, 4, v6
	v_and_b32_e32 v38, 15, v5
	v_add_u32_e32 v20, s25, v16
	v_lshlrev_b32_e32 v132, 3, v38
	v_mad_i64_i32 v[6:7], s[18:19], v20, s69, v[18:19]
	v_lshl_add_u64 v[6:7], v[6:7], 0, v[132:133]
	global_load_dwordx2 v[18:19], v[6:7], off offset:768
	v_lshlrev_b32_e32 v10, 5, v38
	global_load_dwordx4 v[6:9], v10, s[12:13] offset:16
	s_nop 0
	global_load_dwordx4 v[10:13], v10, s[12:13]
	v_lshlrev_b32_e32 v24, 4, v38
	v_lshlrev_b32_e32 v5, 5, v5
	v_mad_u64_u32 v[14:15], s[18:19], v16, s71, v[24:25]
	v_and_b32_e32 v22, 0xe0, v5
	v_add_u32_e32 v5, s4, v16
	ds_read_b128 v[14:17], v14
	v_ashrrev_i32_e32 v21, 31, v20
	v_lshlrev_b64 v[20:21], 8, v[20:21]
	v_lshl_add_u64 v[20:21], s[16:17], 0, v[20:21]
	v_lshl_add_u64 v[20:21], v[20:21], 0, v[22:23]
	s_waitcnt lgkmcnt(0)
; DI void phase_mla_up(const Params& P, int l, char* shm) {
;     ...
;       for (int i = 0; i < 8; ++i) {
;         const int chunk = tid_() + i * 512, row = chunk >> 4, j16 = chunk & 15, c8 = j16 * 8, t = brow + row;
;         const i32x4 v = *(const i32x4*)(shm + row * 272 + c8 * 2);
;         const u32x2 krr = *(const u32x2*)(projC + (size_t)t * 448 + 384 + j16 * 4);
;         float kv[8], kr[4];
; #pragma unroll
;         for (int e = 0; e < 4; ++e) { kv[2 * e] = bflo((unsigned)v[e]); kv[2 * e + 1] = bfhi((unsigned)v[e]); }
;         kr[0] = bflo(krr[0]); kr[1] = bfhi(krr[0]); kr[2] = bflo(krr[1]); kr[3] = bfhi(krr[1]);
;         float ss = 0.f;
; #pragma unroll
;         for (int e = 0; e < 8; ++e) ss += kv[e] * kv[e];
; #pragma unroll
;         for (int e = 0; e < 4; ++e) ss += kr[e] * kr[e];
;         ss += __shfl_xor(ss, 1); ss += __shfl_xor(ss, 2); ss += __shfl_xor(ss, 4); ss += __shfl_xor(ss, 8);
;         const float r = rsqrtf(ss * (1.f / 192.f) + EPS);
;         u16* kd = (u16*)(P.ws + OFF_KC) + ((size_t)((b * 4 + h) * SEQ + s0 + row)) * 192;
;         const f32x4 g0 = *(const f32x4*)(kng + c8), g1 = *(const f32x4*)(kng + c8 + 4);
;         i32x4 o;
;         o[0] = (int)pack2(kv[0] * r * g0[0], kv[1] * r * g0[1]);
;         o[1] = (int)pack2(kv[2] * r * g0[2], kv[3] * r * g0[3]);
;         o[2] = (int)pack2(kv[4] * r * g1[0], kv[5] * r * g1[1]);
;         o[3] = (int)pack2(kv[6] * r * g1[2], kv[7] * r * g1[3]);
;         *(i32x4*)(kd + c8) = o;
;         const f32x4 gr = *(const f32x4*)(kng + 128 + j16 * 4);
;         const f32x4* rt = (const f32x4*)(P.ws + OFF_ROPE) + (size_t)t * 16 + (j16 & 7) * 2;
;         const f32x4 cs01 = rt[0], cs23 = rt[1];
;         float my[4], ot[4], rv[4];
; #pragma unroll
;         for (int e = 0; e < 4; ++e) { my[e] = kr[e] * r * gr[e]; ot[e] = __shfl_xor(my[e], 8); }
;         const float sgn = (j16 < 8) ? -1.f : 1.f;
;         rv[0] = my[0] * cs01[0] + sgn * ot[0] * cs01[1];
;         rv[1] = my[1] * cs01[2] + sgn * ot[1] * cs01[3];
;         rv[2] = my[2] * cs23[0] + sgn * ot[2] * cs23[1];
;         rv[3] = my[3] * cs23[2] + sgn * ot[3] * cs23[3];
;         u32x2 ro = {pack2(rv[0], rv[1]), pack2(rv[2], rv[3])};
;         *(u32x2*)(kd + 128 + j16 * 4) = ro;
;       }
; #pragma unroll 4
;       for (int i = 0; i < 8; ++i) {
;         const int chunk = tid_() + i * 512, dv = chunk >> 5, c8 = (chunk & 31) * 8;
	v_lshlrev_b32_e32 v30, 16, v14
	v_and_b32_e32 v31, 0xffff0000, v14
	v_lshlrev_b32_e32 v22, 16, v17
	v_and_b32_e32 v23, 0xffff0000, v17
	v_lshlrev_b32_e32 v28, 16, v16
	v_and_b32_e32 v29, 0xffff0000, v16
	v_lshlrev_b32_e32 v16, 16, v15
	v_and_b32_e32 v17, 0xffff0000, v15
	v_pk_mul_f32 v[36:37], v[30:31], v[30:31]
	v_mad_i64_i32 v[0:1], s[18:19], v5, s83, v[0:1]
	v_pk_mul_f32 v[34:35], v[16:17], v[16:17]
	v_add_f32_e32 v5, v36, v37
	v_add_f32_e32 v5, v34, v5
	v_pk_mul_f32 v[32:33], v[28:29], v[28:29]
	v_add_f32_e32 v5, v35, v5
	v_add_f32_e32 v5, v32, v5
	v_pk_mul_f32 v[14:15], v[22:23], v[22:23]
	v_add_f32_e32 v5, v33, v5
	v_add_f32_e32 v5, v14, v5
	v_add_f32_e32 v5, v15, v5
	v_mov_b32_e32 v25, v133
	v_lshl_add_u64 v[26:27], v[0:1], 0, v[24:25]
	s_addk_i32 s5, 0x400
	s_cmpk_eq_i32 s5, 0x1000
	v_lshl_add_u64 v[0:1], v[0:1], 0, v[132:133]
	s_waitcnt vmcnt(0)
	v_lshlrev_b32_e32 v34, 16, v18
	v_and_b32_e32 v35, 0xffff0000, v18
	v_and_b32_e32 v32, 0xffff0000, v19
	v_lshlrev_b32_e32 v33, 16, v19
	v_pk_mul_f32 v[18:19], v[34:35], v[34:35]
	v_pk_mul_f32 v[14:15], v[32:33], v[32:33]
	v_add_f32_e32 v5, v18, v5
	v_add_f32_e32 v5, v19, v5
	v_add_f32_e32 v5, v15, v5
	v_add_f32_e32 v5, v14, v5
	ds_bpermute_b32 v14, v162, v5
	s_waitcnt lgkmcnt(0)
	v_add_f32_e32 v5, v5, v14
	ds_bpermute_b32 v14, v2, v5
	s_waitcnt lgkmcnt(0)
	v_add_f32_e32 v5, v5, v14
	ds_bpermute_b32 v14, v3, v5
	s_waitcnt lgkmcnt(0)
	v_add_f32_e32 v5, v5, v14
	ds_bpermute_b32 v14, v4, v5
	s_waitcnt lgkmcnt(0)
	v_add_f32_e32 v5, v5, v14
	v_fmamk_f32 v5, v5, 0x3baaaaab, v134
	v_mul_f32_e32 v14, 0x4b800000, v5
	v_cmp_gt_f32_e32 vcc, s33, v5
	s_nop 1
	v_cndmask_b32_e32 v5, v5, v14, vcc
	v_rsq_f32_e32 v5, v5
	s_nop 0
	v_mul_f32_e32 v14, 0x45800000, v5
	v_cndmask_b32_e32 v18, v5, v14, vcc
	v_pk_mul_f32 v[14:15], v[18:19], v[30:31] op_sel_hi:[0,1]
	v_pk_mul_f32 v[16:17], v[18:19], v[16:17] op_sel_hi:[0,1]
	v_pk_mul_f32 v[28:29], v[18:19], v[28:29] op_sel_hi:[0,1]
	v_pk_mul_f32 v[22:23], v[18:19], v[22:23] op_sel_hi:[0,1]
	v_pk_mul_f32 v[10:11], v[10:11], v[14:15]
	v_pk_mul_f32 v[12:13], v[12:13], v[16:17]
	v_pk_mul_f32 v[14:15], v[6:7], v[28:29]
	v_pk_mul_f32 v[16:17], v[8:9], v[22:23]
	v_cvt_pk_bf16_f32 v6, v10, v11
	v_cvt_pk_bf16_f32 v7, v12, v13
	v_cvt_pk_bf16_f32 v8, v14, v15
	v_cvt_pk_bf16_f32 v9, v16, v17
	global_store_dwordx4 v[26:27], v[6:9], off
	global_load_dwordx4 v[6:9], v24, s[12:13] offset:512
	s_nop 0
	global_load_dwordx4 v[10:13], v[20:21], off
	global_load_dwordx4 v[14:17], v[20:21], off offset:16
	v_pk_mul_f32 v[22:23], v[18:19], v[34:35] op_sel_hi:[0,1]
	v_pk_mul_f32 v[18:19], v[18:19], v[32:33] op_sel_hi:[0,1]
	v_cmp_gt_u32_e32 vcc, 8, v38
	s_waitcnt vmcnt(0)
	v_pk_mul_f32 v[6:7], v[6:7], v[22:23]
	v_pk_mul_f32 v[8:9], v[8:9], v[18:19] op_sel:[0,1] op_sel_hi:[1,0]
	s_waitcnt lgkmcnt(0)
	v_mov_b32_e32 v22, v10
	v_mov_b32_e32 v23, v12
	v_mov_b32_e32 v12, v11
	v_mov_b32_e32 v10, v14
	v_mov_b32_e32 v11, v16
	v_mov_b32_e32 v16, v15
	ds_bpermute_b32 v14, v4, v6
	ds_bpermute_b32 v15, v4, v7
	ds_bpermute_b32 v18, v4, v8
	ds_bpermute_b32 v19, v4, v9
	v_cndmask_b32_e64 v20, 1.0, -1.0, vcc
	v_pk_mul_f32 v[6:7], v[22:23], v[6:7]
	v_pk_mul_f32 v[8:9], v[10:11], v[8:9]
	s_waitcnt lgkmcnt(2)
	v_pk_mul_f32 v[10:11], v[20:21], v[14:15] op_sel_hi:[0,1]
	s_waitcnt lgkmcnt(0)
	v_pk_mul_f32 v[14:15], v[20:21], v[18:19] op_sel_hi:[0,1]
	v_pk_fma_f32 v[6:7], v[12:13], v[10:11], v[6:7]
	v_pk_fma_f32 v[8:9], v[16:17], v[14:15], v[8:9]
	v_cvt_pk_bf16_f32 v6, v6, v7
	v_cvt_pk_bf16_f32 v7, v8, v9
	global_store_dwordx2 v[0:1], v[6:7], off offset:256
	s_cbranch_scc0 .LBB0_541
	s_lshl_b32 s4, s1, 9
	s_lshl_b32 s1, s27, 7
	s_add_i32 s4, s4, s1
	s_lshl_b32 s0, s0, 1
	s_add_u32 s0, s22, s0
	s_addc_u32 s1, s23, 0
	s_mov_b32 s5, 0
.LBB0_543:
	s_nop 0
	v_mov_b32_e32 v0, v135
	s_nop 0
	v_add_u32_e32 v1, s5, v0
	v_ashrrev_i32_e32 v4, 5, v1
	v_lshlrev_b32_e32 v0, 4, v0
	v_mul_lo_u32 v1, v4, s68
	v_and_b32_e32 v132, 0x1f0, v0
	v_add3_u32 v0, v1, v132, s41
	ds_read_b128 v[0:3], v0
	v_add_u32_e32 v4, s4, v4
	v_ashrrev_i32_e32 v5, 31, v4
	v_lshlrev_b64 v[4:5], 14, v[4:5]
	v_lshl_add_u64 v[4:5], s[0:1], 0, v[4:5]
	v_lshl_add_u64 v[4:5], v[4:5], 0, v[132:133]
	s_waitcnt lgkmcnt(0)
	global_store_dwordx4 v[4:5], v[0:3], off
	s_nop 1
	v_mov_b32_e32 v0, v135
	s_nop 0
	v_add_u32_e32 v1, s5, v0
	v_add_u32_e32 v1, 0x200, v1
	v_ashrrev_i32_e32 v4, 5, v1
	v_lshlrev_b32_e32 v0, 4, v0
	v_mul_lo_u32 v1, v4, s68
	v_and_b32_e32 v132, 0x1f0, v0
	v_add3_u32 v0, v1, v132, s41
	ds_read_b128 v[0:3], v0
	v_add_u32_e32 v4, s4, v4
	v_ashrrev_i32_e32 v5, 31, v4
	v_lshlrev_b64 v[4:5], 14, v[4:5]
	v_lshl_add_u64 v[4:5], s[0:1], 0, v[4:5]
	v_lshl_add_u64 v[4:5], v[4:5], 0, v[132:133]
	s_waitcnt lgkmcnt(0)
	global_store_dwordx4 v[4:5], v[0:3], off
	s_nop 1
	v_mov_b32_e32 v0, v135
	s_nop 0
	v_add_u32_e32 v1, s5, v0
	v_add_u32_e32 v1, 0x400, v1
	v_ashrrev_i32_e32 v4, 5, v1
	v_lshlrev_b32_e32 v0, 4, v0
	v_mul_lo_u32 v1, v4, s68
	v_and_b32_e32 v132, 0x1f0, v0
	v_add3_u32 v0, v1, v132, s41
	ds_read_b128 v[0:3], v0
	v_add_u32_e32 v4, s4, v4
	v_ashrrev_i32_e32 v5, 31, v4
	v_lshlrev_b64 v[4:5], 14, v[4:5]
	v_lshl_add_u64 v[4:5], s[0:1], 0, v[4:5]
	v_lshl_add_u64 v[4:5], v[4:5], 0, v[132:133]
	s_waitcnt lgkmcnt(0)
	global_store_dwordx4 v[4:5], v[0:3], off
	s_nop 1
	v_mov_b32_e32 v0, v135
	s_nop 0
	v_add_u32_e32 v1, s5, v0
	v_add_u32_e32 v1, 0x600, v1
	v_ashrrev_i32_e32 v4, 5, v1
	v_lshlrev_b32_e32 v0, 4, v0
	v_mul_lo_u32 v1, v4, s68
	v_and_b32_e32 v132, 0x1f0, v0
	v_add3_u32 v0, v1, v132, s41
	ds_read_b128 v[0:3], v0
	v_add_u32_e32 v4, s4, v4
	v_ashrrev_i32_e32 v5, 31, v4
	v_lshlrev_b64 v[4:5], 14, v[4:5]
	v_lshl_add_u64 v[4:5], s[0:1], 0, v[4:5]
	s_addk_i32 s5, 0x800
	v_lshl_add_u64 v[4:5], v[4:5], 0, v[132:133]
	s_cmpk_eq_i32 s5, 0x1000
	s_waitcnt lgkmcnt(0)
	global_store_dwordx4 v[4:5], v[0:3], off
	s_cbranch_scc0 .LBB0_543
	s_add_i32 s24, s24, s72
	s_cmpk_gt_i32 s24, 0x1ff
	s_waitcnt lgkmcnt(0)
	s_barrier
	s_cbranch_scc0 .LBB0_406

; DI float bflo(unsigned v) { return __uint_as_float(v << 16); }
; DI float bfhi(unsigned v) { return __uint_as_float(v & 0xffff0000u); }
; DI int tid_() { int t = threadIdx.x; asm volatile("" : "+v"(t)); return t; }
; DI void rowscale_prologue(const u16* Ab, int lda, int K, float* rs) {
;   const int tid = tid_(), row = tid >> 1, half = tid & 1;
;   const u16* p = Ab + (long)row * lda + half * (K >> 1);
;   float ss = 0.f;
;   for (int i = 0; i < (K >> 4); ++i) {
;     i32x4 v = *(const i32x4*)(p + i * 8);
; #pragma unroll
;     for (int e = 0; e < 4; ++e) {
;       float a = bflo((unsigned)v[e]), b = bfhi((unsigned)v[e]);
;       ss += a * a + b * b;
;     }
;   }
;   ss += __shfl_xor(ss, 1);
;   if (half == 0) rs[row] = rsqrtf(ss / (float)K + EPS);
.LBB0_548:
	v_lshl_add_u64 v[2:3], v[0:1], 0, s[0:1]
	v_add_co_u32_e32 v2, vcc, 0xf000000, v2
	s_add_u32 s0, s0, 64
	s_nop 0
	v_addc_co_u32_e32 v3, vcc, 0, v3, vcc
	global_load_dwordx4 v[8:11], v[2:3], off
	s_addc_u32 s1, s1, 0
	s_cmpk_eq_i32 s0, 0x100
	s_waitcnt vmcnt(0) lgkmcnt(0)
	v_lshlrev_b32_e32 v12, 16, v8
	v_and_b32_e32 v13, 0xffff0000, v8
	v_pk_mul_f32 v[12:13], v[12:13], v[12:13]
	s_nop 0
	v_add_f32_e32 v7, v12, v13
	v_and_b32_e32 v13, 0xffff0000, v10
	v_and_b32_e32 v12, 0xffff0000, v9
	v_add_f32_e32 v14, v6, v7
	v_lshlrev_b32_e32 v7, 16, v10
	v_lshlrev_b32_e32 v6, 16, v9
	v_pk_mul_f32 v[8:9], v[12:13], v[12:13]
	s_nop 0
	v_pk_fma_f32 v[6:7], v[6:7], v[6:7], v[8:9]
	s_nop 0
	v_add_f32_e32 v6, v6, v14
	v_add_f32_e32 v8, v7, v6
	v_lshlrev_b32_e32 v6, 16, v11
	v_and_b32_e32 v7, 0xffff0000, v11
	v_pk_mul_f32 v[6:7], v[6:7], v[6:7]
	s_nop 0
	v_add_f32_e32 v6, v6, v7
	v_add_f32_e32 v12, v6, v8
	global_load_dwordx4 v[6:9], v[2:3], off offset:16
	s_waitcnt vmcnt(0) lgkmcnt(0)
	v_lshlrev_b32_e32 v10, 16, v6
	v_and_b32_e32 v11, 0xffff0000, v6
	v_pk_mul_f32 v[10:11], v[10:11], v[10:11]
	v_and_b32_e32 v13, 0xffff0000, v8
	v_add_f32_e32 v6, v10, v11
	v_add_f32_e32 v14, v12, v6
	v_and_b32_e32 v12, 0xffff0000, v7
	v_lshlrev_b32_e32 v11, 16, v8
	v_lshlrev_b32_e32 v10, 16, v7
	v_pk_mul_f32 v[6:7], v[12:13], v[12:13]
	s_nop 0
	v_pk_fma_f32 v[6:7], v[10:11], v[10:11], v[6:7]
	s_nop 0
	v_add_f32_e32 v6, v6, v14
	v_add_f32_e32 v8, v7, v6
	v_lshlrev_b32_e32 v6, 16, v9
	v_and_b32_e32 v7, 0xffff0000, v9
	v_pk_mul_f32 v[6:7], v[6:7], v[6:7]
	s_nop 0
	v_add_f32_e32 v6, v6, v7
	v_add_f32_e32 v12, v6, v8
	global_load_dwordx4 v[6:9], v[2:3], off offset:32
	s_waitcnt vmcnt(0) lgkmcnt(0)
	v_lshlrev_b32_e32 v10, 16, v6
	v_and_b32_e32 v11, 0xffff0000, v6
	v_pk_mul_f32 v[10:11], v[10:11], v[10:11]
	v_and_b32_e32 v13, 0xffff0000, v8
	v_add_f32_e32 v6, v10, v11
	v_add_f32_e32 v14, v12, v6
	v_and_b32_e32 v12, 0xffff0000, v7
	v_lshlrev_b32_e32 v11, 16, v8
	v_lshlrev_b32_e32 v10, 16, v7
	v_pk_mul_f32 v[6:7], v[12:13], v[12:13]
	s_nop 0
	v_pk_fma_f32 v[6:7], v[10:11], v[10:11], v[6:7]
	s_nop 0
	v_add_f32_e32 v6, v6, v14
	v_add_f32_e32 v8, v7, v6
	v_lshlrev_b32_e32 v6, 16, v9
	v_and_b32_e32 v7, 0xffff0000, v9
	v_pk_mul_f32 v[6:7], v[6:7], v[6:7]
	s_nop 0
	v_add_f32_e32 v6, v6, v7
	v_add_f32_e32 v10, v6, v8
	global_load_dwordx4 v[6:9], v[2:3], off offset:48
	s_waitcnt vmcnt(0) lgkmcnt(0)
	v_lshlrev_b32_e32 v2, 16, v6
	v_and_b32_e32 v3, 0xffff0000, v6
	v_pk_mul_f32 v[2:3], v[2:3], v[2:3]
	v_and_b32_e32 v11, 0xffff0000, v8
	v_add_f32_e32 v2, v2, v3
	v_add_f32_e32 v12, v10, v2
	v_and_b32_e32 v10, 0xffff0000, v7
	v_lshlrev_b32_e32 v3, 16, v8
	v_lshlrev_b32_e32 v2, 16, v7
	v_pk_mul_f32 v[6:7], v[10:11], v[10:11]
	s_nop 0
	v_pk_fma_f32 v[2:3], v[2:3], v[2:3], v[6:7]
	s_nop 0
	v_add_f32_e32 v2, v2, v12
	v_add_f32_e32 v6, v3, v2
	v_lshlrev_b32_e32 v2, 16, v9
	v_and_b32_e32 v3, 0xffff0000, v9
	v_pk_mul_f32 v[2:3], v[2:3], v[2:3]
	s_nop 0
	v_add_f32_e32 v2, v2, v3
	v_add_f32_e32 v6, v2, v6
	s_cbranch_scc0 .LBB0_548
	v_and_b32_e32 v1, 64, v204
	v_xor_b32_e32 v0, 1, v204
	v_add_u32_e32 v1, 64, v1
	v_cmp_lt_i32_e32 vcc, v0, v1
	s_nop 1
	v_cndmask_b32_e32 v0, v204, v0, vcc
	v_lshlrev_b32_e32 v0, 2, v0
	ds_bpermute_b32 v0, v0, v6
	v_cmp_eq_u32_e32 vcc, 0, v5
	s_and_saveexec_b64 s[0:1], vcc
	s_cbranch_execz .LBB0_551
	s_waitcnt lgkmcnt(0)
	v_add_f32_e32 v0, v6, v0
	v_fmamk_f32 v0, v0, 0x3b800000, v134
	v_mul_f32_e32 v1, 0x4b800000, v0
	v_cmp_gt_f32_e32 vcc, s33, v0
	s_nop 1
	v_cndmask_b32_e32 v0, v0, v1, vcc
	v_rsq_f32_e32 v0, v0
	s_nop 0
	v_mul_f32_e32 v1, 0x45800000, v0
	v_cndmask_b32_e32 v0, v0, v1, vcc
	v_lshl_add_u32 v1, v4, 2, v210
	ds_write_b32 v1, v0

; DI int tid_() { int t = threadIdx.x; asm volatile("" : "+v"(t)); return t; }
; DI void phase_mla_up(const Params& P, int l, char* shm) {
;     ...
; #pragma unroll 4
;     for (int i = 0; i < 16; ++i) {
;       const int chunk = tid_() + i * 512, row = chunk >> 5, c8 = (chunk & 31) * 8;
;       const i32x4 v = *(const i32x4*)(shm + row * 528 + c8 * 2);
;       *(i32x4*)((u16*)(P.ws + OFF_QRAW) + (size_t)(brow + row) * 768 + bcol + c8) = v;
;     }
;     __syncthreads();
.LBB0_556:
	v_mov_b32_e32 v0, v135
	s_nop 0
	v_add_u32_e32 v1, s4, v0
	v_lshlrev_b32_e32 v0, 4, v0
	v_ashrrev_i32_e32 v6, 5, v1
	v_and_b32_e32 v132, 0x1f0, v0
	v_mad_u64_u32 v[0:1], s[6:7], v6, s68, v[132:133]
	ds_read_b128 v[2:5], v0
	v_add_u32_e32 v6, s17, v6
	v_mov_b64_e32 v[0:1], s[0:1]
	v_mad_i64_i32 v[6:7], s[6:7], v6, s3, v[0:1]
	v_lshl_add_u64 v[6:7], v[6:7], 0, v[132:133]
	s_waitcnt lgkmcnt(0)
	global_store_dwordx4 v[6:7], v[2:5], off
	s_nop 1
	v_mov_b32_e32 v2, v135
	s_nop 0
	v_add_u32_e32 v3, s4, v2
	v_add_u32_e32 v3, 0x200, v3
	v_lshlrev_b32_e32 v2, 4, v2
	v_ashrrev_i32_e32 v6, 5, v3
	v_and_b32_e32 v132, 0x1f0, v2
	v_mad_u64_u32 v[2:3], s[6:7], v6, s68, v[132:133]
	ds_read_b128 v[2:5], v2
	v_add_u32_e32 v6, s17, v6
	v_mad_i64_i32 v[6:7], s[6:7], v6, s3, v[0:1]
	v_lshl_add_u64 v[6:7], v[6:7], 0, v[132:133]
	s_waitcnt lgkmcnt(0)
	global_store_dwordx4 v[6:7], v[2:5], off
	s_nop 1
	v_mov_b32_e32 v2, v135
	s_nop 0
	v_add_u32_e32 v3, s4, v2
	v_add_u32_e32 v3, 0x400, v3
	v_lshlrev_b32_e32 v2, 4, v2
	v_ashrrev_i32_e32 v6, 5, v3
	v_and_b32_e32 v132, 0x1f0, v2
	v_mad_u64_u32 v[2:3], s[6:7], v6, s68, v[132:133]
	ds_read_b128 v[2:5], v2
	v_add_u32_e32 v6, s17, v6
	v_mad_i64_i32 v[6:7], s[6:7], v6, s3, v[0:1]
	v_lshl_add_u64 v[6:7], v[6:7], 0, v[132:133]
	s_waitcnt lgkmcnt(0)
	global_store_dwordx4 v[6:7], v[2:5], off
	s_nop 1
	v_mov_b32_e32 v2, v135
	s_nop 0
	v_add_u32_e32 v3, s4, v2
	v_add_u32_e32 v3, 0x600, v3
	v_lshlrev_b32_e32 v2, 4, v2
	v_ashrrev_i32_e32 v6, 5, v3
	v_and_b32_e32 v132, 0x1f0, v2
	v_mad_u64_u32 v[2:3], s[6:7], v6, s68, v[132:133]
	ds_read_b128 v[2:5], v2
	v_add_u32_e32 v6, s17, v6
	v_mad_i64_i32 v[0:1], s[6:7], v6, s3, v[0:1]
	s_addk_i32 s4, 0x800
	v_lshl_add_u64 v[0:1], v[0:1], 0, v[132:133]
	s_cmpk_eq_i32 s4, 0x2000
	s_waitcnt lgkmcnt(0)
	global_store_dwordx4 v[0:1], v[2:5], off
	s_cbranch_scc0 .LBB0_556
	s_add_i32 s16, s16, s72
	s_cmpk_gt_i32 s16, 0x17f
	s_waitcnt lgkmcnt(0)
	s_barrier
	s_cbranch_scc0 .LBB0_547

; DI float bflo(unsigned v) { return __uint_as_float(v << 16); }
; DI float bfhi(unsigned v) { return __uint_as_float(v & 0xffff0000u); }
; DI void attn_c_item(const Params& P, int l, int b, int h, int qb, char* shm, float B2, int dry) {
;     ...
;   for (int qs = 0; qs < 2; ++qs) {
;     const int t = b * SEQ + q0 + qs * 16 + fr;
;     const u16* qp = qraw + (size_t)t * 768 + h * 192 + fq * 8;
;     float v[6][8];
;     float ss = 0.f;
; #pragma unroll
;     for (int ks = 0; ks < 6; ++ks) {
;       i32x4 raw = *(const i32x4*)(qp + ks * 32);
; #pragma unroll
;       for (int e = 0; e < 4; ++e) {
;         v[ks][2 * e] = bflo((unsigned)raw[e]);
;         v[ks][2 * e + 1] = bfhi((unsigned)raw[e]);
;         ss += v[ks][2 * e] * v[ks][2 * e] + v[ks][2 * e + 1] * v[ks][2 * e + 1];
;       }
;     }
.LBB0_575:
	s_xor_b64 s[20:21], s[0:1], -1
	s_and_b64 s[0:1], s[0:1], exec
	s_cselect_b32 s0, s30, s29
	v_mov_b32_e32 v184, v135
	s_lshl_b32 s35, s0, 8
	s_or_b32 s35, s35, s31
	v_readfirstlane_b32 s1, v184
	v_and_b32_e32 v185, 15, v184
	v_bfe_u32 v16, v184, 4, 2
	s_ashr_i32 s34, s1, 6
	v_or_b32_e32 v0, s35, v185
	v_lshlrev_b32_e32 v132, 4, v16
	v_lshl_add_u32 v114, s34, 5, v0
	v_lshl_add_u64 v[0:1], s[14:15], 0, v[132:133]
	v_mad_i64_i32 v[12:13], s[36:37], v114, s3, v[0:1]
	v_or_b32_e32 v112, 16, v114
	global_load_dwordx4 v[50:53], v[12:13], off offset:256
	global_load_dwordx4 v[64:67], v[12:13], off offset:320
	v_mad_i64_i32 v[14:15], s[36:37], v112, s3, v[0:1]
	v_mov_b32_e32 v1, v133
	v_lshlrev_b32_e32 v0, 6, v16
	v_ashrrev_i32_e32 v115, 31, v114
	v_lshl_add_u64 v[0:1], s[10:11], 0, v[0:1]
	v_lshlrev_b64 v[2:3], 8, v[114:115]
	v_lshl_add_u64 v[32:33], v[0:1], 0, v[2:3]
	global_load_dwordx4 v[98:101], v[14:15], off offset:256
	global_load_dwordx4 v[106:109], v[14:15], off offset:320
	global_load_dwordx4 v[46:49], v[32:33], off offset:48
	global_load_dwordx4 v[38:41], v[32:33], off offset:32
	v_ashrrev_i32_e32 v113, 31, v112
	v_lshlrev_b64 v[2:3], 8, v[112:113]
	v_lshl_add_u64 v[62:63], v[0:1], 0, v[2:3]
	global_load_dwordx4 v[0:3], v[62:63], off offset:48
	global_load_dwordx4 v[4:7], v[62:63], off offset:32
	global_load_dwordx4 v[34:37], v[32:33], off offset:16
	global_load_dwordx4 v[8:11], v[62:63], off offset:16
	v_lshlrev_b32_e32 v186, 5, v16
	v_lshlrev_b32_e32 v116, 2, v16
	global_load_dwordx4 v[20:23], v186, s[8:9] offset:528
	global_load_dwordx4 v[28:31], v186, s[8:9] offset:512
	global_load_dwordx4 v[16:19], v186, s[8:9] offset:656
	global_load_dwordx4 v[24:27], v186, s[8:9] offset:640
	global_load_dwordx4 v[54:57], v[12:13], off
	global_load_dwordx4 v[68:71], v[12:13], off offset:64
	global_load_dwordx4 v[76:79], v[12:13], off offset:128
	global_load_dwordx4 v[152:155], v[12:13], off offset:192
	global_load_dwordx4 v[58:61], v[14:15], off
	global_load_dwordx4 v[72:75], v[14:15], off offset:64
	global_load_dwordx4 v[80:83], v[14:15], off offset:128
	global_load_dwordx4 v[156:159], v[14:15], off offset:192
	global_load_dwordx4 v[42:45], v[32:33], off
	s_nop 0
	global_load_dwordx4 v[12:15], v[62:63], off
	s_mov_b32 s36, 0x3baaaaab
	s_lshl_b32 s34, s34, 10
	s_mov_b32 m0, s34
	s_lshl_b32 s35, s0, 2
	s_ashr_i32 s1, s1, 7
	s_add_i32 s0, s35, 4
	s_add_i32 s1, s1, s35
	s_waitcnt vmcnt(0) lgkmcnt(0)
	v_and_b32_e32 v33, 0xffff0000, v53
	v_and_b32_e32 v63, 0xffff0000, v67
	v_and_b32_e32 v105, 0xffff0000, v66
	v_lshlrev_b32_e32 v62, 16, v67
	v_and_b32_e32 v103, 0xffff0000, v52
	v_lshlrev_b32_e32 v104, 16, v66
	v_mov_b32_e32 v92, v63
	v_mov_b32_e32 v93, v105
	v_lshlrev_b32_e32 v32, 16, v53
	v_lshlrev_b32_e32 v102, 16, v52
	v_and_b32_e32 v87, 0xffff0000, v101
	v_mov_b32_e32 v66, v33
	v_mov_b32_e32 v67, v103
	v_mov_b32_e32 v90, v62
	v_mov_b32_e32 v91, v104
	v_and_b32_e32 v89, 0xffff0000, v100
	v_pk_mul_f32 v[94:95], v[92:93], v[92:93]
	v_lshlrev_b32_e32 v86, 16, v101
	v_and_b32_e32 v85, 0xffff0000, v109
	v_mov_b32_e32 v52, v32
	v_mov_b32_e32 v53, v102
	v_lshlrev_b32_e32 v88, 16, v100
	v_mov_b32_e32 v118, v46
	v_mov_b32_e32 v119, v48
	v_mov_b32_e32 v48, v47
	v_pk_mul_f32 v[66:67], v[66:67], v[66:67]
	v_mov_b32_e32 v46, v38
	v_mov_b32_e32 v47, v40
	v_mov_b32_e32 v40, v39
	v_mov_b32_e32 v92, v0
	v_mov_b32_e32 v93, v2
	v_mov_b32_e32 v2, v1
	v_pk_fma_f32 v[38:39], v[90:91], v[90:91], v[94:95]
	v_mov_b32_e32 v0, v87
	v_mov_b32_e32 v1, v89
	v_and_b32_e32 v91, 0xffff0000, v108
	v_lshlrev_b32_e32 v84, 16, v109
	v_mov_b32_e32 v96, v86
	v_mov_b32_e32 v97, v88
	v_pk_fma_f32 v[142:143], v[52:53], v[52:53], v[66:67]
	v_pk_mul_f32 v[0:1], v[0:1], v[0:1]
	v_lshlrev_b32_e32 v90, 16, v108
	v_mov_b32_e32 v52, v85
	v_mov_b32_e32 v53, v91
	v_and_b32_e32 v123, 0xffff0000, v51
	v_and_b32_e32 v129, 0xffff0000, v50
	v_pk_fma_f32 v[146:147], v[96:97], v[96:97], v[0:1]
	v_mov_b32_e32 v0, v84
	v_mov_b32_e32 v1, v90
	v_pk_mul_f32 v[52:53], v[52:53], v[52:53]
	v_lshlrev_b32_e32 v122, 16, v51
	v_mov_b32_e32 v126, v34
	v_mov_b32_e32 v127, v36
	v_mov_b32_e32 v36, v35
	v_lshlrev_b32_e32 v128, 16, v50
	v_mov_b32_e32 v34, v123
	v_mov_b32_e32 v35, v129
	v_pk_fma_f32 v[138:139], v[0:1], v[0:1], v[52:53]
	v_mov_b32_e32 v0, v4
	v_mov_b32_e32 v1, v6
	v_mov_b32_e32 v6, v5
	v_and_b32_e32 v125, 0xffff0000, v65
	v_mov_b32_e32 v4, v8
	v_mov_b32_e32 v5, v10
	v_mov_b32_e32 v10, v9
	v_mov_b32_e32 v8, v122
	v_mov_b32_e32 v9, v128
	v_pk_mul_f32 v[34:35], v[34:35], v[34:35]
	v_and_b32_e32 v131, 0xffff0000, v64
	v_lshlrev_b32_e32 v140, 16, v155
	v_and_b32_e32 v141, 0xffff0000, v155
	v_lshlrev_b32_e32 v144, 16, v154
	v_and_b32_e32 v145, 0xffff0000, v154
	v_lshlrev_b32_e32 v108, 16, v157
	v_and_b32_e32 v109, 0xffff0000, v157
	v_lshlrev_b32_e32 v110, 16, v156
	v_and_b32_e32 v111, 0xffff0000, v156
	v_lshlrev_b32_e32 v154, 16, v79
	v_and_b32_e32 v155, 0xffff0000, v79
	v_lshlrev_b32_e32 v120, 16, v83
	v_and_b32_e32 v121, 0xffff0000, v83
	v_lshlrev_b32_e32 v156, 16, v78
	v_and_b32_e32 v157, 0xffff0000, v78
	v_lshlrev_b32_e32 v78, 16, v82
	v_and_b32_e32 v79, 0xffff0000, v82
	v_lshlrev_b32_e32 v82, 16, v81
	v_and_b32_e32 v83, 0xffff0000, v81
	v_and_b32_e32 v163, 0xffff0000, v71
	v_and_b32_e32 v81, 0xffff0000, v75
	v_lshlrev_b32_e32 v124, 16, v65
	v_pk_fma_f32 v[174:175], v[8:9], v[8:9], v[34:35]
	v_lshlrev_b32_e32 v130, 16, v64
	v_mov_b32_e32 v34, v125
	v_mov_b32_e32 v35, v131
	v_mov_b32_e32 v136, v81
	v_mov_b32_e32 v137, v163
	v_mov_b32_e32 v8, v124
	v_mov_b32_e32 v9, v130
	v_pk_mul_f32 v[34:35], v[34:35], v[34:35]
	v_pk_mul_f32 v[190:191], v[136:137], v[136:137]
	v_and_b32_e32 v167, 0xffff0000, v70
; DI float bflo(unsigned v) { return __uint_as_float(v << 16); }
; DI float bfhi(unsigned v) { return __uint_as_float(v & 0xffff0000u); }
; DI void attn_c_item(const Params& P, int l, int b, int h, int qb, char* shm, float B2, int dry) {
;     ...
;     for (int ks = 0; ks < 6; ++ks) {
;       i32x4 raw = *(const i32x4*)(qp + ks * 32);
; #pragma unroll
;       for (int e = 0; e < 4; ++e) {
;         v[ks][2 * e] = bflo((unsigned)raw[e]);
;         v[ks][2 * e + 1] = bfhi((unsigned)raw[e]);
;         ss += v[ks][2 * e] * v[ks][2 * e] + v[ks][2 * e + 1] * v[ks][2 * e + 1];
;       }
;     }
	v_and_b32_e32 v137, 0xffff0000, v74
	v_lshlrev_b32_e32 v96, 16, v99
	v_and_b32_e32 v97, 0xffff0000, v99
	v_lshlrev_b32_e32 v94, 16, v107
	v_and_b32_e32 v95, 0xffff0000, v107
	v_pk_fma_f32 v[34:35], v[8:9], v[8:9], v[34:35]
	v_lshlrev_b32_e32 v8, 16, v98
	v_and_b32_e32 v9, 0xffff0000, v98
	v_lshlrev_b32_e32 v98, 16, v106
	v_and_b32_e32 v99, 0xffff0000, v106
	v_lshlrev_b32_e32 v100, 16, v159
	v_and_b32_e32 v101, 0xffff0000, v159
	v_lshlrev_b32_e32 v106, 16, v158
	v_and_b32_e32 v107, 0xffff0000, v158
	v_lshlrev_b32_e32 v158, 16, v77
	v_and_b32_e32 v159, 0xffff0000, v77
	v_lshlrev_b32_e32 v160, 16, v76
	v_and_b32_e32 v161, 0xffff0000, v76
	v_lshlrev_b32_e32 v76, 16, v80
	v_and_b32_e32 v77, 0xffff0000, v80
	v_lshlrev_b32_e32 v80, 16, v75
	v_lshlrev_b32_e32 v166, 16, v70
	v_lshlrev_b32_e32 v136, 16, v74
	v_mov_b32_e32 v74, v137
	v_mov_b32_e32 v75, v167
	v_lshlrev_b32_e32 v162, 16, v71
	v_mov_b32_e32 v70, v136
	v_mov_b32_e32 v71, v166
	v_pk_mul_f32 v[74:75], v[74:75], v[74:75]
	v_lshlrev_b32_e32 v148, 16, v153
	v_pk_fma_f32 v[192:193], v[70:71], v[70:71], v[74:75]
	v_and_b32_e32 v71, 0xffff0000, v69
	v_and_b32_e32 v75, 0xffff0000, v73
	v_and_b32_e32 v149, 0xffff0000, v153
	v_lshlrev_b32_e32 v70, 16, v69
	v_lshlrev_b32_e32 v74, 16, v73
	v_and_b32_e32 v171, 0xffff0000, v68
	v_and_b32_e32 v153, 0xffff0000, v72
	v_lshlrev_b32_e32 v178, 16, v55
	v_and_b32_e32 v179, 0xffff0000, v55
	v_lshlrev_b32_e32 v168, 16, v59
	v_and_b32_e32 v169, 0xffff0000, v59
	v_lshlrev_b32_e32 v172, 16, v54
	v_and_b32_e32 v173, 0xffff0000, v54
	v_lshlrev_b32_e32 v54, 16, v58
	v_and_b32_e32 v55, 0xffff0000, v58
	v_mov_b32_e32 v58, v75
	v_mov_b32_e32 v59, v71
	v_lshlrev_b32_e32 v150, 16, v152
	v_and_b32_e32 v151, 0xffff0000, v152
	v_lshlrev_b32_e32 v170, 16, v68
	v_lshlrev_b32_e32 v152, 16, v72
	v_lshlrev_b32_e32 v68, 16, v57
	v_and_b32_e32 v69, 0xffff0000, v57
	v_lshlrev_b32_e32 v72, 16, v61
	v_and_b32_e32 v73, 0xffff0000, v61
	v_lshlrev_b32_e32 v176, 16, v56
	v_and_b32_e32 v177, 0xffff0000, v56
	v_lshlrev_b32_e32 v164, 16, v60
	v_and_b32_e32 v165, 0xffff0000, v60
	v_mov_b32_e32 v56, v74
	v_mov_b32_e32 v57, v70
	v_pk_mul_f32 v[58:59], v[58:59], v[58:59]
	v_mov_b32_e32 v60, v153
	v_mov_b32_e32 v61, v171
	v_pk_fma_f32 v[56:57], v[56:57], v[56:57], v[58:59]
	v_mov_b32_e32 v58, v152
	v_mov_b32_e32 v59, v170
	v_pk_mul_f32 v[60:61], v[60:61], v[60:61]
	v_mov_b32_e32 v194, v73
	v_mov_b32_e32 v195, v69
	v_pk_fma_f32 v[58:59], v[58:59], v[58:59], v[60:61]
	v_mov_b32_e32 v60, v72
	v_mov_b32_e32 v61, v68
	v_pk_mul_f32 v[194:195], v[194:195], v[194:195]
	v_mov_b32_e32 v196, v165
	v_mov_b32_e32 v197, v177
	v_pk_fma_f32 v[60:61], v[60:61], v[60:61], v[194:195]
	v_mov_b32_e32 v194, v164
	v_mov_b32_e32 v195, v176
	v_pk_mul_f32 v[196:197], v[196:197], v[196:197]
	v_mov_b32_e32 v198, v169
	v_mov_b32_e32 v199, v179
	v_pk_fma_f32 v[194:195], v[194:195], v[194:195], v[196:197]
	v_mov_b32_e32 v196, v168
	v_mov_b32_e32 v197, v178
	v_pk_mul_f32 v[198:199], v[198:199], v[198:199]
	v_mov_b32_e32 v200, v55
	v_mov_b32_e32 v201, v173
	v_pk_fma_f32 v[196:197], v[196:197], v[196:197], v[198:199]
	v_mov_b32_e32 v198, v54
	v_mov_b32_e32 v199, v172
	v_pk_mul_f32 v[200:201], v[200:201], v[200:201]
	v_mov_b32_e32 v218, v79
	v_pk_fma_f32 v[198:199], v[198:199], v[198:199], v[200:201]
	v_mov_b32_e32 v200, v121
	v_pk_add_f32 v[196:197], v[198:199], v[196:197]
	v_mov_b32_e32 v198, v111
	v_pk_add_f32 v[194:195], v[194:195], v[196:197]
	v_mov_b32_e32 v196, v109
	v_pk_add_f32 v[60:61], v[60:61], v[194:195]
	v_mov_b32_e32 v194, v107
	v_pk_add_f32 v[58:59], v[58:59], v[60:61]
	v_mov_b32_e32 v60, v101
	v_mov_b32_e32 v61, v141
	v_pk_add_f32 v[56:57], v[56:57], v[58:59]
	v_mov_b32_e32 v58, v100
	v_mov_b32_e32 v59, v140
	v_pk_mul_f32 v[60:61], v[60:61], v[60:61]
	v_mov_b32_e32 v195, v145
	v_pk_fma_f32 v[58:59], v[58:59], v[58:59], v[60:61]
	v_mov_b32_e32 v60, v106
	v_mov_b32_e32 v61, v144
	v_pk_mul_f32 v[194:195], v[194:195], v[194:195]
	v_mov_b32_e32 v197, v149
	v_pk_fma_f32 v[60:61], v[60:61], v[60:61], v[194:195]
	v_mov_b32_e32 v194, v108
	v_mov_b32_e32 v195, v148
	v_pk_mul_f32 v[196:197], v[196:197], v[196:197]
	v_mov_b32_e32 v199, v151
	v_pk_fma_f32 v[194:195], v[194:195], v[194:195], v[196:197]
	v_mov_b32_e32 v196, v110
	v_mov_b32_e32 v197, v150
	v_pk_mul_f32 v[198:199], v[198:199], v[198:199]
	v_mov_b32_e32 v201, v155
	v_pk_fma_f32 v[196:197], v[196:197], v[196:197], v[198:199]
	v_mov_b32_e32 v198, v120
	v_mov_b32_e32 v199, v154
	v_pk_mul_f32 v[200:201], v[200:201], v[200:201]
	v_mov_b32_e32 v219, v157
	v_pk_fma_f32 v[198:199], v[198:199], v[198:199], v[200:201]
	v_mov_b32_e32 v200, v78
	v_mov_b32_e32 v201, v156
	v_pk_mul_f32 v[218:219], v[218:219], v[218:219]
	v_mov_b32_e32 v220, v83
	v_mov_b32_e32 v221, v159
	v_mov_b32_e32 v188, v80
	v_mov_b32_e32 v189, v162
	v_pk_fma_f32 v[200:201], v[200:201], v[200:201], v[218:219]
	v_mov_b32_e32 v218, v82
	v_mov_b32_e32 v219, v158
	v_pk_mul_f32 v[220:221], v[220:221], v[220:221]
	v_mov_b32_e32 v222, v77
	v_mov_b32_e32 v223, v161
	v_mov_b32_e32 v52, v97
	v_mov_b32_e32 v53, v9
	v_pk_fma_f32 v[218:219], v[218:219], v[218:219], v[220:221]
	v_mov_b32_e32 v220, v76
	v_mov_b32_e32 v221, v160
	v_pk_mul_f32 v[222:223], v[222:223], v[222:223]
	v_pk_fma_f32 v[188:189], v[188:189], v[188:189], v[190:191]
	v_pk_add_f32 v[56:57], v[192:193], v[56:57]
	v_mov_b32_e32 v50, v96
	v_mov_b32_e32 v51, v8
	v_pk_mul_f32 v[52:53], v[52:53], v[52:53]
	v_pk_fma_f32 v[220:221], v[220:221], v[220:221], v[222:223]
	v_pk_add_f32 v[56:57], v[188:189], v[56:57]
	v_pk_fma_f32 v[182:183], v[50:51], v[50:51], v[52:53]
	v_mov_b32_e32 v52, v95
	v_mov_b32_e32 v53, v99
	v_pk_add_f32 v[56:57], v[220:221], v[56:57]
; DI void attn_c_item(const Params& P, int l, int b, int h, int qb, char* shm, float B2, int dry) {
;     ...
;     ss += __shfl_xor(ss, 16);
;     ss += __shfl_xor(ss, 32);
;     const float r = rsqrtf(ss * (1.f / 192.f) + EPS);
; #pragma unroll
;     for (int ks = 0; ks < 6; ++ks)
; #pragma unroll
;       for (int e = 0; e < 8; ++e) v[ks][e] *= r * qg[ks * 32 + fq * 8 + e];
;     const f32x4* rt = (const f32x4*)(P.ws + OFF_ROPE) + (size_t)t * 16 + fq * 4;
; #pragma unroll
;     for (int e2 = 0; e2 < 4; ++e2) {
;       const f32x4 cssn = rt[e2];
; #pragma unroll
;       for (int u = 0; u < 2; ++u) {
;         const int e = e2 * 2 + u;
;         const float cs = cssn[2 * u], sn = cssn[2 * u + 1];
;         const float x1 = v[4][e], x2 = v[5][e];
;         v[4][e] = x1 * cs - x2 * sn;
;         v[5][e] = x2 * cs + x1 * sn;
;       }
;     }
; #pragma unroll
;     for (int ks = 0; ks < 6; ++ks) {
;       i32x4 pk;
; #pragma unroll
;       for (int e = 0; e < 4; ++e) pk[e] = (int)pack2(v[ks][2 * e] * qscale, v[ks][2 * e + 1] * qscale);
;       qf[qs][ks] = __builtin_bit_cast(bf16x8, pk);
;     }
	v_mov_b32_e32 v50, v94
	v_mov_b32_e32 v51, v98
	v_pk_mul_f32 v[52:53], v[52:53], v[52:53]
	v_pk_add_f32 v[56:57], v[218:219], v[56:57]
	v_pk_fma_f32 v[180:181], v[50:51], v[50:51], v[52:53]
	global_load_dwordx4 v[50:53], v186, s[8:9] offset:400
	global_load_dwordx4 v[64:67], v186, s[8:9] offset:384
	v_pk_add_f32 v[56:57], v[200:201], v[56:57]
	global_load_dwordx4 v[188:191], v186, s[8:9] offset:256
	v_pk_add_f32 v[56:57], v[198:199], v[56:57]
	s_nop 0
	v_pk_add_f32 v[56:57], v[196:197], v[56:57]
	s_nop 0
	v_pk_add_f32 v[56:57], v[194:195], v[56:57]
	s_nop 0
	v_pk_add_f32 v[56:57], v[60:61], v[56:57]
	s_nop 0
	v_pk_add_f32 v[56:57], v[58:59], v[56:57]
	v_mov_b32_e32 v58, v183
	v_mov_b32_e32 v59, v175
	v_pk_add_f32 v[56:57], v[58:59], v[56:57]
	v_mov_b32_e32 v183, v174
	v_pk_add_f32 v[56:57], v[182:183], v[56:57]
	v_mov_b32_e32 v58, v147
	v_mov_b32_e32 v59, v143
	v_pk_add_f32 v[56:57], v[58:59], v[56:57]
	v_mov_b32_e32 v147, v142
	v_pk_add_f32 v[56:57], v[146:147], v[56:57]
	v_mov_b32_e32 v58, v181
	v_mov_b32_e32 v59, v35
	v_pk_add_f32 v[56:57], v[58:59], v[56:57]
	v_mov_b32_e32 v181, v34
	v_pk_add_f32 v[34:35], v[180:181], v[56:57]
	global_load_dwordx4 v[180:183], v186, s[8:9] offset:272
	global_load_dwordx4 v[192:195], v186, s[8:9] offset:144
	global_load_dwordx4 v[196:199], v186, s[8:9] offset:128
	global_load_dwordx4 v[218:221], v186, s[8:9] offset:16
	global_load_dwordx4 v[222:225], v186, s[8:9]
	v_mov_b32_e32 v56, v139
	v_mov_b32_e32 v57, v39
	v_pk_add_f32 v[34:35], v[56:57], v[34:35]
	v_mov_b32_e32 v139, v38
	v_pk_add_f32 v[34:35], v[138:139], v[34:35]
	ds_bpermute_b32 v39, v212, v35
	ds_bpermute_b32 v38, v212, v34
	v_mov_b32_e32 v56, v42
	v_mov_b32_e32 v57, v44
	v_mov_b32_e32 v44, v43
	v_mov_b32_e32 v42, v12
	s_waitcnt lgkmcnt(0)
	v_pk_add_f32 v[34:35], v[34:35], v[38:39]
	ds_bpermute_b32 v39, v211, v35
	ds_bpermute_b32 v38, v211, v34
	v_mov_b32_e32 v43, v14
	v_mov_b32_e32 v14, v13
	s_waitcnt lgkmcnt(0)
	v_pk_add_f32 v[12:13], v[34:35], v[38:39]
	s_nop 0
	v_pk_fma_f32 v[12:13], v[12:13], s[36:37], v[134:135] op_sel_hi:[1,0,0]
	s_mov_b32 s36, 0
	v_mul_f32_e32 v34, 0x4b800000, v13
	v_cmp_gt_f32_e32 vcc, s33, v13
	s_nop 1
	v_cndmask_b32_e32 v13, v13, v34, vcc
	v_rsq_f32_e32 v13, v13
	s_nop 0
	v_mul_f32_e32 v34, 0x45800000, v13
	v_cndmask_b32_e32 v138, v13, v34, vcc
	v_pk_mul_f32 v[34:35], v[138:139], v[22:23] op_sel_hi:[0,1]
	v_pk_mul_f32 v[32:33], v[34:35], v[32:33]
	v_pk_mul_f32 v[34:35], v[138:139], v[18:19] op_sel_hi:[0,1]
	v_pk_mul_f32 v[34:35], v[34:35], v[62:63]
	v_mul_f32_e32 v13, 0x4b800000, v12
	v_pk_mul_f32 v[38:39], v[34:35], v[118:119]
	v_pk_mul_f32 v[34:35], v[34:35], v[48:49]
	v_pk_fma_f32 v[38:39], v[32:33], v[48:49], v[38:39]
	v_pk_fma_f32 v[32:33], v[32:33], v[118:119], v[34:35] neg_lo:[0,0,1] neg_hi:[0,0,1]
	v_pk_mul_f32 v[48:49], v[138:139], v[16:17] op_sel_hi:[0,1]
	v_pk_mul_f32 v[32:33], v[32:33], s[92:93] op_sel_hi:[1,0]
	v_pk_mul_f32 v[48:49], v[48:49], v[104:105]
	v_cvt_pk_bf16_f32 v35, v32, v33
	v_pk_mul_f32 v[32:33], v[38:39], s[92:93] op_sel_hi:[1,0]
	v_pk_mul_f32 v[58:59], v[48:49], v[46:47]
	v_cvt_pk_bf16_f32 v39, v32, v33
	v_pk_mul_f32 v[32:33], v[138:139], v[20:21] op_sel_hi:[0,1]
	v_pk_mul_f32 v[32:33], v[32:33], v[102:103]
	v_cmp_gt_f32_e32 vcc, s33, v12
	v_pk_fma_f32 v[58:59], v[32:33], v[40:41], v[58:59]
	v_pk_mul_f32 v[40:41], v[48:49], v[40:41]
	v_cndmask_b32_e32 v12, v12, v13, vcc
	v_pk_fma_f32 v[32:33], v[32:33], v[46:47], v[40:41] neg_lo:[0,0,1] neg_hi:[0,0,1]
	v_pk_mul_f32 v[40:41], v[138:139], v[26:27] op_sel_hi:[0,1]
	v_pk_mul_f32 v[32:33], v[32:33], s[92:93] op_sel_hi:[1,0]
	v_pk_mul_f32 v[40:41], v[40:41], v[124:125]
	v_cvt_pk_bf16_f32 v34, v32, v33
	v_pk_mul_f32 v[32:33], v[58:59], s[92:93] op_sel_hi:[1,0]
	v_pk_mul_f32 v[46:47], v[40:41], v[126:127]
	v_cvt_pk_bf16_f32 v38, v32, v33
	v_pk_mul_f32 v[32:33], v[138:139], v[30:31] op_sel_hi:[0,1]
	v_pk_mul_f32 v[32:33], v[32:33], v[122:123]
	s_nop 0
	v_pk_fma_f32 v[46:47], v[32:33], v[36:37], v[46:47]
	v_pk_mul_f32 v[36:37], v[40:41], v[36:37]
	v_pk_mul_f32 v[40:41], v[138:139], v[28:29] op_sel_hi:[0,1]
	v_pk_fma_f32 v[32:33], v[32:33], v[126:127], v[36:37] neg_lo:[0,0,1] neg_hi:[0,0,1]
	v_pk_mul_f32 v[36:37], v[46:47], s[92:93] op_sel_hi:[1,0]
	v_pk_mul_f32 v[46:47], v[138:139], v[24:25] op_sel_hi:[0,1]
	v_pk_mul_f32 v[46:47], v[46:47], v[130:131]
	v_pk_mul_f32 v[40:41], v[40:41], v[128:129]
	v_pk_mul_f32 v[48:49], v[46:47], v[56:57]
	v_pk_mul_f32 v[32:33], v[32:33], s[92:93] op_sel_hi:[1,0]
	v_pk_fma_f32 v[48:49], v[40:41], v[44:45], v[48:49]
	v_pk_mul_f32 v[44:45], v[46:47], v[44:45]
	v_cvt_pk_bf16_f32 v33, v32, v33
	v_pk_fma_f32 v[40:41], v[40:41], v[56:57], v[44:45] neg_lo:[0,0,1] neg_hi:[0,0,1]
	v_cvt_pk_bf16_f32 v37, v36, v37
	v_pk_mul_f32 v[40:41], v[40:41], s[92:93] op_sel_hi:[1,0]
	s_nop 0
	v_cvt_pk_bf16_f32 v32, v40, v41
	v_pk_mul_f32 v[40:41], v[48:49], s[92:93] op_sel_hi:[1,0]
	v_rsq_f32_e32 v48, v12
	v_cvt_pk_bf16_f32 v36, v40, v41
	s_waitcnt vmcnt(7)
	v_pk_mul_f32 v[40:41], v[138:139], v[52:53] op_sel_hi:[0,1]
	v_pk_mul_f32 v[40:41], v[40:41], v[140:141]
	s_nop 0
	v_pk_mul_f32 v[40:41], v[40:41], s[92:93] op_sel_hi:[1,0]
	s_nop 0
	v_cvt_pk_bf16_f32 v47, v40, v41
	v_pk_mul_f32 v[40:41], v[50:51], v[138:139] op_sel_hi:[1,0]
	s_nop 0
	v_pk_mul_f32 v[40:41], v[40:41], v[144:145]
	s_nop 0
	v_pk_mul_f32 v[40:41], v[40:41], s[92:93] op_sel_hi:[1,0]
	s_nop 0
	v_cvt_pk_bf16_f32 v46, v40, v41
	s_waitcnt vmcnt(6)
; DI void attn_c_item(const Params& P, int l, int b, int h, int qb, char* shm, float B2, int dry) {
;     ...
; #pragma unroll
;     for (int ks = 0; ks < 6; ++ks)
; #pragma unroll
;       for (int e = 0; e < 8; ++e) v[ks][e] *= r * qg[ks * 32 + fq * 8 + e];
;     const f32x4* rt = (const f32x4*)(P.ws + OFF_ROPE) + (size_t)t * 16 + fq * 4;
; #pragma unroll
;     for (int e2 = 0; e2 < 4; ++e2) {
;       const f32x4 cssn = rt[e2];
; #pragma unroll
;       for (int u = 0; u < 2; ++u) {
;         const int e = e2 * 2 + u;
;         const float cs = cssn[2 * u], sn = cssn[2 * u + 1];
;         const float x1 = v[4][e], x2 = v[5][e];
;         v[4][e] = x1 * cs - x2 * sn;
;         v[5][e] = x2 * cs + x1 * sn;
;       }
;     }
; #pragma unroll
;     for (int ks = 0; ks < 6; ++ks) {
;       i32x4 pk;
; #pragma unroll
;       for (int e = 0; e < 4; ++e) pk[e] = (int)pack2(v[ks][2 * e] * qscale, v[ks][2 * e + 1] * qscale);
;       qf[qs][ks] = __builtin_bit_cast(bf16x8, pk);
;     }
	v_pk_mul_f32 v[40:41], v[66:67], v[138:139] op_sel_hi:[1,0]
	s_nop 0
	v_pk_mul_f32 v[40:41], v[40:41], v[148:149]
	s_nop 0
	v_pk_mul_f32 v[40:41], v[40:41], s[92:93] op_sel_hi:[1,0]
	s_nop 0
	v_cvt_pk_bf16_f32 v45, v40, v41
	v_pk_mul_f32 v[40:41], v[64:65], v[138:139] op_sel_hi:[1,0]
	s_nop 0
	v_pk_mul_f32 v[40:41], v[40:41], v[150:151]
	s_nop 0
	v_pk_mul_f32 v[40:41], v[40:41], s[92:93] op_sel_hi:[1,0]
	s_nop 0
	v_cvt_pk_bf16_f32 v44, v40, v41
	s_waitcnt vmcnt(4)
	v_pk_mul_f32 v[40:41], v[182:183], v[138:139] op_sel_hi:[1,0]
	s_nop 0
	v_pk_mul_f32 v[40:41], v[40:41], v[154:155]
	s_nop 0
	v_pk_mul_f32 v[40:41], v[40:41], s[92:93] op_sel_hi:[1,0]
	s_nop 0
	v_cvt_pk_bf16_f32 v59, v40, v41
	v_pk_mul_f32 v[40:41], v[180:181], v[138:139] op_sel_hi:[1,0]
	s_nop 0
	v_pk_mul_f32 v[40:41], v[40:41], v[156:157]
	s_nop 0
	v_pk_mul_f32 v[40:41], v[40:41], s[92:93] op_sel_hi:[1,0]
	s_nop 0
	v_cvt_pk_bf16_f32 v58, v40, v41
	v_pk_mul_f32 v[40:41], v[190:191], v[138:139] op_sel_hi:[1,0]
	s_nop 0
	v_pk_mul_f32 v[40:41], v[40:41], v[158:159]
	s_nop 0
	v_pk_mul_f32 v[40:41], v[40:41], s[92:93] op_sel_hi:[1,0]
	s_nop 0
	v_cvt_pk_bf16_f32 v57, v40, v41
	v_pk_mul_f32 v[40:41], v[188:189], v[138:139] op_sel_hi:[1,0]
	s_nop 0
	v_pk_mul_f32 v[40:41], v[40:41], v[160:161]
	s_nop 0
	v_pk_mul_f32 v[40:41], v[40:41], s[92:93] op_sel_hi:[1,0]
	s_nop 0
	v_cvt_pk_bf16_f32 v56, v40, v41
	s_waitcnt vmcnt(3)
	v_pk_mul_f32 v[40:41], v[194:195], v[138:139] op_sel_hi:[1,0]
	s_nop 0
	v_pk_mul_f32 v[40:41], v[40:41], v[162:163]
	s_nop 0
	v_pk_mul_f32 v[40:41], v[40:41], s[92:93] op_sel_hi:[1,0]
	s_nop 0
	v_cvt_pk_bf16_f32 v63, v40, v41
	v_pk_mul_f32 v[40:41], v[192:193], v[138:139] op_sel_hi:[1,0]
	s_nop 0
	v_pk_mul_f32 v[40:41], v[40:41], v[166:167]
	s_nop 0
	v_pk_mul_f32 v[40:41], v[40:41], s[92:93] op_sel_hi:[1,0]
	s_nop 0
	v_cvt_pk_bf16_f32 v62, v40, v41
	s_waitcnt vmcnt(2)
	v_pk_mul_f32 v[40:41], v[198:199], v[138:139] op_sel_hi:[1,0]
	s_nop 0
	v_pk_mul_f32 v[40:41], v[40:41], v[70:71]
	s_nop 0
	v_pk_mul_f32 v[40:41], v[40:41], s[92:93] op_sel_hi:[1,0]
	s_nop 0
	v_cvt_pk_bf16_f32 v61, v40, v41
	v_pk_mul_f32 v[40:41], v[196:197], v[138:139] op_sel_hi:[1,0]
	s_nop 0
	v_pk_mul_f32 v[40:41], v[40:41], v[170:171]
	s_nop 0
	v_pk_mul_f32 v[40:41], v[40:41], s[92:93] op_sel_hi:[1,0]
	s_nop 0
	v_cvt_pk_bf16_f32 v60, v40, v41
	s_waitcnt vmcnt(1)
	v_pk_mul_f32 v[40:41], v[220:221], v[138:139] op_sel_hi:[1,0]
	s_nop 0
	v_pk_mul_f32 v[40:41], v[40:41], v[68:69]
	s_nop 0
	v_pk_mul_f32 v[40:41], v[40:41], s[92:93] op_sel_hi:[1,0]
	s_nop 0
	v_cvt_pk_bf16_f32 v71, v40, v41
	v_pk_mul_f32 v[40:41], v[218:219], v[138:139] op_sel_hi:[1,0]
	s_nop 0
	v_pk_mul_f32 v[40:41], v[40:41], v[176:177]
	s_nop 0
	v_pk_mul_f32 v[40:41], v[40:41], s[92:93] op_sel_hi:[1,0]
	s_nop 0
	v_cvt_pk_bf16_f32 v70, v40, v41
	s_waitcnt vmcnt(0)
	v_pk_mul_f32 v[40:41], v[224:225], v[138:139] op_sel_hi:[1,0]
	s_nop 0
	v_pk_mul_f32 v[40:41], v[40:41], v[178:179]
	s_nop 0
	v_pk_mul_f32 v[40:41], v[40:41], s[92:93] op_sel_hi:[1,0]
	s_nop 0
	v_cvt_pk_bf16_f32 v69, v40, v41
	v_pk_mul_f32 v[40:41], v[222:223], v[138:139] op_sel_hi:[1,0]
	s_nop 0
	v_pk_mul_f32 v[12:13], v[40:41], v[172:173]
	s_nop 0
	v_pk_mul_f32 v[12:13], v[12:13], s[92:93] op_sel_hi:[1,0]
	s_nop 0
	v_cvt_pk_bf16_f32 v68, v12, v13
	v_mul_f32_e32 v12, 0x45800000, v48
	v_cndmask_b32_e32 v12, v48, v12, vcc
	v_pk_mul_f32 v[118:119], v[194:195], v[12:13] op_sel_hi:[1,0]
	v_pk_mul_f32 v[40:41], v[222:223], v[12:13] op_sel_hi:[1,0]
	v_pk_mul_f32 v[118:119], v[118:119], v[80:81]
	v_pk_mul_f32 v[80:81], v[188:189], v[12:13] op_sel_hi:[1,0]
	v_pk_mul_f32 v[102:103], v[220:221], v[12:13] op_sel_hi:[1,0]
	v_pk_mul_f32 v[122:123], v[80:81], v[76:77]
	v_pk_mul_f32 v[76:77], v[190:191], v[12:13] op_sel_hi:[1,0]
	v_pk_mul_f32 v[104:105], v[198:199], v[12:13] op_sel_hi:[1,0]
	v_pk_mul_f32 v[124:125], v[76:77], v[82:83]
	v_pk_mul_f32 v[76:77], v[180:181], v[12:13] op_sel_hi:[1,0]
	v_pk_mul_f32 v[28:29], v[28:29], v[12:13] op_sel_hi:[1,0]
	v_pk_mul_f32 v[16:17], v[16:17], v[12:13] op_sel_hi:[1,0]
	v_pk_mul_f32 v[40:41], v[40:41], v[54:55]
	v_pk_mul_f32 v[48:49], v[224:225], v[12:13] op_sel_hi:[1,0]
	v_pk_mul_f32 v[54:55], v[218:219], v[12:13] op_sel_hi:[1,0]
	v_pk_mul_f32 v[72:73], v[102:103], v[72:73]
	v_pk_mul_f32 v[102:103], v[196:197], v[12:13] op_sel_hi:[1,0]
	v_pk_mul_f32 v[74:75], v[104:105], v[74:75]
	v_pk_mul_f32 v[104:105], v[192:193], v[12:13] op_sel_hi:[1,0]
	v_pk_mul_f32 v[126:127], v[76:77], v[78:79]
	v_pk_mul_f32 v[76:77], v[182:183], v[12:13] op_sel_hi:[1,0]
	v_pk_mul_f32 v[64:65], v[64:65], v[12:13] op_sel_hi:[1,0]
	v_pk_mul_f32 v[66:67], v[66:67], v[12:13] op_sel_hi:[1,0]
	v_pk_mul_f32 v[50:51], v[50:51], v[12:13] op_sel_hi:[1,0]
	v_pk_mul_f32 v[52:53], v[52:53], v[12:13] op_sel_hi:[1,0]
	v_pk_mul_f32 v[8:9], v[28:29], v[8:9]
	v_pk_mul_f32 v[28:29], v[30:31], v[12:13] op_sel_hi:[1,0]
	v_pk_mul_f32 v[20:21], v[20:21], v[12:13] op_sel_hi:[1,0]
	v_pk_mul_f32 v[22:23], v[22:23], v[12:13] op_sel_hi:[1,0]
	v_pk_mul_f32 v[24:25], v[24:25], v[12:13] op_sel_hi:[1,0]
	v_pk_mul_f32 v[26:27], v[26:27], v[12:13] op_sel_hi:[1,0]
	v_pk_mul_f32 v[16:17], v[16:17], v[90:91]
	v_pk_mul_f32 v[12:13], v[18:19], v[12:13] op_sel_hi:[1,0]
	v_pk_mul_f32 v[120:121], v[76:77], v[120:121]
	v_pk_mul_f32 v[20:21], v[20:21], v[88:89]
	v_pk_mul_f32 v[12:13], v[12:13], v[84:85]
	v_pk_mul_f32 v[76:77], v[0:1], v[16:17]
	v_pk_mul_f32 v[48:49], v[48:49], v[168:169]
	v_pk_mul_f32 v[22:23], v[22:23], v[86:87]
	v_pk_mul_f32 v[26:27], v[26:27], v[94:95]
	v_pk_fma_f32 v[94:95], v[6:7], v[20:21], v[76:77]
	v_pk_mul_f32 v[76:77], v[92:93], v[12:13]
	v_pk_mul_f32 v[40:41], v[40:41], s[92:93] op_sel_hi:[1,0]
; DI void attn_c_item(const Params& P, int l, int b, int h, int qb, char* shm, float B2, int dry) {
;     ...
;         v[4][e] = x1 * cs - x2 * sn;
;         v[5][e] = x2 * cs + x1 * sn;
;       }
;     }
; #pragma unroll
;     for (int ks = 0; ks < 6; ++ks) {
;       i32x4 pk;
; #pragma unroll
;       for (int e = 0; e < 4; ++e) pk[e] = (int)pack2(v[ks][2 * e] * qscale, v[ks][2 * e + 1] * qscale);
;       qf[qs][ks] = __builtin_bit_cast(bf16x8, pk);
;     }
;   }
;   constexpr int KT_B = 24576, VT_B = 16384, BUF_B = KT_B + VT_B;
;   const int ntile = qb * 4 + 4;
;   const int my_last = qb * 4 + (wid >> 1);
;   f32x4 o[8][2];
; #pragma unroll
;   for (int i = 0; i < 8; ++i) { o[i][0] = f32x4{0.f, 0.f, 0.f, 0.f}; o[i][1] = f32x4{0.f, 0.f, 0.f, 0.f}; }
;   float lsum[2] = {0.f, 0.f};
;   int kR[3], kC[3], vR[2], vC[2];
; #pragma unroll
;   for (int i = 0; i < 3; ++i) stage_rc<6>((tid + i * 512) * 16, kR[i], kC[i]);
; #pragma unroll
;   for (int i = 0; i < 2; ++i) stage_rc<2>((tid + i * 512) * 16, vR[i], vC[i]);
;   int pk[3], pv[2];
; #pragma unroll
;   for (int i = 0; i < 3; ++i) pk[i] = kR[i] * 192 + kC[i];
; #pragma unroll
;   for (int i = 0; i < 2; ++i) pv[i] = vR[i] * SEQ + vC[i];
;     ...
;   A_STAGE(0, 0);
;   asm volatile("s_waitcnt vmcnt(0)" ::: "memory");
;   __syncthreads();
	v_pk_mul_f32 v[54:55], v[54:55], v[164:165]
	v_pk_mul_f32 v[28:29], v[28:29], v[96:97]
	v_pk_fma_f32 v[96:97], v[2:3], v[22:23], v[76:77]
	v_cvt_pk_bf16_f32 v76, v40, v41
	v_pk_mul_f32 v[40:41], v[48:49], s[92:93] op_sel_hi:[1,0]
	v_pk_mul_f32 v[102:103], v[102:103], v[152:153]
	v_cvt_pk_bf16_f32 v77, v40, v41
	v_pk_mul_f32 v[40:41], v[54:55], s[92:93] op_sel_hi:[1,0]
	v_pk_mul_f32 v[104:105], v[104:105], v[136:137]
	v_cvt_pk_bf16_f32 v78, v40, v41
	v_pk_mul_f32 v[40:41], v[72:73], s[92:93] op_sel_hi:[1,0]
	v_pk_mul_f32 v[24:25], v[24:25], v[98:99]
	v_cvt_pk_bf16_f32 v79, v40, v41
	v_pk_mul_f32 v[40:41], v[102:103], s[92:93] op_sel_hi:[1,0]
	v_pk_mul_f32 v[64:65], v[64:65], v[110:111]
	v_cvt_pk_bf16_f32 v80, v40, v41
	v_pk_mul_f32 v[40:41], v[74:75], s[92:93] op_sel_hi:[1,0]
	v_pk_mul_f32 v[18:19], v[42:43], v[24:25]
	v_cvt_pk_bf16_f32 v81, v40, v41
	v_pk_mul_f32 v[40:41], v[104:105], s[92:93] op_sel_hi:[1,0]
	v_pk_mul_f32 v[66:67], v[66:67], v[108:109]
	v_cvt_pk_bf16_f32 v82, v40, v41
	v_pk_mul_f32 v[40:41], v[118:119], s[92:93] op_sel_hi:[1,0]
	v_pk_fma_f32 v[18:19], v[14:15], v[8:9], v[18:19]
	v_cvt_pk_bf16_f32 v83, v40, v41
	v_pk_mul_f32 v[40:41], v[122:123], s[92:93] op_sel_hi:[1,0]
	v_pk_mul_f32 v[14:15], v[14:15], v[24:25]
	v_cvt_pk_bf16_f32 v84, v40, v41
	v_pk_mul_f32 v[40:41], v[124:125], s[92:93] op_sel_hi:[1,0]
	v_pk_mul_f32 v[50:51], v[50:51], v[106:107]
	v_cvt_pk_bf16_f32 v85, v40, v41
	v_pk_mul_f32 v[40:41], v[126:127], s[92:93] op_sel_hi:[1,0]
	v_pk_fma_f32 v[8:9], v[42:43], v[8:9], v[14:15] neg_lo:[0,0,1] neg_hi:[0,0,1]
	v_cvt_pk_bf16_f32 v86, v40, v41
	v_pk_mul_f32 v[40:41], v[120:121], s[92:93] op_sel_hi:[1,0]
	v_lshlrev_b32_e32 v14, 4, v184
	v_cvt_pk_bf16_f32 v87, v40, v41
	v_pk_mul_f32 v[40:41], v[64:65], s[92:93] op_sel_hi:[1,0]
	v_and_b32_e32 v15, 32, v184
	v_cvt_pk_bf16_f32 v88, v40, v41
	v_pk_mul_f32 v[40:41], v[66:67], s[92:93] op_sel_hi:[1,0]
	v_bitop3_b32 v15, v14, v15, 48 bitop3:0x6c
	v_cvt_pk_bf16_f32 v89, v40, v41
	v_pk_mul_f32 v[40:41], v[50:51], s[92:93] op_sel_hi:[1,0]
	v_bfe_i32 v50, v184, 6, 22
	v_lshrrev_b32_e32 v120, 1, v15
	v_mul_hi_i32 v15, v50, s39
	v_lshrrev_b32_e32 v24, 31, v15
	v_pk_mul_f32 v[52:53], v[52:53], v[100:101]
	v_add_u32_e32 v15, v15, v24
	v_add_u32_e32 v24, 0x2000, v14
	v_cvt_pk_bf16_f32 v90, v40, v41
	v_pk_mul_f32 v[40:41], v[52:53], s[92:93] op_sel_hi:[1,0]
	v_ashrrev_i32_e32 v53, 10, v24
	v_add_u32_e32 v14, 0x4000, v14
	v_cvt_pk_bf16_f32 v91, v40, v41
	v_mul_hi_i32 v40, v53, s39
	v_ashrrev_i32_e32 v64, 10, v14
	v_lshrrev_b32_e32 v41, 31, v40
	v_mul_hi_i32 v14, v64, s39
	v_add_u32_e32 v40, v40, v41
	v_lshrrev_b32_e32 v41, 31, v14
	v_add_u32_e32 v14, v14, v41
	v_bfe_u32 v25, v184, 2, 4
	v_mul_i32_i24_e32 v66, 6, v14
	v_lshl_or_b32 v65, v14, 4, v25
	v_sub_u32_e32 v14, v64, v66
	v_lshl_or_b32 v41, v14, 5, v120
	v_bfe_u32 v14, v184, 27, 1
	v_mul_i32_i24_e32 v52, 6, v15
	v_add_u32_e32 v14, v50, v14
	v_lshl_or_b32 v51, v15, 4, v25
	v_sub_u32_e32 v15, v50, v52
	v_ashrrev_i32_e32 v42, 1, v14
	v_lshrrev_b32_e32 v14, 31, v24
	v_lshl_or_b32 v15, v15, 5, v120
	v_add_u32_e32 v14, v53, v14
	v_mul_i32_i24_e32 v55, 6, v40
	v_ashrrev_i32_e32 v48, 1, v14
	v_mad_i32_i24 v14, v51, s63, v15
	v_lshlrev_b32_e32 v15, 13, v25
	v_lshl_or_b32 v54, v40, 4, v25
	v_sub_u32_e32 v40, v53, v55
	v_mul_i32_i24_e32 v72, 2, v48
	v_lshl_or_b32 v74, v48, 17, v15
	v_lshl_or_b32 v40, v40, 5, v120
	v_mul_i32_i24_e32 v67, 2, v42
	v_sub_u32_e32 v49, v53, v72
	v_lshl_or_b32 v73, v42, 17, v15
	v_or_b32_e32 v15, v74, v120
	v_sub_u32_e32 v43, v50, v67
	v_mad_i32_i24 v24, v54, s63, v40
	v_or_b32_e32 v25, v73, v120
	v_lshl_add_u32 v48, v49, 5, v15
	v_ashrrev_i32_e32 v15, 31, v14
	v_mad_i32_i24 v40, v65, s63, v41
	v_lshl_add_u32 v42, v43, 5, v25
	v_lshl_add_u64 v[14:15], v[14:15], 1, s[12:13]
	v_ashrrev_i32_e32 v25, 31, v24
	global_load_lds_dwordx4 v[14:15], off
	v_lshl_add_u64 v[14:15], v[24:25], 1, s[12:13]
	s_add_i32 m0, s34, 0x2000
	v_ashrrev_i32_e32 v41, 31, v40
	global_load_lds_dwordx4 v[14:15], off
	v_lshl_add_u64 v[14:15], v[40:41], 1, s[12:13]
	s_add_i32 m0, s34, 0x4000
	v_ashrrev_i32_e32 v43, 31, v42
	global_load_lds_dwordx4 v[14:15], off
	s_add_i32 m0, s34, 0x6000
	v_lshl_add_u64 v[14:15], v[42:43], 1, s[16:17]
	v_ashrrev_i32_e32 v49, 31, v48
	global_load_lds_dwordx4 v[14:15], off
	v_lshl_add_u64 v[14:15], v[48:49], 1, s[16:17]
	s_add_i32 m0, s34, 0x8000
	v_pk_mul_f32 v[8:9], v[8:9], s[92:93] op_sel_hi:[1,0]
	global_load_lds_dwordx4 v[14:15], off
	v_cvt_pk_bf16_f32 v100, v8, v9
	v_pk_mul_f32 v[8:9], v[10:11], v[26:27]
	v_pk_mul_f32 v[30:31], v[4:5], v[26:27]
	v_pk_fma_f32 v[4:5], v[4:5], v[28:29], v[8:9] neg_lo:[0,0,1] neg_hi:[0,0,1]
	v_pk_fma_f32 v[30:31], v[10:11], v[28:29], v[30:31]
	v_pk_mul_f32 v[4:5], v[4:5], s[92:93] op_sel_hi:[1,0]
	s_waitcnt vmcnt(0)
	s_waitcnt vmcnt(0) lgkmcnt(0)
	v_cvt_pk_bf16_f32 v101, v4, v5
	v_pk_mul_f32 v[4:5], v[6:7], v[16:17]
	s_barrier
; DI void attn_c_item(const Params& P, int l, int b, int h, int qb, char* shm, float B2, int dry) {
;     ...
;         v[4][e] = x1 * cs - x2 * sn;
;         v[5][e] = x2 * cs + x1 * sn;
;       }
;     }
; #pragma unroll
;     for (int ks = 0; ks < 6; ++ks) {
;       i32x4 pk;
; #pragma unroll
;       for (int e = 0; e < 4; ++e) pk[e] = (int)pack2(v[ks][2 * e] * qscale, v[ks][2 * e + 1] * qscale);
;       qf[qs][ks] = __builtin_bit_cast(bf16x8, pk);
;     }
;   }
;   constexpr int KT_B = 24576, VT_B = 16384, BUF_B = KT_B + VT_B;
;   const int ntile = qb * 4 + 4;
;   const int my_last = qb * 4 + (wid >> 1);
;   f32x4 o[8][2];
; #pragma unroll
;   for (int i = 0; i < 8; ++i) { o[i][0] = f32x4{0.f, 0.f, 0.f, 0.f}; o[i][1] = f32x4{0.f, 0.f, 0.f, 0.f}; }
;   float lsum[2] = {0.f, 0.f};
;   int kR[3], kC[3], vR[2], vC[2];
; #pragma unroll
;   for (int i = 0; i < 3; ++i) stage_rc<6>((tid + i * 512) * 16, kR[i], kC[i]);
; #pragma unroll
;   for (int i = 0; i < 2; ++i) stage_rc<2>((tid + i * 512) * 16, vR[i], vC[i]);
;   int pk[3], pv[2];
; #pragma unroll
;   for (int i = 0; i < 3; ++i) pk[i] = kR[i] * 192 + kC[i];
; #pragma unroll
;   for (int i = 0; i < 2; ++i) pv[i] = vR[i] * SEQ + vC[i];
;     ...
;   A_STAGE(0, 0);
;   asm volatile("s_waitcnt vmcnt(0)" ::: "memory");
;   __syncthreads();
; #pragma clang loop unroll(disable)
;   for (int kt = 0; kt < ntile; ++kt) {
;     const int cur = kt & 1;
;     if (kt + 1 < ntile) A_STAGE(cur ^ 1, kt + 1);
	v_pk_fma_f32 v[0:1], v[0:1], v[20:21], v[4:5] neg_lo:[0,0,1] neg_hi:[0,0,1]
	s_nop 0
	v_pk_mul_f32 v[0:1], v[0:1], s[92:93] op_sel_hi:[1,0]
	s_nop 0
	v_cvt_pk_bf16_f32 v102, v0, v1
	v_pk_mul_f32 v[0:1], v[2:3], v[12:13]
	v_lshlrev_b32_e32 v2, 5, v55
	v_pk_fma_f32 v[0:1], v[92:93], v[22:23], v[0:1] neg_lo:[0,0,1] neg_hi:[0,0,1]
	v_lshlrev_b32_e32 v3, 5, v52
	v_pk_mul_f32 v[0:1], v[0:1], s[92:93] op_sel_hi:[1,0]
	s_nop 0
	v_cvt_pk_bf16_f32 v103, v0, v1
	v_pk_mul_f32 v[0:1], v[18:19], s[92:93] op_sel_hi:[1,0]
	s_nop 0
	v_cvt_pk_bf16_f32 v108, v0, v1
	v_pk_mul_f32 v[0:1], v[30:31], s[92:93] op_sel_hi:[1,0]
	s_nop 0
	v_cvt_pk_bf16_f32 v109, v0, v1
	v_pk_mul_f32 v[0:1], v[94:95], s[92:93] op_sel_hi:[1,0]
	s_nop 0
	v_cvt_pk_bf16_f32 v110, v0, v1
	v_pk_mul_f32 v[0:1], v[96:97], s[92:93] op_sel_hi:[1,0]
	s_nop 0
	v_cvt_pk_bf16_f32 v111, v0, v1
	v_lshlrev_b32_e32 v1, 2, v184
	v_lshlrev_b32_e32 v0, 6, v185
	v_and_b32_e32 v1, 32, v1
	v_bitop3_b32 v121, v132, v1, v0 bitop3:0x36
	v_lshlrev_b32_e32 v0, 5, v64
	v_mad_i32_i24 v0, v65, s63, v0
	v_lshlrev_b32_e32 v1, 5, v66
	v_sub_u32_e32 v0, v0, v1
	v_add_u32_e32 v122, 0x3000, v0
	v_lshlrev_b32_e32 v0, 5, v53
	v_mad_i32_i24 v1, v54, s63, v0
	v_sub_u32_e32 v1, v1, v2
	v_add_u32_e32 v123, 0x3000, v1
	v_lshlrev_b32_e32 v1, 5, v50
	v_mad_i32_i24 v2, v51, s63, v1
	v_sub_u32_e32 v2, v2, v3
	v_add_u32_e32 v124, 0x3000, v2
	v_add_u32_e32 v0, v0, v74
	v_lshlrev_b32_e32 v2, 5, v72
	v_sub_u32_e32 v0, v0, v2
	v_add_u32_e32 v125, 64, v0
	v_add_u32_e32 v0, v1, v73
	v_lshlrev_b32_e32 v1, 5, v67
	v_sub_u32_e32 v0, v0, v1
	v_mov_b32_e32 v2, v133
	v_mov_b32_e32 v3, v133
	v_add_u32_e32 v126, 64, v0
	v_mov_b32_e32 v132, v133
	v_mov_b32_e32 v0, v133
	v_mov_b32_e32 v1, v133
	v_mov_b64_e32 v[42:43], v[2:3]
	v_mov_b64_e32 v[6:7], v[2:3]
	v_mov_b64_e32 v[50:51], v[2:3]
	v_mov_b64_e32 v[10:11], v[2:3]
	v_mov_b64_e32 v[54:55], v[2:3]
	v_mov_b64_e32 v[14:15], v[2:3]
	v_mov_b64_e32 v[66:67], v[2:3]
	v_mov_b64_e32 v[18:19], v[2:3]
	v_mov_b64_e32 v[74:75], v[2:3]
	v_mov_b64_e32 v[22:23], v[2:3]
	v_mov_b64_e32 v[94:95], v[2:3]
	v_mov_b64_e32 v[26:27], v[2:3]
	v_mov_b64_e32 v[98:99], v[2:3]
	v_mov_b64_e32 v[30:31], v[2:3]
	v_mov_b64_e32 v[106:107], v[2:3]
	v_mov_b64_e32 v[40:41], v[0:1]
	v_mov_b64_e32 v[4:5], v[0:1]
	v_mov_b64_e32 v[48:49], v[0:1]
	v_mov_b64_e32 v[8:9], v[0:1]
	v_mov_b64_e32 v[52:53], v[0:1]
	v_mov_b64_e32 v[12:13], v[0:1]
	v_mov_b64_e32 v[64:65], v[0:1]
	v_mov_b64_e32 v[16:17], v[0:1]
	v_mov_b64_e32 v[72:73], v[0:1]
	v_mov_b64_e32 v[20:21], v[0:1]
	v_mov_b64_e32 v[92:93], v[0:1]
	v_mov_b64_e32 v[24:25], v[0:1]
	v_mov_b64_e32 v[96:97], v[0:1]
	v_mov_b64_e32 v[28:29], v[0:1]
	v_mov_b64_e32 v[104:105], v[0:1]
	v_mov_b64_e32 v[118:119], v[132:133]
	s_and_b32 s37, s36, 1
	s_add_i32 s35, s36, 1
	s_cmp_ge_u32 s35, s0
	s_cbranch_scc1 .LBB0_578
	s_branch .LBB0_577

; DI float bflo(unsigned v) { return __uint_as_float(v << 16); }
; DI float bfhi(unsigned v) { return __uint_as_float(v & 0xffff0000u); }
; DI void attn_c_item(const Params& P, int l, int b, int h, int qb, char* shm, float B2, int dry) {
;     ...
;   for (int kt = 0; kt < ntile; ++kt) {
;     const int cur = kt & 1;
;     if (kt + 1 < ntile) A_STAGE(cur ^ 1, kt + 1);
;     ...
;     asm volatile("s_waitcnt vmcnt(0)" ::: "memory");
;     __syncthreads();
;   }
;     ...
;   u16* actC = (u16*)(P.ws + OFF_ACTC);
; #pragma unroll
;   for (int qs = 0; qs < 2; ++qs) {
;     float lt = lsum[qs];
;     lt += __shfl_xor(lt, 16);
;     lt += __shfl_xor(lt, 32);
;     const float inv = 1.f / lt;
;     u16* dp = actC + (size_t)(b * SEQ + q0 + qs * 16 + fr) * 512 + h * 128 + fq * 4;
; #pragma unroll
;     for (int dvs = 0; dvs < 8; ++dvs) {
;       u32x2 gz = *(const u32x2*)(dp + dvs * 16);
;       u32x2 ov = {pack2(o[dvs][qs][0] * inv * bflo(gz[0]), o[dvs][qs][1] * inv * bfhi(gz[0])),
;                   pack2(o[dvs][qs][2] * inv * bflo(gz[1]), o[dvs][qs][3] * inv * bfhi(gz[1]))};
;       if (!dry) *(u32x2*)(dp + dvs * 16) = ov;
;     }
;   }
.LBB0_580:
	s_waitcnt vmcnt(0)
	v_add_u32_e32 v122, 0x3000, v122
	v_add_u32_e32 v123, 0x3000, v123
	v_add_u32_e32 v124, 0x3000, v124
	v_add_u32_e32 v125, 64, v125
	s_cmp_lg_u32 s0, s35
	v_add_u32_e32 v126, 64, v126
	s_waitcnt vmcnt(0) lgkmcnt(0)
	s_barrier
	s_cbranch_scc1 .LBB0_576
	ds_bpermute_b32 v32, v212, v119
	v_lshlrev_b32_e32 v132, 1, v116
	v_lshl_add_u64 v[34:35], s[18:19], 0, v[132:133]
	s_waitcnt lgkmcnt(0)
	v_add_f32_e32 v32, v119, v32
	ds_bpermute_b32 v33, v211, v32
	s_waitcnt lgkmcnt(0)
	v_add_f32_e32 v32, v32, v33
	v_div_scale_f32 v33, s[0:1], v32, v32, 1.0
	v_rcp_f32_e32 v36, v33
	s_nop 0
	v_fma_f32 v37, -v33, v36, 1.0
	v_fmac_f32_e32 v36, v37, v36
	v_div_scale_f32 v37, vcc, 1.0, v32, 1.0
	v_mul_f32_e32 v38, v37, v36
	v_fma_f32 v39, -v33, v38, v37
	v_fmac_f32_e32 v38, v39, v36
	v_fma_f32 v33, -v33, v38, v37
	v_div_fmas_f32 v33, v33, v36, v38
	v_lshlrev_b64 v[36:37], 10, v[114:115]
	v_lshl_add_u64 v[36:37], v[34:35], 0, v[36:37]
	global_load_dwordx2 v[38:39], v[36:37], off
	v_div_fixup_f32 v32, v33, v32, 1.0
	v_pk_mul_f32 v[44:45], v[104:105], v[32:33] op_sel_hi:[1,0]
	v_pk_mul_f32 v[40:41], v[40:41], v[32:33] op_sel_hi:[1,0]
	s_waitcnt vmcnt(0) lgkmcnt(0)
	v_lshlrev_b32_e32 v46, 16, v38
	v_and_b32_e32 v47, 0xffff0000, v38
	v_pk_mul_f32 v[44:45], v[44:45], v[46:47]
	v_lshlrev_b32_e32 v46, 16, v39
	v_cvt_pk_bf16_f32 v38, v44, v45
	v_pk_mul_f32 v[44:45], v[106:107], v[32:33] op_sel_hi:[1,0]
	v_and_b32_e32 v47, 0xffff0000, v39
	v_pk_mul_f32 v[44:45], v[44:45], v[46:47]
	s_nop 0
	v_cvt_pk_bf16_f32 v39, v44, v45
	global_store_dwordx2 v[36:37], v[38:39], off
	global_load_dwordx2 v[38:39], v[36:37], off offset:32
	v_pk_mul_f32 v[44:45], v[96:97], v[32:33] op_sel_hi:[1,0]
	s_waitcnt vmcnt(0) lgkmcnt(0)
	v_lshlrev_b32_e32 v46, 16, v38
	v_and_b32_e32 v47, 0xffff0000, v38
	v_pk_mul_f32 v[44:45], v[44:45], v[46:47]
	v_lshlrev_b32_e32 v46, 16, v39
	v_cvt_pk_bf16_f32 v38, v44, v45
	v_pk_mul_f32 v[44:45], v[98:99], v[32:33] op_sel_hi:[1,0]
	v_and_b32_e32 v47, 0xffff0000, v39
	v_pk_mul_f32 v[44:45], v[44:45], v[46:47]
	s_nop 0
	v_cvt_pk_bf16_f32 v39, v44, v45
	global_store_dwordx2 v[36:37], v[38:39], off offset:32
	global_load_dwordx2 v[38:39], v[36:37], off offset:64
	v_pk_mul_f32 v[44:45], v[92:93], v[32:33] op_sel_hi:[1,0]
	s_waitcnt vmcnt(0) lgkmcnt(0)
	v_lshlrev_b32_e32 v46, 16, v38
	v_and_b32_e32 v47, 0xffff0000, v38
	v_pk_mul_f32 v[44:45], v[44:45], v[46:47]
	v_lshlrev_b32_e32 v46, 16, v39
	v_cvt_pk_bf16_f32 v38, v44, v45
	v_pk_mul_f32 v[44:45], v[94:95], v[32:33] op_sel_hi:[1,0]
	v_and_b32_e32 v47, 0xffff0000, v39
	v_pk_mul_f32 v[44:45], v[44:45], v[46:47]
	s_nop 0
	v_cvt_pk_bf16_f32 v39, v44, v45
	global_store_dwordx2 v[36:37], v[38:39], off offset:64
	global_load_dwordx2 v[38:39], v[36:37], off offset:96
	v_pk_mul_f32 v[44:45], v[72:73], v[32:33] op_sel_hi:[1,0]
	s_waitcnt vmcnt(0) lgkmcnt(0)
	v_lshlrev_b32_e32 v46, 16, v38
	v_and_b32_e32 v47, 0xffff0000, v38
	v_pk_mul_f32 v[44:45], v[44:45], v[46:47]
	v_lshlrev_b32_e32 v46, 16, v39
	v_cvt_pk_bf16_f32 v38, v44, v45
	v_pk_mul_f32 v[44:45], v[74:75], v[32:33] op_sel_hi:[1,0]
	v_and_b32_e32 v47, 0xffff0000, v39
	v_pk_mul_f32 v[44:45], v[44:45], v[46:47]
	s_nop 0
	v_cvt_pk_bf16_f32 v39, v44, v45
	global_store_dwordx2 v[36:37], v[38:39], off offset:96
	global_load_dwordx2 v[38:39], v[36:37], off offset:128
	v_pk_mul_f32 v[44:45], v[64:65], v[32:33] op_sel_hi:[1,0]
	s_waitcnt vmcnt(0) lgkmcnt(0)
	v_lshlrev_b32_e32 v46, 16, v38
	v_and_b32_e32 v47, 0xffff0000, v38
	v_pk_mul_f32 v[44:45], v[44:45], v[46:47]
	v_lshlrev_b32_e32 v46, 16, v39
	v_cvt_pk_bf16_f32 v38, v44, v45
	v_pk_mul_f32 v[44:45], v[66:67], v[32:33] op_sel_hi:[1,0]
	v_and_b32_e32 v47, 0xffff0000, v39
	v_pk_mul_f32 v[44:45], v[44:45], v[46:47]
	s_nop 0
	v_cvt_pk_bf16_f32 v39, v44, v45
	global_store_dwordx2 v[36:37], v[38:39], off offset:128
	global_load_dwordx2 v[38:39], v[36:37], off offset:160
	v_pk_mul_f32 v[44:45], v[52:53], v[32:33] op_sel_hi:[1,0]
	s_waitcnt vmcnt(0) lgkmcnt(0)
	v_lshlrev_b32_e32 v46, 16, v38
	v_and_b32_e32 v47, 0xffff0000, v38
	v_pk_mul_f32 v[44:45], v[44:45], v[46:47]
	v_lshlrev_b32_e32 v46, 16, v39
	v_cvt_pk_bf16_f32 v38, v44, v45
	v_pk_mul_f32 v[44:45], v[54:55], v[32:33] op_sel_hi:[1,0]
	v_and_b32_e32 v47, 0xffff0000, v39
	v_pk_mul_f32 v[44:45], v[44:45], v[46:47]
	s_nop 0
	v_cvt_pk_bf16_f32 v39, v44, v45
	global_store_dwordx2 v[36:37], v[38:39], off offset:160
	global_load_dwordx2 v[38:39], v[36:37], off offset:192
	v_pk_mul_f32 v[44:45], v[48:49], v[32:33] op_sel_hi:[1,0]
	s_waitcnt vmcnt(0) lgkmcnt(0)
	v_lshlrev_b32_e32 v46, 16, v38
	v_and_b32_e32 v47, 0xffff0000, v38
	v_pk_mul_f32 v[44:45], v[44:45], v[46:47]
	v_lshlrev_b32_e32 v46, 16, v39
	v_cvt_pk_bf16_f32 v38, v44, v45
	v_pk_mul_f32 v[44:45], v[50:51], v[32:33] op_sel_hi:[1,0]
	v_and_b32_e32 v47, 0xffff0000, v39
	v_pk_mul_f32 v[44:45], v[44:45], v[46:47]
	v_pk_mul_f32 v[32:33], v[42:43], v[32:33] op_sel_hi:[1,0]
	v_cvt_pk_bf16_f32 v39, v44, v45
	global_store_dwordx2 v[36:37], v[38:39], off offset:192
	global_load_dwordx2 v[38:39], v[36:37], off offset:224
	s_waitcnt vmcnt(0) lgkmcnt(0)
	v_lshlrev_b32_e32 v44, 16, v38
	v_and_b32_e32 v45, 0xffff0000, v38
	v_pk_mul_f32 v[40:41], v[40:41], v[44:45]
	s_nop 0
	v_cvt_pk_bf16_f32 v38, v40, v41
	v_lshlrev_b32_e32 v40, 16, v39
	v_and_b32_e32 v41, 0xffff0000, v39
	v_pk_mul_f32 v[32:33], v[32:33], v[40:41]
	s_nop 0
	v_cvt_pk_bf16_f32 v39, v32, v33
	ds_bpermute_b32 v32, v212, v118
	global_store_dwordx2 v[36:37], v[38:39], off offset:224
	s_waitcnt lgkmcnt(0)
; DI float bflo(unsigned v) { return __uint_as_float(v << 16); }
; DI float bfhi(unsigned v) { return __uint_as_float(v & 0xffff0000u); }
; DI void attn_c_item(const Params& P, int l, int b, int h, int qb, char* shm, float B2, int dry) {
;     ...
;   for (int qs = 0; qs < 2; ++qs) {
;     float lt = lsum[qs];
;     lt += __shfl_xor(lt, 16);
;     lt += __shfl_xor(lt, 32);
;     const float inv = 1.f / lt;
;     u16* dp = actC + (size_t)(b * SEQ + q0 + qs * 16 + fr) * 512 + h * 128 + fq * 4;
; #pragma unroll
;     for (int dvs = 0; dvs < 8; ++dvs) {
;       u32x2 gz = *(const u32x2*)(dp + dvs * 16);
;       u32x2 ov = {pack2(o[dvs][qs][0] * inv * bflo(gz[0]), o[dvs][qs][1] * inv * bfhi(gz[0])),
;                   pack2(o[dvs][qs][2] * inv * bflo(gz[1]), o[dvs][qs][3] * inv * bfhi(gz[1]))};
;       if (!dry) *(u32x2*)(dp + dvs * 16) = ov;
;     }
;   }
; DI void phase_attn_c(const Params& P, int l, char* shm, int dry) {
;     ...
;   for (int it = blockIdx.x; it < 256; it += gridDim.x) {
;     const int bh = it >> 4, pr = it & 15, b = bh >> 2, h = bh & 3;
; #pragma clang loop unroll(disable)
;     for (int hf = 0; hf < 2; ++hf) attn_c_item(P, l, b, h, hf ? pr : 31 - pr, shm, B2, dry);
	v_add_f32_e32 v32, v118, v32
	ds_bpermute_b32 v33, v211, v32
	s_waitcnt lgkmcnt(0)
	v_add_f32_e32 v32, v32, v33
	v_div_scale_f32 v33, s[0:1], v32, v32, 1.0
	v_rcp_f32_e32 v36, v33
	s_mov_b64 s[0:1], 0
	v_fma_f32 v37, -v33, v36, 1.0
	v_fmac_f32_e32 v36, v37, v36
	v_div_scale_f32 v37, vcc, 1.0, v32, 1.0
	v_mul_f32_e32 v38, v37, v36
	v_fma_f32 v39, -v33, v38, v37
	v_fmac_f32_e32 v38, v39, v36
	v_fma_f32 v33, -v33, v38, v37
	v_div_fmas_f32 v33, v33, v36, v38
	v_lshlrev_b64 v[36:37], 10, v[112:113]
	v_lshl_add_u64 v[34:35], v[34:35], 0, v[36:37]
	global_load_dwordx2 v[36:37], v[34:35], off
	v_div_fixup_f32 v32, v33, v32, 1.0
	v_pk_mul_f32 v[28:29], v[28:29], v[32:33] op_sel_hi:[1,0]
	v_pk_mul_f32 v[30:31], v[30:31], v[32:33] op_sel_hi:[1,0]
	v_pk_mul_f32 v[24:25], v[24:25], v[32:33] op_sel_hi:[1,0]
	v_pk_mul_f32 v[26:27], v[26:27], v[32:33] op_sel_hi:[1,0]
	v_pk_mul_f32 v[20:21], v[20:21], v[32:33] op_sel_hi:[1,0]
	v_pk_mul_f32 v[22:23], v[22:23], v[32:33] op_sel_hi:[1,0]
	v_pk_mul_f32 v[16:17], v[16:17], v[32:33] op_sel_hi:[1,0]
	v_pk_mul_f32 v[18:19], v[18:19], v[32:33] op_sel_hi:[1,0]
	v_pk_mul_f32 v[12:13], v[12:13], v[32:33] op_sel_hi:[1,0]
	v_pk_mul_f32 v[14:15], v[14:15], v[32:33] op_sel_hi:[1,0]
	v_pk_mul_f32 v[8:9], v[8:9], v[32:33] op_sel_hi:[1,0]
	v_pk_mul_f32 v[10:11], v[10:11], v[32:33] op_sel_hi:[1,0]
	v_pk_mul_f32 v[4:5], v[4:5], v[32:33] op_sel_hi:[1,0]
	v_pk_mul_f32 v[6:7], v[6:7], v[32:33] op_sel_hi:[1,0]
	v_pk_mul_f32 v[0:1], v[0:1], v[32:33] op_sel_hi:[1,0]
	v_pk_mul_f32 v[2:3], v[2:3], v[32:33] op_sel_hi:[1,0]
	s_and_b64 vcc, exec, s[20:21]
	s_waitcnt vmcnt(0) lgkmcnt(0)
	v_lshlrev_b32_e32 v38, 16, v36
	v_and_b32_e32 v39, 0xffff0000, v36
	v_lshlrev_b32_e32 v36, 16, v37
	v_and_b32_e32 v37, 0xffff0000, v37
	v_pk_mul_f32 v[28:29], v[28:29], v[38:39]
	v_pk_mul_f32 v[30:31], v[30:31], v[36:37]
	v_cvt_pk_bf16_f32 v28, v28, v29
	v_cvt_pk_bf16_f32 v29, v30, v31
	global_store_dwordx2 v[34:35], v[28:29], off
	global_load_dwordx2 v[28:29], v[34:35], off offset:32
	s_waitcnt vmcnt(0) lgkmcnt(0)
	v_lshlrev_b32_e32 v30, 16, v28
	v_and_b32_e32 v31, 0xffff0000, v28
	v_lshlrev_b32_e32 v28, 16, v29
	v_and_b32_e32 v29, 0xffff0000, v29
	v_pk_mul_f32 v[24:25], v[24:25], v[30:31]
	v_pk_mul_f32 v[26:27], v[26:27], v[28:29]
	v_cvt_pk_bf16_f32 v24, v24, v25
	v_cvt_pk_bf16_f32 v25, v26, v27
	global_store_dwordx2 v[34:35], v[24:25], off offset:32
	global_load_dwordx2 v[24:25], v[34:35], off offset:64
	s_waitcnt vmcnt(0) lgkmcnt(0)
	v_lshlrev_b32_e32 v26, 16, v24
	v_and_b32_e32 v27, 0xffff0000, v24
	v_lshlrev_b32_e32 v24, 16, v25
	v_and_b32_e32 v25, 0xffff0000, v25
	v_pk_mul_f32 v[20:21], v[20:21], v[26:27]
	v_pk_mul_f32 v[22:23], v[22:23], v[24:25]
	v_cvt_pk_bf16_f32 v20, v20, v21
	v_cvt_pk_bf16_f32 v21, v22, v23
	global_store_dwordx2 v[34:35], v[20:21], off offset:64
	global_load_dwordx2 v[20:21], v[34:35], off offset:96
	s_waitcnt vmcnt(0) lgkmcnt(0)
	v_lshlrev_b32_e32 v22, 16, v20
	v_and_b32_e32 v23, 0xffff0000, v20
	v_lshlrev_b32_e32 v20, 16, v21
	v_and_b32_e32 v21, 0xffff0000, v21
	v_pk_mul_f32 v[16:17], v[16:17], v[22:23]
	v_pk_mul_f32 v[18:19], v[18:19], v[20:21]
	v_cvt_pk_bf16_f32 v16, v16, v17
	v_cvt_pk_bf16_f32 v17, v18, v19
	global_store_dwordx2 v[34:35], v[16:17], off offset:96
	global_load_dwordx2 v[16:17], v[34:35], off offset:128
	s_waitcnt vmcnt(0) lgkmcnt(0)
	v_lshlrev_b32_e32 v18, 16, v16
	v_and_b32_e32 v19, 0xffff0000, v16
	v_lshlrev_b32_e32 v16, 16, v17
	v_and_b32_e32 v17, 0xffff0000, v17
	v_pk_mul_f32 v[12:13], v[12:13], v[18:19]
	v_pk_mul_f32 v[14:15], v[14:15], v[16:17]
	v_cvt_pk_bf16_f32 v12, v12, v13
	v_cvt_pk_bf16_f32 v13, v14, v15
	global_store_dwordx2 v[34:35], v[12:13], off offset:128
	global_load_dwordx2 v[12:13], v[34:35], off offset:160
	s_waitcnt vmcnt(0) lgkmcnt(0)
	v_lshlrev_b32_e32 v14, 16, v12
	v_and_b32_e32 v15, 0xffff0000, v12
	v_lshlrev_b32_e32 v12, 16, v13
	v_and_b32_e32 v13, 0xffff0000, v13
	v_pk_mul_f32 v[8:9], v[8:9], v[14:15]
	v_pk_mul_f32 v[10:11], v[10:11], v[12:13]
	v_cvt_pk_bf16_f32 v8, v8, v9
	v_cvt_pk_bf16_f32 v9, v10, v11
	global_store_dwordx2 v[34:35], v[8:9], off offset:160
	global_load_dwordx2 v[8:9], v[34:35], off offset:192
	s_waitcnt vmcnt(0) lgkmcnt(0)
	v_lshlrev_b32_e32 v10, 16, v8
	v_and_b32_e32 v11, 0xffff0000, v8
	v_lshlrev_b32_e32 v8, 16, v9
	v_and_b32_e32 v9, 0xffff0000, v9
	v_pk_mul_f32 v[4:5], v[4:5], v[10:11]
	v_pk_mul_f32 v[6:7], v[6:7], v[8:9]
	v_cvt_pk_bf16_f32 v4, v4, v5
	v_cvt_pk_bf16_f32 v5, v6, v7
	global_store_dwordx2 v[34:35], v[4:5], off offset:192
	global_load_dwordx2 v[4:5], v[34:35], off offset:224
	s_waitcnt vmcnt(0) lgkmcnt(0)
	v_lshlrev_b32_e32 v6, 16, v4
	v_and_b32_e32 v7, 0xffff0000, v4
	v_lshlrev_b32_e32 v4, 16, v5
	v_and_b32_e32 v5, 0xffff0000, v5
	v_pk_mul_f32 v[0:1], v[0:1], v[6:7]
	v_pk_mul_f32 v[2:3], v[2:3], v[4:5]
	v_cvt_pk_bf16_f32 v0, v0, v1
	v_cvt_pk_bf16_f32 v1, v2, v3
	global_store_dwordx2 v[34:35], v[0:1], off offset:224
	s_cbranch_vccz .LBB0_575
	s_add_i32 s28, s28, s72
	s_cmpk_gt_i32 s28, 0xff
	s_cbranch_scc0 .LBB0_574
	v_readlane_b32 s50, v252, 18
	v_readlane_b32 s51, v252, 19
	s_movk_i32 s42, 0xfc0
	v_readlane_b32 s46, v252, 31
	s_mov_b64 s[34:35], 0x20000
	s_mov_b64 s[36:37], 0x8000
	s_mov_b64 s[38:39], 0x18000

; DI int tid_() { int t = threadIdx.x; asm volatile("" : "+v"(t)); return t; }
; template <int MODE>
; DI void phase_inproj(const Params& P, char* shm) {
;     ...
;     for (int i = 0; i < 16; ++i) {
;       const int chunk = tid_() + i * 512, row = chunk >> 5, c8 = (chunk & 31) * 8;
;       const i32x4 v = *(const i32x4*)(shm + row * 528 + c8 * 2);
;       const int gcol = bcol + c8;
;       u16* d = nullptr;
;       if (MODE == 0) {
;         if (gcol < 448) d = (u16*)(P.ws + OFF_PROJC) + (size_t)(brow + row) * 448 + gcol;
;         else if (gcol >= 512) d = (u16*)(P.ws + OFF_ACTC) + (size_t)(brow + row) * 512 + (gcol - 512);
;       } else if (MODE == 1) {
;         if (gcol < 1024) d = (u16*)(P.ws + OFF_PROJD) + (size_t)(brow + row) * 1024 + gcol;
;         else if (gcol < 1536) {
;           const int c2 = gcol - c8 - 1024 + row;
;           const int b = brow >> 13, s0 = brow & 8191;
;           d = (u16*)(P.ws + OFF_VTD) + ((size_t)((b * 4 + (c2 >> 7)) * 128 + (c2 & 127))) * SEQ + s0 + c8;
;         } else d = (u16*)(P.ws + OFF_ACTD) + (size_t)(brow + row) * 512 + (gcol - 1536);
;       } else if (MODE == 2) {
;         if (gcol < 1024) d = (u16*)(P.ws + OFF_PROJA) + (size_t)(brow + row) * 1024 + gcol;
;         else d = (u16*)(P.ws + OFF_ACTA) + (size_t)(brow + row) * 512 + (gcol - 1024);
;       } else {
;         if (gcol < 512) d = (u16*)(P.ws + OFF_PROJB) + (size_t)(brow + row) * 512 + gcol;
;         else d = (u16*)(P.ws + OFF_ACTB) + (size_t)(brow + row) * 512 + (gcol - 512);
;       }
;       if (d) *(i32x4*)d = v;
;     }
.LBB0_656:
	s_or_b64 exec, exec, s[0:1]
	s_addk_i32 s4, 0x800
	s_cmpk_eq_i32 s4, 0x2000
	s_waitcnt lgkmcnt(0)
	global_store_dwordx4 v[4:5], v[0:3], off
	s_cbranch_scc1 .LBB0_586
.LBB0_657:
	s_nop 0
	v_mov_b32_e32 v0, v135
	s_nop 0
	v_add_u32_e32 v1, s4, v0
	v_ashrrev_i32_e32 v5, 5, v1
	v_lshlrev_b32_e32 v0, 3, v0
	v_and_b32_e32 v4, 0xf8, v0
	v_mul_lo_u32 v0, v5, s68
	v_lshl_add_u32 v0, v4, 1, v0
	ds_read_b128 v[0:3], v0
	v_or_b32_e32 v4, s14, v4
	v_add_u32_e32 v8, s12, v5
	v_cmp_lt_i32_e32 vcc, s91, v4
	v_ashrrev_i32_e32 v9, 31, v8
	s_and_saveexec_b64 s[0:1], vcc
	s_xor_b64 s[0:1], exec, s[0:1]
	v_lshlrev_b64 v[6:7], 10, v[8:9]
	v_lshl_add_u64 v[6:7], s[8:9], 0, v[6:7]
	v_mov_b32_e32 v5, v133
	v_lshl_add_u64 v[4:5], v[4:5], 1, v[6:7]
	v_lshl_add_u64 v[6:7], v[4:5], 0, s[24:25]
	s_andn2_saveexec_b64 s[0:1], s[0:1]
	v_lshlrev_b64 v[6:7], 11, v[8:9]
	v_lshl_add_u64 v[6:7], s[10:11], 0, v[6:7]
	v_ashrrev_i32_e32 v5, 31, v4
	v_lshl_add_u64 v[6:7], v[4:5], 1, v[6:7]
	s_or_b64 exec, exec, s[0:1]
	s_waitcnt lgkmcnt(0)
	global_store_dwordx4 v[6:7], v[0:3], off
	s_nop 1
	v_mov_b32_e32 v0, v135
	s_nop 0
	v_add_u32_e32 v1, s4, v0
	v_add_u32_e32 v1, 0x200, v1
	v_ashrrev_i32_e32 v4, 5, v1
	v_lshlrev_b32_e32 v0, 3, v0
	v_and_b32_e32 v5, 0xf8, v0
	v_mul_lo_u32 v0, v4, s68
	v_lshl_add_u32 v0, v5, 1, v0
	ds_read_b128 v[0:3], v0
	v_or_b32_e32 v132, s14, v5
	v_add_u32_e32 v6, s12, v4
	v_cmp_lt_i32_e32 vcc, s91, v132
	v_ashrrev_i32_e32 v7, 31, v6
	s_and_saveexec_b64 s[0:1], vcc
	s_xor_b64 s[0:1], exec, s[0:1]
	v_lshlrev_b64 v[4:5], 10, v[6:7]
	v_lshl_add_u64 v[4:5], s[8:9], 0, v[4:5]
	v_lshl_add_u64 v[4:5], v[132:133], 1, v[4:5]
	v_lshl_add_u64 v[4:5], v[4:5], 0, s[24:25]
	s_andn2_saveexec_b64 s[0:1], s[0:1]
	v_lshlrev_b64 v[4:5], 11, v[6:7]
	v_lshl_add_u64 v[4:5], s[10:11], 0, v[4:5]
	v_ashrrev_i32_e32 v7, 31, v132
	v_mov_b32_e32 v6, v132
	v_lshl_add_u64 v[4:5], v[6:7], 1, v[4:5]
	s_or_b64 exec, exec, s[0:1]
	s_waitcnt lgkmcnt(0)
	global_store_dwordx4 v[4:5], v[0:3], off
	s_nop 1
	v_mov_b32_e32 v0, v135
	s_nop 0
	v_add_u32_e32 v1, s4, v0
	v_add_u32_e32 v1, 0x400, v1
	v_ashrrev_i32_e32 v4, 5, v1
	v_lshlrev_b32_e32 v0, 3, v0
	v_and_b32_e32 v5, 0xf8, v0
	v_mul_lo_u32 v0, v4, s68
	v_lshl_add_u32 v0, v5, 1, v0
	ds_read_b128 v[0:3], v0
	v_or_b32_e32 v132, s14, v5
	v_add_u32_e32 v6, s12, v4
	v_cmp_lt_i32_e32 vcc, s91, v132
	v_ashrrev_i32_e32 v7, 31, v6
	s_and_saveexec_b64 s[0:1], vcc
	s_xor_b64 s[0:1], exec, s[0:1]
	v_lshlrev_b64 v[4:5], 10, v[6:7]
	v_lshl_add_u64 v[4:5], s[8:9], 0, v[4:5]
	v_lshl_add_u64 v[4:5], v[132:133], 1, v[4:5]
	v_lshl_add_u64 v[4:5], v[4:5], 0, s[24:25]
	s_andn2_saveexec_b64 s[0:1], s[0:1]
	v_lshlrev_b64 v[4:5], 11, v[6:7]
	v_lshl_add_u64 v[4:5], s[10:11], 0, v[4:5]
	v_ashrrev_i32_e32 v7, 31, v132
	v_mov_b32_e32 v6, v132
	v_lshl_add_u64 v[4:5], v[6:7], 1, v[4:5]
	s_or_b64 exec, exec, s[0:1]
	s_waitcnt lgkmcnt(0)
	global_store_dwordx4 v[4:5], v[0:3], off
	s_nop 1
	v_mov_b32_e32 v0, v135
	s_nop 0
	v_add_u32_e32 v1, s4, v0
	v_add_u32_e32 v1, 0x600, v1
	v_ashrrev_i32_e32 v4, 5, v1
	v_lshlrev_b32_e32 v0, 3, v0
	v_and_b32_e32 v5, 0xf8, v0
	v_mul_lo_u32 v0, v4, s68
	v_lshl_add_u32 v0, v5, 1, v0
	ds_read_b128 v[0:3], v0
	v_or_b32_e32 v132, s14, v5
	v_add_u32_e32 v6, s12, v4
	v_cmp_lt_i32_e32 vcc, s91, v132
	v_ashrrev_i32_e32 v7, 31, v6
	s_and_saveexec_b64 s[0:1], vcc
	s_xor_b64 s[0:1], exec, s[0:1]
	v_lshlrev_b64 v[4:5], 10, v[6:7]
	v_lshl_add_u64 v[4:5], s[8:9], 0, v[4:5]
	v_lshl_add_u64 v[4:5], v[132:133], 1, v[4:5]
	v_lshl_add_u64 v[4:5], v[4:5], 0, s[24:25]
	s_andn2_saveexec_b64 s[0:1], s[0:1]
	s_cbranch_execz .LBB0_656
	v_lshlrev_b64 v[4:5], 11, v[6:7]
	v_lshl_add_u64 v[4:5], s[10:11], 0, v[4:5]
	v_ashrrev_i32_e32 v7, 31, v132
	v_mov_b32_e32 v6, v132
	v_lshl_add_u64 v[4:5], v[6:7], 1, v[4:5]
	s_branch .LBB0_656

; DI int tid_() { int t = threadIdx.x; asm volatile("" : "+v"(t)); return t; }
; template <int MODE>
; DI void phase_inproj(const Params& P, char* shm) {
;     ...
;     for (int i = 0; i < 16; ++i) {
;       const int chunk = tid_() + i * 512, row = chunk >> 5, c8 = (chunk & 31) * 8;
;       const i32x4 v = *(const i32x4*)(shm + row * 528 + c8 * 2);
;       const int gcol = bcol + c8;
;       u16* d = nullptr;
;       if (MODE == 0) {
;         if (gcol < 448) d = (u16*)(P.ws + OFF_PROJC) + (size_t)(brow + row) * 448 + gcol;
;         else if (gcol >= 512) d = (u16*)(P.ws + OFF_ACTC) + (size_t)(brow + row) * 512 + (gcol - 512);
;       } else if (MODE == 1) {
;         if (gcol < 1024) d = (u16*)(P.ws + OFF_PROJD) + (size_t)(brow + row) * 1024 + gcol;
;         else if (gcol < 1536) {
;           const int c2 = gcol - c8 - 1024 + row;
;           const int b = brow >> 13, s0 = brow & 8191;
;           d = (u16*)(P.ws + OFF_VTD) + ((size_t)((b * 4 + (c2 >> 7)) * 128 + (c2 & 127))) * SEQ + s0 + c8;
;         } else d = (u16*)(P.ws + OFF_ACTD) + (size_t)(brow + row) * 512 + (gcol - 1536);
;       } else if (MODE == 2) {
;         if (gcol < 1024) d = (u16*)(P.ws + OFF_PROJA) + (size_t)(brow + row) * 1024 + gcol;
;         else d = (u16*)(P.ws + OFF_ACTA) + (size_t)(brow + row) * 512 + (gcol - 1024);
;       } else {
;         if (gcol < 512) d = (u16*)(P.ws + OFF_PROJB) + (size_t)(brow + row) * 512 + gcol;
;         else d = (u16*)(P.ws + OFF_ACTB) + (size_t)(brow + row) * 512 + (gcol - 512);
;       }
;       if (d) *(i32x4*)d = v;
;     }
.LBB0_746:
	s_nop 0
	v_mov_b32_e32 v0, v135
	s_nop 0
	v_add_u32_e32 v1, s4, v0
	v_ashrrev_i32_e32 v5, 5, v1
	v_lshlrev_b32_e32 v0, 3, v0
	v_and_b32_e32 v4, 0xf8, v0
	v_mul_lo_u32 v0, v5, s68
	v_lshl_add_u32 v0, v4, 1, v0
	ds_read_b128 v[0:3], v0
	v_add_u32_e32 v6, s12, v5
	v_or_b32_e32 v4, s14, v4
	v_ashrrev_i32_e32 v7, 31, v6
	v_cmp_lt_i32_e32 vcc, s89, v4
	v_lshlrev_b64 v[8:9], 10, v[6:7]
	s_and_saveexec_b64 s[0:1], vcc
	s_xor_b64 s[0:1], exec, s[0:1]
	v_lshl_add_u64 v[6:7], s[8:9], 0, v[8:9]
	v_mov_b32_e32 v5, v133
	v_lshl_add_u64 v[4:5], v[4:5], 1, v[6:7]
	v_lshl_add_u64 v[6:7], v[4:5], 0, s[94:95]
	s_andn2_saveexec_b64 s[0:1], s[0:1]
	v_lshl_add_u64 v[6:7], s[10:11], 0, v[8:9]
	v_ashrrev_i32_e32 v5, 31, v4
	v_lshl_add_u64 v[6:7], v[4:5], 1, v[6:7]
	s_or_b64 exec, exec, s[0:1]
	s_waitcnt lgkmcnt(0)
	global_store_dwordx4 v[6:7], v[0:3], off
	s_nop 1
	v_mov_b32_e32 v0, v135
	s_nop 0
	v_add_u32_e32 v1, s4, v0
	v_add_u32_e32 v1, 0x200, v1
	v_ashrrev_i32_e32 v4, 5, v1
	v_lshlrev_b32_e32 v0, 3, v0
	v_and_b32_e32 v5, 0xf8, v0
	v_mul_lo_u32 v0, v4, s68
	v_lshl_add_u32 v0, v5, 1, v0
	ds_read_b128 v[0:3], v0
	v_add_u32_e32 v4, s12, v4
	v_or_b32_e32 v132, s14, v5
	v_ashrrev_i32_e32 v5, 31, v4
	v_cmp_lt_i32_e32 vcc, s89, v132
	v_lshlrev_b64 v[6:7], 10, v[4:5]
	s_and_saveexec_b64 s[0:1], vcc
	s_xor_b64 s[0:1], exec, s[0:1]
	v_lshl_add_u64 v[4:5], s[8:9], 0, v[6:7]
	v_lshl_add_u64 v[4:5], v[132:133], 1, v[4:5]
	v_lshl_add_u64 v[4:5], v[4:5], 0, s[94:95]
	s_andn2_saveexec_b64 s[0:1], s[0:1]
	v_lshl_add_u64 v[4:5], s[10:11], 0, v[6:7]
	v_ashrrev_i32_e32 v7, 31, v132
	v_mov_b32_e32 v6, v132
	v_lshl_add_u64 v[4:5], v[6:7], 1, v[4:5]
	s_or_b64 exec, exec, s[0:1]
	s_waitcnt lgkmcnt(0)
	global_store_dwordx4 v[4:5], v[0:3], off
	s_nop 1
	v_mov_b32_e32 v0, v135
	s_nop 0
	v_add_u32_e32 v1, s4, v0
	v_add_u32_e32 v1, 0x400, v1
	v_ashrrev_i32_e32 v4, 5, v1
	v_lshlrev_b32_e32 v0, 3, v0
	v_and_b32_e32 v5, 0xf8, v0
	v_mul_lo_u32 v0, v4, s68
	v_lshl_add_u32 v0, v5, 1, v0
	ds_read_b128 v[0:3], v0
	v_add_u32_e32 v4, s12, v4
	v_or_b32_e32 v132, s14, v5
	v_ashrrev_i32_e32 v5, 31, v4
	v_cmp_lt_i32_e32 vcc, s89, v132
	v_lshlrev_b64 v[6:7], 10, v[4:5]
	s_and_saveexec_b64 s[0:1], vcc
	s_xor_b64 s[0:1], exec, s[0:1]
	v_lshl_add_u64 v[4:5], s[8:9], 0, v[6:7]
	v_lshl_add_u64 v[4:5], v[132:133], 1, v[4:5]
	v_lshl_add_u64 v[4:5], v[4:5], 0, s[94:95]
	s_andn2_saveexec_b64 s[0:1], s[0:1]
	v_lshl_add_u64 v[4:5], s[10:11], 0, v[6:7]
	v_ashrrev_i32_e32 v7, 31, v132
	v_mov_b32_e32 v6, v132
	v_lshl_add_u64 v[4:5], v[6:7], 1, v[4:5]
	s_or_b64 exec, exec, s[0:1]
	s_waitcnt lgkmcnt(0)
	global_store_dwordx4 v[4:5], v[0:3], off
	s_nop 1
	v_mov_b32_e32 v0, v135
	s_nop 0
	v_add_u32_e32 v1, s4, v0
	v_add_u32_e32 v1, 0x600, v1
	v_ashrrev_i32_e32 v4, 5, v1
	v_lshlrev_b32_e32 v0, 3, v0
	v_and_b32_e32 v5, 0xf8, v0
	v_mul_lo_u32 v0, v4, s68
	v_lshl_add_u32 v0, v5, 1, v0
	ds_read_b128 v[0:3], v0
	v_add_u32_e32 v4, s12, v4
	v_or_b32_e32 v132, s14, v5
	v_ashrrev_i32_e32 v5, 31, v4
	v_cmp_lt_i32_e32 vcc, s89, v132
	v_lshlrev_b64 v[6:7], 10, v[4:5]
	s_and_saveexec_b64 s[0:1], vcc
	s_xor_b64 s[0:1], exec, s[0:1]
	v_lshl_add_u64 v[4:5], s[8:9], 0, v[6:7]
	v_lshl_add_u64 v[4:5], v[132:133], 1, v[4:5]
	v_lshl_add_u64 v[4:5], v[4:5], 0, s[94:95]
	s_andn2_saveexec_b64 s[0:1], s[0:1]
	s_cbranch_execz .LBB0_745
	v_lshl_add_u64 v[4:5], s[10:11], 0, v[6:7]
	v_ashrrev_i32_e32 v7, 31, v132
	v_mov_b32_e32 v6, v132
	v_lshl_add_u64 v[4:5], v[6:7], 1, v[4:5]
	s_branch .LBB0_745

; DI float bflo(unsigned v) { return __uint_as_float(v << 16); }
; DI float bfhi(unsigned v) { return __uint_as_float(v & 0xffff0000u); }
;     ...
;       const int tok = tid >> 2, qu = tid & 3;
;       const u16* p = projA + (size_t)(T0 + tok) * 1024 + 512 + qu * 128;
;       float s1 = 0.f, s2 = 0.f;
; #pragma unroll
;       for (int i = 0; i < 16; ++i) {
;         i32x4 v = *(const i32x4*)(p + i * 8);
; #pragma unroll
;         for (int e = 0; e < 4; ++e) {
;           float a = bflo((unsigned)v[e]), c = bfhi((unsigned)v[e]);
;           s1 += a + c;
;           s2 += a * a + c * c;
;         }
;       }
.LBB0_778:
	v_lshl_add_u32 v0, s4, 7, v29
	v_ashrrev_i32_e32 v1, 31, v0
	v_lshlrev_b64 v[0:1], 11, v[0:1]
	v_lshl_add_u64 v[0:1], s[12:13], 0, v[0:1]
	v_lshl_add_u64 v[0:1], v[0:1], 0, v[132:133]
	global_load_dwordx4 v[2:5], v[0:1], off offset:1024
	s_waitcnt vmcnt(0) lgkmcnt(0)
	v_lshlrev_b32_e32 v11, 16, v3
	v_and_b32_e32 v7, 0xffff0000, v2
	v_lshlrev_b32_e32 v10, 16, v2
	v_mov_b32_e32 v2, v11
	v_and_b32_e32 v9, 0xffff0000, v3
	v_pk_mul_f32 v[36:37], v[10:11], v[2:3] op_sel:[1,0] op_sel_hi:[0,1]
	v_pk_add_f32 v[2:3], v[10:11], v[6:7] op_sel:[1,0] op_sel_hi:[0,1]
	v_mov_b32_e32 v37, v3
	v_lshlrev_b32_e32 v39, 16, v4
	v_and_b32_e32 v41, 0xffff0000, v4
	v_lshlrev_b32_e32 v43, 16, v5
	v_and_b32_e32 v45, 0xffff0000, v5
	global_load_dwordx4 v[2:5], v[0:1], off offset:1040
	v_mul_f32_e32 v34, v10, v10
	v_mul_f32_e32 v6, v9, v9
	v_mov_b32_e32 v35, v11
	v_mul_f32_e32 v8, v7, v7
	v_mov_b32_e32 v7, v133
	v_mul_f32_e32 v38, v39, v39
	v_mul_f32_e32 v40, v41, v41
	v_pk_add_f32 v[8:9], v[34:35], v[8:9]
	v_pk_add_f32 v[6:7], v[36:37], v[6:7]
	v_mul_f32_e32 v42, v43, v43
	v_mul_f32_e32 v44, v45, v45
	v_pk_add_f32 v[6:7], v[8:9], v[6:7]
	v_pk_add_f32 v[8:9], v[38:39], v[40:41]
	s_waitcnt vmcnt(0) lgkmcnt(0)
	v_lshlrev_b32_e32 v47, 16, v2
	v_and_b32_e32 v49, 0xffff0000, v2
	v_lshlrev_b32_e32 v51, 16, v3
	v_and_b32_e32 v53, 0xffff0000, v3
	v_lshlrev_b32_e32 v55, 16, v4
	v_and_b32_e32 v57, 0xffff0000, v4
	v_lshlrev_b32_e32 v59, 16, v5
	v_and_b32_e32 v61, 0xffff0000, v5
	global_load_dwordx4 v[2:5], v[0:1], off offset:1056
	v_mul_f32_e32 v46, v47, v47
	v_mul_f32_e32 v48, v49, v49
	v_pk_add_f32 v[6:7], v[8:9], v[6:7]
	v_pk_add_f32 v[8:9], v[42:43], v[44:45]
	v_mul_f32_e32 v50, v51, v51
	v_mul_f32_e32 v52, v53, v53
	v_pk_add_f32 v[6:7], v[8:9], v[6:7]
	v_pk_add_f32 v[8:9], v[46:47], v[48:49]
	v_mul_f32_e32 v54, v55, v55
	v_mul_f32_e32 v56, v57, v57
	v_pk_add_f32 v[6:7], v[8:9], v[6:7]
	v_pk_add_f32 v[8:9], v[50:51], v[52:53]
	v_mul_f32_e32 v58, v59, v59
	v_mul_f32_e32 v60, v61, v61
	v_pk_add_f32 v[6:7], v[8:9], v[6:7]
	v_pk_add_f32 v[8:9], v[54:55], v[56:57]
	s_waitcnt vmcnt(0) lgkmcnt(0)
	v_lshlrev_b32_e32 v63, 16, v2
	v_and_b32_e32 v105, 0xffff0000, v2
	v_mul_f32_e32 v62, v63, v63
	v_mul_f32_e32 v104, v105, v105
	v_lshlrev_b32_e32 v107, 16, v3
	v_and_b32_e32 v3, 0xffff0000, v3
	v_pk_add_f32 v[6:7], v[8:9], v[6:7]
	v_pk_add_f32 v[8:9], v[58:59], v[60:61]
	v_mul_f32_e32 v106, v107, v107
	v_mul_f32_e32 v2, v3, v3
	v_lshlrev_b32_e32 v109, 16, v4
	v_and_b32_e32 v111, 0xffff0000, v4
	v_pk_add_f32 v[6:7], v[8:9], v[6:7]
	v_pk_add_f32 v[8:9], v[62:63], v[104:105]
	v_mul_f32_e32 v108, v109, v109
	v_mul_f32_e32 v110, v111, v111
	v_pk_add_f32 v[6:7], v[8:9], v[6:7]
	v_pk_add_f32 v[2:3], v[106:107], v[2:3]
	s_nop 0
	v_pk_add_f32 v[2:3], v[2:3], v[6:7]
	v_pk_add_f32 v[6:7], v[108:109], v[110:111]
	s_nop 0
	v_pk_add_f32 v[2:3], v[6:7], v[2:3]
	v_lshlrev_b32_e32 v7, 16, v5
	v_and_b32_e32 v5, 0xffff0000, v5
	v_mul_f32_e32 v6, v7, v7
	v_mul_f32_e32 v4, v5, v5
	v_pk_add_f32 v[4:5], v[6:7], v[4:5]
	global_load_dwordx4 v[6:9], v[0:1], off offset:1072
	v_pk_add_f32 v[2:3], v[4:5], v[2:3]
	s_waitcnt vmcnt(0) lgkmcnt(0)
	v_lshlrev_b32_e32 v11, 16, v6
	v_and_b32_e32 v35, 0xffff0000, v6
	v_lshlrev_b32_e32 v37, 16, v7
	v_and_b32_e32 v39, 0xffff0000, v7
	v_lshlrev_b32_e32 v41, 16, v8
	v_and_b32_e32 v43, 0xffff0000, v8
	v_lshlrev_b32_e32 v45, 16, v9
	v_and_b32_e32 v47, 0xffff0000, v9
	global_load_dwordx4 v[6:9], v[0:1], off offset:1088
	v_mul_f32_e32 v10, v11, v11
	v_mul_f32_e32 v34, v35, v35
	v_mul_f32_e32 v36, v37, v37
	v_mul_f32_e32 v38, v39, v39
	v_pk_add_f32 v[4:5], v[10:11], v[34:35]
	v_mul_f32_e32 v40, v41, v41
	v_mul_f32_e32 v42, v43, v43
	v_pk_add_f32 v[2:3], v[4:5], v[2:3]
	v_pk_add_f32 v[4:5], v[36:37], v[38:39]
	v_mul_f32_e32 v44, v45, v45
	v_mul_f32_e32 v46, v47, v47
	v_pk_add_f32 v[2:3], v[4:5], v[2:3]
	v_pk_add_f32 v[4:5], v[40:41], v[42:43]
	s_waitcnt vmcnt(0) lgkmcnt(0)
	v_lshlrev_b32_e32 v49, 16, v6
	v_and_b32_e32 v51, 0xffff0000, v6
	v_lshlrev_b32_e32 v53, 16, v7
	v_and_b32_e32 v55, 0xffff0000, v7
	v_lshlrev_b32_e32 v57, 16, v8
	v_and_b32_e32 v59, 0xffff0000, v8
	v_lshlrev_b32_e32 v61, 16, v9
	v_and_b32_e32 v63, 0xffff0000, v9
	global_load_dwordx4 v[6:9], v[0:1], off offset:1104
	v_pk_add_f32 v[2:3], v[4:5], v[2:3]
	v_pk_add_f32 v[4:5], v[44:45], v[46:47]
	global_load_dwordx4 v[44:47], v[0:1], off offset:1120
	v_mul_f32_e32 v48, v49, v49
	v_mul_f32_e32 v50, v51, v51
	v_mul_f32_e32 v52, v53, v53
	v_mul_f32_e32 v54, v55, v55
	v_pk_add_f32 v[2:3], v[4:5], v[2:3]
	v_pk_add_f32 v[4:5], v[48:49], v[50:51]
	v_mul_f32_e32 v56, v57, v57
	v_mul_f32_e32 v58, v59, v59
	v_pk_add_f32 v[2:3], v[4:5], v[2:3]
	v_pk_add_f32 v[4:5], v[52:53], v[54:55]
	v_mul_f32_e32 v60, v61, v61
	v_mul_f32_e32 v62, v63, v63
	v_pk_add_f32 v[2:3], v[4:5], v[2:3]
	v_pk_add_f32 v[4:5], v[56:57], v[58:59]
	s_waitcnt vmcnt(0) lgkmcnt(0)
; DI float bflo(unsigned v) { return __uint_as_float(v << 16); }
; DI float bfhi(unsigned v) { return __uint_as_float(v & 0xffff0000u); }
;     ...
; #pragma unroll
;       for (int i = 0; i < 16; ++i) {
;         i32x4 v = *(const i32x4*)(p + i * 8);
; #pragma unroll
;         for (int e = 0; e < 4; ++e) {
;           float a = bflo((unsigned)v[e]), c = bfhi((unsigned)v[e]);
;           s1 += a + c;
;           s2 += a * a + c * c;
;         }
;       }
	v_lshlrev_b32_e32 v105, 16, v6
	v_and_b32_e32 v107, 0xffff0000, v6
	v_mul_f32_e32 v104, v105, v105
	v_mul_f32_e32 v106, v107, v107
	v_lshlrev_b32_e32 v109, 16, v7
	v_and_b32_e32 v7, 0xffff0000, v7
	v_pk_add_f32 v[2:3], v[4:5], v[2:3]
	v_pk_add_f32 v[4:5], v[60:61], v[62:63]
	v_mul_f32_e32 v108, v109, v109
	v_mul_f32_e32 v6, v7, v7
	v_pk_add_f32 v[2:3], v[4:5], v[2:3]
	v_pk_add_f32 v[4:5], v[104:105], v[106:107]
	v_lshlrev_b32_e32 v11, 16, v44
	v_pk_add_f32 v[2:3], v[4:5], v[2:3]
	v_pk_add_f32 v[4:5], v[108:109], v[6:7]
	v_and_b32_e32 v7, 0xffff0000, v8
	v_pk_add_f32 v[2:3], v[4:5], v[2:3]
	v_lshlrev_b32_e32 v5, 16, v8
	v_mul_f32_e32 v4, v5, v5
	v_mul_f32_e32 v6, v7, v7
	v_pk_add_f32 v[4:5], v[4:5], v[6:7]
	v_lshlrev_b32_e32 v7, 16, v9
	v_and_b32_e32 v9, 0xffff0000, v9
	v_mul_f32_e32 v6, v7, v7
	v_mul_f32_e32 v8, v9, v9
	v_and_b32_e32 v35, 0xffff0000, v44
	global_load_dwordx4 v[60:63], v[0:1], off offset:1136
	v_mul_f32_e32 v10, v11, v11
	v_mul_f32_e32 v34, v35, v35
	v_lshlrev_b32_e32 v37, 16, v45
	v_and_b32_e32 v39, 0xffff0000, v45
	v_pk_add_f32 v[2:3], v[4:5], v[2:3]
	v_pk_add_f32 v[4:5], v[6:7], v[8:9]
	v_mul_f32_e32 v36, v37, v37
	v_mul_f32_e32 v38, v39, v39
	v_pk_add_f32 v[2:3], v[4:5], v[2:3]
	v_pk_add_f32 v[4:5], v[10:11], v[34:35]
	global_load_dwordx4 v[104:107], v[0:1], off offset:1152
	v_pk_add_f32 v[2:3], v[4:5], v[2:3]
	v_pk_add_f32 v[4:5], v[36:37], v[38:39]
	global_load_dwordx4 v[36:39], v[0:1], off offset:1168
	v_lshlrev_b32_e32 v41, 16, v46
	v_and_b32_e32 v43, 0xffff0000, v46
	v_mul_f32_e32 v40, v41, v41
	v_mul_f32_e32 v42, v43, v43
	v_lshlrev_b32_e32 v45, 16, v47
	v_and_b32_e32 v47, 0xffff0000, v47
	v_mul_f32_e32 v44, v45, v45
	v_mul_f32_e32 v46, v47, v47
	v_pk_add_f32 v[2:3], v[4:5], v[2:3]
	v_pk_add_f32 v[4:5], v[40:41], v[42:43]
	s_waitcnt vmcnt(0) lgkmcnt(0)
	v_lshlrev_b32_e32 v49, 16, v60
	v_and_b32_e32 v51, 0xffff0000, v60
	v_mul_f32_e32 v48, v49, v49
	v_mul_f32_e32 v50, v51, v51
	v_lshlrev_b32_e32 v53, 16, v61
	v_and_b32_e32 v55, 0xffff0000, v61
	v_pk_add_f32 v[2:3], v[4:5], v[2:3]
	v_pk_add_f32 v[4:5], v[44:45], v[46:47]
	v_mul_f32_e32 v52, v53, v53
	v_mul_f32_e32 v54, v55, v55
	v_pk_add_f32 v[2:3], v[4:5], v[2:3]
	v_pk_add_f32 v[4:5], v[48:49], v[50:51]
	v_lshlrev_b32_e32 v57, 16, v62
	v_pk_add_f32 v[2:3], v[4:5], v[2:3]
	v_pk_add_f32 v[4:5], v[52:53], v[54:55]
	v_lshlrev_b32_e32 v41, 16, v36
	v_and_b32_e32 v43, 0xffff0000, v36
	v_lshlrev_b32_e32 v45, 16, v37
	v_and_b32_e32 v47, 0xffff0000, v37
	v_lshlrev_b32_e32 v49, 16, v38
	v_and_b32_e32 v51, 0xffff0000, v38
	v_lshlrev_b32_e32 v53, 16, v39
	v_and_b32_e32 v55, 0xffff0000, v39
	global_load_dwordx4 v[36:39], v[0:1], off offset:1184
	v_and_b32_e32 v59, 0xffff0000, v62
	v_mul_f32_e32 v56, v57, v57
	v_mul_f32_e32 v58, v59, v59
	v_lshlrev_b32_e32 v61, 16, v63
	v_and_b32_e32 v63, 0xffff0000, v63
	v_mul_f32_e32 v60, v61, v61
	v_mul_f32_e32 v62, v63, v63
	v_lshlrev_b32_e32 v109, 16, v104
	v_and_b32_e32 v111, 0xffff0000, v104
	v_pk_add_f32 v[2:3], v[4:5], v[2:3]
	v_pk_add_f32 v[4:5], v[56:57], v[58:59]
	v_mul_f32_e32 v108, v109, v109
	v_mul_f32_e32 v110, v111, v111
	v_pk_add_f32 v[2:3], v[4:5], v[2:3]
	v_pk_add_f32 v[4:5], v[60:61], v[62:63]
	v_and_b32_e32 v7, 0xffff0000, v105
	v_pk_add_f32 v[2:3], v[4:5], v[2:3]
	v_pk_add_f32 v[4:5], v[108:109], v[110:111]
	v_mul_f32_e32 v6, v7, v7
	v_pk_add_f32 v[2:3], v[4:5], v[2:3]
	v_lshlrev_b32_e32 v5, 16, v105
	v_mul_f32_e32 v4, v5, v5
	v_pk_add_f32 v[4:5], v[4:5], v[6:7]
	v_lshlrev_b32_e32 v7, 16, v106
	v_and_b32_e32 v9, 0xffff0000, v106
	v_mul_f32_e32 v6, v7, v7
	v_mul_f32_e32 v8, v9, v9
	v_lshlrev_b32_e32 v11, 16, v107
	v_and_b32_e32 v35, 0xffff0000, v107
	v_mul_f32_e32 v10, v11, v11
	v_mul_f32_e32 v34, v35, v35
	v_pk_add_f32 v[2:3], v[4:5], v[2:3]
	v_pk_add_f32 v[4:5], v[6:7], v[8:9]
	v_mul_f32_e32 v40, v41, v41
	v_mul_f32_e32 v42, v43, v43
	v_pk_add_f32 v[2:3], v[4:5], v[2:3]
	v_pk_add_f32 v[4:5], v[10:11], v[34:35]
	v_mul_f32_e32 v44, v45, v45
	v_pk_add_f32 v[2:3], v[4:5], v[2:3]
	v_pk_add_f32 v[4:5], v[40:41], v[42:43]
	global_load_dwordx4 v[40:43], v[0:1], off offset:1216
	v_mul_f32_e32 v46, v47, v47
	v_mul_f32_e32 v48, v49, v49
	v_mul_f32_e32 v50, v51, v51
	v_pk_add_f32 v[2:3], v[4:5], v[2:3]
	v_pk_add_f32 v[4:5], v[44:45], v[46:47]
	v_mul_f32_e32 v52, v53, v53
	v_mul_f32_e32 v54, v55, v55
	v_pk_add_f32 v[2:3], v[4:5], v[2:3]
	v_pk_add_f32 v[4:5], v[48:49], v[50:51]
	s_waitcnt vmcnt(0) lgkmcnt(0)
	v_lshlrev_b32_e32 v57, 16, v36
	v_and_b32_e32 v59, 0xffff0000, v36
	v_mul_f32_e32 v56, v57, v57
	v_mul_f32_e32 v58, v59, v59
	v_lshlrev_b32_e32 v61, 16, v37
	v_and_b32_e32 v37, 0xffff0000, v37
	v_pk_add_f32 v[2:3], v[4:5], v[2:3]
	v_pk_add_f32 v[4:5], v[52:53], v[54:55]
	v_mul_f32_e32 v60, v61, v61
	v_mul_f32_e32 v36, v37, v37
	v_lshlrev_b32_e32 v63, 16, v38
	v_and_b32_e32 v105, 0xffff0000, v38
	v_pk_add_f32 v[2:3], v[4:5], v[2:3]
	v_pk_add_f32 v[4:5], v[56:57], v[58:59]
	v_mul_f32_e32 v62, v63, v63
	v_mul_f32_e32 v104, v105, v105
	v_lshlrev_b32_e32 v107, 16, v39
	v_and_b32_e32 v39, 0xffff0000, v39
	v_pk_add_f32 v[2:3], v[4:5], v[2:3]
	v_pk_add_f32 v[4:5], v[60:61], v[36:37]
	v_mul_f32_e32 v106, v107, v107
	v_mul_f32_e32 v38, v39, v39
	v_pk_add_f32 v[2:3], v[4:5], v[2:3]
	v_pk_add_f32 v[4:5], v[62:63], v[104:105]
	v_lshlrev_b32_e32 v45, 16, v40
	v_pk_add_f32 v[2:3], v[4:5], v[2:3]
	v_pk_add_f32 v[4:5], v[106:107], v[38:39]
	global_load_dwordx4 v[36:39], v[0:1], off offset:1200
	v_and_b32_e32 v47, 0xffff0000, v40
	v_lshlrev_b32_e32 v49, 16, v41
	v_and_b32_e32 v51, 0xffff0000, v41
	v_lshlrev_b32_e32 v53, 16, v42
	v_and_b32_e32 v55, 0xffff0000, v42
	v_lshlrev_b32_e32 v57, 16, v43
	v_and_b32_e32 v59, 0xffff0000, v43
	global_load_dwordx4 v[40:43], v[0:1], off offset:1232
	v_pk_add_f32 v[2:3], v[4:5], v[2:3]
	v_mul_f32_e32 v44, v45, v45
	v_mul_f32_e32 v46, v47, v47
	v_mul_f32_e32 v48, v49, v49
	v_mul_f32_e32 v50, v51, v51
	v_mul_f32_e32 v52, v53, v53
	v_mul_f32_e32 v54, v55, v55
	v_mul_f32_e32 v56, v57, v57
	v_mul_f32_e32 v58, v59, v59
	s_waitcnt vmcnt(0) lgkmcnt(0)
; DI float bflo(unsigned v) { return __uint_as_float(v << 16); }
; DI float bfhi(unsigned v) { return __uint_as_float(v & 0xffff0000u); }
;     ...
; #pragma unroll
;       for (int i = 0; i < 16; ++i) {
;         i32x4 v = *(const i32x4*)(p + i * 8);
; #pragma unroll
;         for (int e = 0; e < 4; ++e) {
;           float a = bflo((unsigned)v[e]), c = bfhi((unsigned)v[e]);
;           s1 += a + c;
;           s2 += a * a + c * c;
;         }
;       }
;       s1 += __shfl_xor(s1, 1); s2 += __shfl_xor(s2, 1);
;       s1 += __shfl_xor(s1, 2); s2 += __shfl_xor(s2, 2);
;       const float mean = s1 * (1.f / 512.f);
;       const float var = fmaxf(s2 * (1.f / 512.f) - mean * mean, 0.f);
;       if (qu == 0) { st[tok] = mean; st[128 + tok] = rsqrtf(var + EPS); }
	v_lshlrev_b32_e32 v5, 16, v36
	v_and_b32_e32 v7, 0xffff0000, v36
	v_mul_f32_e32 v4, v5, v5
	v_mul_f32_e32 v6, v7, v7
	v_pk_add_f32 v[4:5], v[4:5], v[6:7]
	v_lshlrev_b32_e32 v7, 16, v37
	v_and_b32_e32 v9, 0xffff0000, v37
	v_mul_f32_e32 v6, v7, v7
	v_mul_f32_e32 v8, v9, v9
	v_lshlrev_b32_e32 v11, 16, v38
	v_and_b32_e32 v35, 0xffff0000, v38
	v_mul_f32_e32 v10, v11, v11
	v_mul_f32_e32 v34, v35, v35
	v_lshlrev_b32_e32 v37, 16, v39
	v_and_b32_e32 v39, 0xffff0000, v39
	v_pk_add_f32 v[2:3], v[4:5], v[2:3]
	v_pk_add_f32 v[4:5], v[6:7], v[8:9]
	v_mul_f32_e32 v36, v37, v37
	v_mul_f32_e32 v38, v39, v39
	v_pk_add_f32 v[2:3], v[4:5], v[2:3]
	v_pk_add_f32 v[4:5], v[10:11], v[34:35]
	v_lshlrev_b32_e32 v61, 16, v40
	v_pk_add_f32 v[2:3], v[4:5], v[2:3]
	v_pk_add_f32 v[4:5], v[36:37], v[38:39]
	v_and_b32_e32 v63, 0xffff0000, v40
	v_pk_add_f32 v[2:3], v[4:5], v[2:3]
	v_pk_add_f32 v[4:5], v[44:45], v[46:47]
	v_mul_f32_e32 v60, v61, v61
	v_pk_add_f32 v[2:3], v[4:5], v[2:3]
	v_pk_add_f32 v[4:5], v[48:49], v[50:51]
	v_mul_f32_e32 v62, v63, v63
	v_pk_add_f32 v[2:3], v[4:5], v[2:3]
	v_pk_add_f32 v[4:5], v[52:53], v[54:55]
	v_lshlrev_b32_e32 v105, 16, v41
	v_and_b32_e32 v41, 0xffff0000, v41
	v_pk_add_f32 v[2:3], v[4:5], v[2:3]
	v_pk_add_f32 v[4:5], v[56:57], v[58:59]
	v_mul_f32_e32 v104, v105, v105
	v_mul_f32_e32 v40, v41, v41
	v_lshlrev_b32_e32 v107, 16, v42
	v_and_b32_e32 v109, 0xffff0000, v42
	v_pk_add_f32 v[2:3], v[4:5], v[2:3]
	v_pk_add_f32 v[4:5], v[60:61], v[62:63]
	v_mul_f32_e32 v106, v107, v107
	v_mul_f32_e32 v108, v109, v109
	v_pk_add_f32 v[2:3], v[4:5], v[2:3]
	v_pk_add_f32 v[4:5], v[104:105], v[40:41]
	global_load_dwordx4 v[8:11], v[0:1], off offset:1248
	v_pk_add_f32 v[2:3], v[4:5], v[2:3]
	v_pk_add_f32 v[4:5], v[106:107], v[108:109]
	v_and_b32_e32 v7, 0xffff0000, v43
	v_pk_add_f32 v[4:5], v[4:5], v[2:3]
	v_lshlrev_b32_e32 v3, 16, v43
	v_mul_f32_e32 v2, v3, v3
	v_mul_f32_e32 v6, v7, v7
	v_pk_add_f32 v[6:7], v[2:3], v[6:7]
	global_load_dwordx4 v[0:3], v[0:1], off offset:1264
	v_pk_add_f32 v[4:5], v[6:7], v[4:5]
	s_waitcnt vmcnt(0) lgkmcnt(0)
	v_lshlrev_b32_e32 v43, 16, v8
	v_and_b32_e32 v45, 0xffff0000, v8
	v_mul_f32_e32 v42, v43, v43
	v_mul_f32_e32 v44, v45, v45
	v_lshlrev_b32_e32 v39, 16, v9
	v_and_b32_e32 v41, 0xffff0000, v9
	v_mul_f32_e32 v38, v39, v39
	v_mul_f32_e32 v40, v41, v41
	v_lshlrev_b32_e32 v35, 16, v10
	v_and_b32_e32 v37, 0xffff0000, v10
	v_pk_add_f32 v[6:7], v[42:43], v[44:45]
	v_mul_f32_e32 v34, v35, v35
	v_mul_f32_e32 v36, v37, v37
	v_lshlrev_b32_e32 v9, 16, v11
	v_and_b32_e32 v11, 0xffff0000, v11
	v_pk_add_f32 v[4:5], v[6:7], v[4:5]
	v_pk_add_f32 v[6:7], v[38:39], v[40:41]
	v_mul_f32_e32 v8, v9, v9
	v_mul_f32_e32 v10, v11, v11
	v_lshlrev_b32_e32 v47, 16, v0
	v_and_b32_e32 v49, 0xffff0000, v0
	v_pk_add_f32 v[4:5], v[6:7], v[4:5]
	v_pk_add_f32 v[6:7], v[34:35], v[36:37]
	v_mul_f32_e32 v46, v47, v47
	v_mul_f32_e32 v48, v49, v49
	v_lshlrev_b32_e32 v51, 16, v1
	v_and_b32_e32 v1, 0xffff0000, v1
	v_pk_add_f32 v[4:5], v[6:7], v[4:5]
	v_pk_add_f32 v[6:7], v[8:9], v[10:11]
	v_mul_f32_e32 v50, v51, v51
	v_mul_f32_e32 v0, v1, v1
	v_lshlrev_b32_e32 v53, 16, v2
	v_and_b32_e32 v55, 0xffff0000, v2
	v_pk_add_f32 v[4:5], v[6:7], v[4:5]
	v_pk_add_f32 v[6:7], v[46:47], v[48:49]
	v_mul_f32_e32 v52, v53, v53
	v_mul_f32_e32 v54, v55, v55
	v_lshlrev_b32_e32 v57, 16, v3
	v_and_b32_e32 v3, 0xffff0000, v3
	v_pk_add_f32 v[4:5], v[6:7], v[4:5]
	v_pk_add_f32 v[0:1], v[50:51], v[0:1]
	v_mul_f32_e32 v56, v57, v57
	v_mul_f32_e32 v2, v3, v3
	v_pk_add_f32 v[0:1], v[0:1], v[4:5]
	v_pk_add_f32 v[4:5], v[52:53], v[54:55]
	v_pk_add_f32 v[2:3], v[56:57], v[2:3]
	v_pk_add_f32 v[0:1], v[4:5], v[0:1]
	s_nop 0
	v_pk_add_f32 v[0:1], v[2:3], v[0:1]
	ds_bpermute_b32 v3, v216, v1
	ds_bpermute_b32 v2, v216, v0
	s_waitcnt lgkmcnt(0)
	v_pk_add_f32 v[0:1], v[0:1], v[2:3]
	ds_bpermute_b32 v3, v215, v1
	ds_bpermute_b32 v2, v215, v0
	s_and_saveexec_b64 s[0:1], s[8:9]
	s_cbranch_execz .LBB0_780
	s_waitcnt lgkmcnt(0)
	v_pk_add_f32 v[0:1], v[0:1], v[2:3]
	s_mov_b32 s16, 0x3b000000
	v_pk_mul_f32 v[0:1], v[0:1], s[16:17] op_sel_hi:[1,0]
	s_nop 0
	v_fma_f32 v0, -v1, v1, v0
	v_max_f32_e32 v0, 0, v0
	v_add_f32_e32 v0, 0x358637bd, v0
	v_mul_f32_e32 v2, 0x4b800000, v0
	v_cmp_gt_f32_e32 vcc, s33, v0
	s_nop 1
	v_cndmask_b32_e32 v0, v0, v2, vcc
	v_rsq_f32_e32 v0, v0
	s_nop 0
	v_mul_f32_e32 v2, 0x45800000, v0
	v_cndmask_b32_e32 v0, v0, v2, vcc
	ds_write2st64_b32 v64, v1, v0 offset0:136 offset1:138

; DI u16 f2bf(float a) { return (u16)(pack2(a, 0.f) & 0xffffu); }
; DI float bflo(unsigned v) { return __uint_as_float(v << 16); }
; DI float bfhi(unsigned v) { return __uint_as_float(v & 0xffff0000u); }
;     ...
;     for (int g = 0; g < 4; ++g) {
;       {
;         const int s = tid >> 2, cq = tid & 3;
;         const float mean = st[s], rstd = st[128 + s];
;         const u16* p = projA + (size_t)(T0 + s) * 1024 + 512 + g * 128 + cq * 32;
; #pragma unroll
;         for (int i = 0; i < 4; ++i) {
;           i32x4 v = *(const i32x4*)(p + i * 8);
; #pragma unroll
;           for (int e = 0; e < 4; ++e) {
;             const int c = cq * 32 + i * 8 + 2 * e;
;             float a = (bflo((unsigned)v[e]) - mean) * rstd * lng[g * 128 + c] + lnb[g * 128 + c];
;             float d = (bfhi((unsigned)v[e]) - mean) * rstd * lng[g * 128 + c + 1] + lnb[g * 128 + c + 1];
;             vT[c * 136 + s] = f2bf(a);
;             vT[(c + 1) * 136 + s] = f2bf(d);
;           }
;         }
;       }
.LBB0_781:
	v_lshl_add_u64 v[2:3], s[18:19], 0, v[42:43]
	v_add_co_u32_e32 v10, vcc, 0x19000000, v2
	ds_read2st64_b32 v[0:1], v64 offset0:136 offset1:138
	s_nop 0
	v_addc_co_u32_e32 v11, vcc, 0, v3, vcc
	global_load_dwordx4 v[2:5], v[10:11], off offset:1024
	v_lshl_add_u64 v[62:63], v[24:25], 0, s[16:17]
	v_lshl_add_u64 v[124:125], v[26:27], 0, s[16:17]
	v_ashrrev_i32_e32 v53, 31, v52
	s_add_u32 s16, s16, 0x200
	s_addc_u32 s17, s17, 0
	s_waitcnt vmcnt(0) lgkmcnt(0)
	v_lshlrev_b32_e32 v6, 16, v2
	v_sub_f32_e32 v6, v6, v0
	v_mul_f32_e32 v17, v1, v6
	global_load_dwordx4 v[6:9], v[62:63], off offset:48
	global_load_dwordx4 v[54:57], v[62:63], off offset:32
	global_load_dwordx4 v[58:61], v[62:63], off offset:16
	global_load_dwordx4 v[104:107], v[62:63], off
	global_load_dwordx4 v[108:111], v[124:125], off offset:48
	global_load_dwordx4 v[112:115], v[124:125], off offset:32
	global_load_dwordx4 v[116:119], v[124:125], off offset:16
	global_load_dwordx4 v[120:123], v[124:125], off
	v_and_b32_e32 v2, 0xffff0000, v2
	v_sub_f32_e32 v2, v2, v0
	v_mul_f32_e32 v2, v1, v2
	s_waitcnt vmcnt(0)
	v_fma_f32 v17, v104, v17, v120
	v_fma_f32 v2, v105, v2, v121
	v_cvt_pk_bf16_f32 v17, v17, s0
	v_cvt_pk_bf16_f32 v2, v2, s0
	ds_write_b16 v66, v17
	ds_write_b16 v67, v2 offset:272
	v_lshlrev_b32_e32 v2, 16, v3
	v_sub_f32_e32 v2, v2, v0
	v_and_b32_e32 v3, 0xffff0000, v3
	v_mul_f32_e32 v2, v1, v2
	v_sub_f32_e32 v3, v3, v0
	v_fma_f32 v2, v2, v106, v122
	v_mul_f32_e32 v3, v1, v3
	v_fmac_f32_e32 v123, v3, v107
	v_cvt_pk_bf16_f32 v2, v2, s0
	ds_write_b16 v68, v2
	v_cvt_pk_bf16_f32 v2, v123, s0
	ds_write_b16 v69, v2 offset:272
	v_lshlrev_b32_e32 v2, 16, v4
	v_sub_f32_e32 v2, v2, v0
	v_and_b32_e32 v3, 0xffff0000, v4
	v_mul_f32_e32 v2, v1, v2
	v_sub_f32_e32 v3, v3, v0
	v_fma_f32 v2, v2, v58, v116
	v_mul_f32_e32 v3, v1, v3
	v_fma_f32 v3, v3, v59, v117
	v_cvt_pk_bf16_f32 v2, v2, s0
	ds_write_b16 v70, v2
	v_cvt_pk_bf16_f32 v2, v3, s0
	ds_write_b16 v71, v2 offset:272
	v_lshlrev_b32_e32 v2, 16, v5
	v_sub_f32_e32 v2, v2, v0
	v_and_b32_e32 v3, 0xffff0000, v5
	v_mul_f32_e32 v2, v1, v2
	v_sub_f32_e32 v3, v3, v0
	v_fma_f32 v2, v2, v60, v118
	v_mul_f32_e32 v3, v1, v3
	v_fmac_f32_e32 v119, v3, v61
	v_cvt_pk_bf16_f32 v2, v2, s0
	ds_write_b16 v72, v2
	v_cvt_pk_bf16_f32 v2, v119, s0
	ds_write_b16 v73, v2 offset:272
	global_load_dwordx4 v[2:5], v[10:11], off offset:1040
	s_waitcnt vmcnt(0) lgkmcnt(0)
	v_lshlrev_b32_e32 v17, 16, v2
	v_and_b32_e32 v2, 0xffff0000, v2
	v_sub_f32_e32 v17, v17, v0
	v_sub_f32_e32 v2, v2, v0
	v_mul_f32_e32 v17, v1, v17
	v_mul_f32_e32 v2, v1, v2
	v_fma_f32 v17, v54, v17, v112
	v_fma_f32 v2, v55, v2, v113
	v_cvt_pk_bf16_f32 v17, v17, s0
	v_cvt_pk_bf16_f32 v2, v2, s0
	ds_write_b16 v74, v17
	ds_write_b16 v75, v2 offset:272
	v_lshlrev_b32_e32 v2, 16, v3
	v_sub_f32_e32 v2, v2, v0
	v_and_b32_e32 v3, 0xffff0000, v3
	v_mul_f32_e32 v2, v1, v2
	v_sub_f32_e32 v3, v3, v0
	v_fma_f32 v2, v2, v56, v114
	v_mul_f32_e32 v3, v1, v3
	v_fmac_f32_e32 v115, v3, v57
	v_cvt_pk_bf16_f32 v2, v2, s0
	ds_write_b16 v76, v2
	v_cvt_pk_bf16_f32 v2, v115, s0
	ds_write_b16 v77, v2 offset:272
	v_lshlrev_b32_e32 v2, 16, v4
	v_sub_f32_e32 v2, v2, v0
	v_and_b32_e32 v3, 0xffff0000, v4
	v_mul_f32_e32 v2, v1, v2
	v_sub_f32_e32 v3, v3, v0
	v_fma_f32 v2, v2, v6, v108
	v_mul_f32_e32 v3, v1, v3
	v_fma_f32 v3, v3, v7, v109
	v_cvt_pk_bf16_f32 v2, v2, s0
	ds_write_b16 v78, v2
	v_cvt_pk_bf16_f32 v2, v3, s0
	ds_write_b16 v79, v2 offset:272
	v_lshlrev_b32_e32 v2, 16, v5
	v_sub_f32_e32 v2, v2, v0
	v_and_b32_e32 v3, 0xffff0000, v5
	v_mul_f32_e32 v2, v1, v2
	v_sub_f32_e32 v3, v3, v0
	v_fma_f32 v2, v2, v8, v110
	v_mul_f32_e32 v3, v1, v3
	v_fmac_f32_e32 v111, v3, v9
	v_cvt_pk_bf16_f32 v2, v2, s0
	ds_write_b16 v80, v2
	v_cvt_pk_bf16_f32 v2, v111, s0
	ds_write_b16 v81, v2 offset:272
	global_load_dwordx4 v[2:5], v[10:11], off offset:1056
	s_waitcnt vmcnt(0) lgkmcnt(0)
	v_lshlrev_b32_e32 v6, 16, v2
	v_sub_f32_e32 v6, v6, v0
	v_mul_f32_e32 v17, v1, v6
	global_load_dwordx4 v[6:9], v[62:63], off offset:112
	global_load_dwordx4 v[54:57], v[62:63], off offset:96
	global_load_dwordx4 v[58:61], v[62:63], off offset:80
	global_load_dwordx4 v[104:107], v[62:63], off offset:64
	global_load_dwordx4 v[108:111], v[124:125], off offset:112
	global_load_dwordx4 v[112:115], v[124:125], off offset:96
	global_load_dwordx4 v[116:119], v[124:125], off offset:80
	global_load_dwordx4 v[120:123], v[124:125], off offset:64
	v_and_b32_e32 v2, 0xffff0000, v2
	v_sub_f32_e32 v2, v2, v0
	v_mul_f32_e32 v2, v1, v2
	s_waitcnt vmcnt(0)
	v_fma_f32 v17, v104, v17, v120
	v_fma_f32 v2, v105, v2, v121
	v_cvt_pk_bf16_f32 v17, v17, s0
	v_cvt_pk_bf16_f32 v2, v2, s0
	ds_write_b16 v82, v17
	ds_write_b16 v83, v2 offset:272
	v_lshlrev_b32_e32 v2, 16, v3
	v_sub_f32_e32 v2, v2, v0
	v_and_b32_e32 v3, 0xffff0000, v3
	v_mul_f32_e32 v2, v1, v2
	v_sub_f32_e32 v3, v3, v0
	v_fma_f32 v2, v2, v106, v122
	v_mul_f32_e32 v3, v1, v3
	v_fmac_f32_e32 v123, v3, v107
	v_cvt_pk_bf16_f32 v2, v2, s0
	ds_write_b16 v84, v2
	v_cvt_pk_bf16_f32 v2, v123, s0
	ds_write_b16 v85, v2 offset:272
	v_lshlrev_b32_e32 v2, 16, v4
	v_sub_f32_e32 v2, v2, v0
	v_and_b32_e32 v3, 0xffff0000, v4
	v_mul_f32_e32 v2, v1, v2
	v_sub_f32_e32 v3, v3, v0
	v_fma_f32 v2, v2, v58, v116
	v_mul_f32_e32 v3, v1, v3
	v_fma_f32 v3, v3, v59, v117
	v_cvt_pk_bf16_f32 v2, v2, s0
	ds_write_b16 v86, v2
	v_cvt_pk_bf16_f32 v2, v3, s0
	ds_write_b16 v87, v2 offset:272
	v_lshlrev_b32_e32 v2, 16, v5
	v_sub_f32_e32 v2, v2, v0
	v_and_b32_e32 v3, 0xffff0000, v5
	v_mul_f32_e32 v2, v1, v2
	v_sub_f32_e32 v3, v3, v0
	v_fma_f32 v2, v2, v60, v118
	v_mul_f32_e32 v3, v1, v3
	v_fmac_f32_e32 v119, v3, v61
	v_cvt_pk_bf16_f32 v2, v2, s0
	ds_write_b16 v88, v2
	v_cvt_pk_bf16_f32 v2, v119, s0
	ds_write_b16 v89, v2 offset:272
	global_load_dwordx4 v[2:5], v[10:11], off offset:1072
	s_waitcnt vmcnt(0) lgkmcnt(0)
; #define MFMA16(a, b, c) __builtin_amdgcn_mfma_f32_16x16x32_bf16((a), (b), (c), 0, 0, 0)
; DI u16 f2bf(float a) { return (u16)(pack2(a, 0.f) & 0xffffu); }
; DI float bflo(unsigned v) { return __uint_as_float(v << 16); }
; DI float bfhi(unsigned v) { return __uint_as_float(v & 0xffff0000u); }
;     ...
; #pragma unroll
;           for (int e = 0; e < 4; ++e) {
;             const int c = cq * 32 + i * 8 + 2 * e;
;             float a = (bflo((unsigned)v[e]) - mean) * rstd * lng[g * 128 + c] + lnb[g * 128 + c];
;             float d = (bfhi((unsigned)v[e]) - mean) * rstd * lng[g * 128 + c + 1] + lnb[g * 128 + c + 1];
;             vT[c * 136 + s] = f2bf(a);
;             vT[(c + 1) * 136 + s] = f2bf(d);
;           }
;         }
;       }
;       __syncthreads();
;       f32x4 acc[8];
; #pragma unroll
;       for (int i = 0; i < 8; ++i) acc[i] = f32x4{0.f, 0.f, 0.f, 0.f};
;       const u16* wp = Wsgu + (size_t)(g * 128 + wid * 16 + fr) * 128 + fq * 8;
; #pragma unroll
;       for (int ks = 0; ks < 4; ++ks) {
;         bf16x8 af = *(const bf16x8*)(wp + ks * 32);
; #pragma unroll
;         for (int ns = 0; ns < 8; ++ns) {
;           bf16x8 bfr = *(const bf16x8*)(vT + (ns * 16 + fr) * 136 + ks * 32 + fq * 8);
;           acc[ns] = MFMA16(bfr, af, acc[ns]);
;         }
;       }
	v_lshlrev_b32_e32 v10, 16, v2
	v_and_b32_e32 v2, 0xffff0000, v2
	v_sub_f32_e32 v10, v10, v0
	v_sub_f32_e32 v2, v2, v0
	v_mul_f32_e32 v10, v1, v10
	v_mul_f32_e32 v2, v1, v2
	v_fma_f32 v10, v54, v10, v112
	v_fma_f32 v2, v55, v2, v113
	v_cvt_pk_bf16_f32 v10, v10, s0
	v_cvt_pk_bf16_f32 v2, v2, s0
	ds_write_b16 v90, v10
	ds_write_b16 v91, v2 offset:272
	v_lshlrev_b32_e32 v2, 16, v3
	v_sub_f32_e32 v2, v2, v0
	v_and_b32_e32 v3, 0xffff0000, v3
	v_mul_f32_e32 v2, v1, v2
	v_sub_f32_e32 v3, v3, v0
	v_fma_f32 v2, v2, v56, v114
	v_mul_f32_e32 v3, v1, v3
	v_fmac_f32_e32 v115, v3, v57
	v_cvt_pk_bf16_f32 v2, v2, s0
	ds_write_b16 v92, v2
	v_cvt_pk_bf16_f32 v2, v115, s0
	ds_write_b16 v93, v2 offset:272
	v_lshlrev_b32_e32 v2, 16, v4
	v_sub_f32_e32 v2, v2, v0
	v_and_b32_e32 v3, 0xffff0000, v4
	v_mul_f32_e32 v2, v1, v2
	v_sub_f32_e32 v3, v3, v0
	v_fma_f32 v2, v2, v6, v108
	v_mul_f32_e32 v3, v1, v3
	v_fma_f32 v3, v3, v7, v109
	v_cvt_pk_bf16_f32 v2, v2, s0
	ds_write_b16 v94, v2
	v_cvt_pk_bf16_f32 v2, v3, s0
	ds_write_b16 v95, v2 offset:272
	v_lshlrev_b32_e32 v2, 16, v5
	v_sub_f32_e32 v2, v2, v0
	v_and_b32_e32 v3, 0xffff0000, v5
	v_mul_f32_e32 v2, v1, v2
	v_sub_f32_e32 v0, v3, v0
	v_fma_f32 v2, v2, v8, v110
	v_mul_f32_e32 v0, v1, v0
	v_fmac_f32_e32 v111, v0, v9
	v_cvt_pk_bf16_f32 v0, v2, s0
	ds_write_b16 v96, v0
	v_cvt_pk_bf16_f32 v0, v111, s0
	ds_write_b16 v97, v0 offset:272
	v_lshlrev_b64 v[0:1], 8, v[52:53]
	v_lshl_add_u64 v[0:1], v[12:13], 0, v[0:1]
	s_waitcnt lgkmcnt(0)
	s_barrier
	global_load_dwordx4 v[2:5], v[0:1], off
	ds_read_b128 v[6:9], v98
	ds_read_b128 v[54:57], v98 offset:4352
	ds_read_b128 v[58:61], v98 offset:8704
	ds_read_b128 v[104:107], v98 offset:13056
	ds_read_b128 v[108:111], v98 offset:17408
	ds_read_b128 v[112:115], v98 offset:21760
	ds_read_b128 v[116:119], v98 offset:26112
	ds_read_b128 v[120:123], v98 offset:30464
	s_waitcnt vmcnt(0) lgkmcnt(0)
	v_mfma_f32_16x16x32_bf16 v[6:9], v[6:9], v[2:5], 0
	ds_read_b128 v[124:127], v98 offset:64
	v_mfma_f32_16x16x32_bf16 v[54:57], v[54:57], v[2:5], 0
	v_mfma_f32_16x16x32_bf16 v[58:61], v[58:61], v[2:5], 0
	v_mfma_f32_16x16x32_bf16 v[104:107], v[104:107], v[2:5], 0
	v_mfma_f32_16x16x32_bf16 v[108:111], v[108:111], v[2:5], 0
	v_mfma_f32_16x16x32_bf16 v[112:115], v[112:115], v[2:5], 0
	v_mfma_f32_16x16x32_bf16 v[116:119], v[116:119], v[2:5], 0
	v_mfma_f32_16x16x32_bf16 v[2:5], v[120:123], v[2:5], 0
	global_load_dwordx4 v[120:123], v[0:1], off offset:64
	s_waitcnt vmcnt(0) lgkmcnt(0)
	v_mfma_f32_16x16x32_bf16 v[6:9], v[124:127], v[120:123], v[6:9]
	ds_read_b128 v[124:127], v98 offset:4416
	s_waitcnt lgkmcnt(0)
	v_mfma_f32_16x16x32_bf16 v[54:57], v[124:127], v[120:123], v[54:57]
	ds_read_b128 v[124:127], v98 offset:8768
	s_waitcnt lgkmcnt(0)
	v_mfma_f32_16x16x32_bf16 v[58:61], v[124:127], v[120:123], v[58:61]
	ds_read_b128 v[124:127], v98 offset:13120
	s_waitcnt lgkmcnt(0)
	v_mfma_f32_16x16x32_bf16 v[104:107], v[124:127], v[120:123], v[104:107]
	ds_read_b128 v[124:127], v98 offset:17472
	s_waitcnt lgkmcnt(0)
	v_mfma_f32_16x16x32_bf16 v[108:111], v[124:127], v[120:123], v[108:111]
	ds_read_b128 v[124:127], v98 offset:21824
	s_waitcnt lgkmcnt(0)
	v_mfma_f32_16x16x32_bf16 v[112:115], v[124:127], v[120:123], v[112:115]
	ds_read_b128 v[124:127], v98 offset:26176
	s_waitcnt lgkmcnt(0)
	v_mfma_f32_16x16x32_bf16 v[116:119], v[124:127], v[120:123], v[116:119]
	ds_read_b128 v[124:127], v98 offset:30528
	s_waitcnt lgkmcnt(0)
	v_mfma_f32_16x16x32_bf16 v[2:5], v[124:127], v[120:123], v[2:5]
	global_load_dwordx4 v[120:123], v[0:1], off offset:128
	ds_read_b128 v[124:127], v98 offset:128
	s_waitcnt vmcnt(0) lgkmcnt(0)
	v_mfma_f32_16x16x32_bf16 v[6:9], v[124:127], v[120:123], v[6:9]
	ds_read_b128 v[124:127], v98 offset:4480
	s_waitcnt lgkmcnt(0)
	v_mfma_f32_16x16x32_bf16 v[54:57], v[124:127], v[120:123], v[54:57]
	ds_read_b128 v[124:127], v98 offset:8832
	s_waitcnt lgkmcnt(0)
	v_mfma_f32_16x16x32_bf16 v[58:61], v[124:127], v[120:123], v[58:61]
	ds_read_b128 v[124:127], v98 offset:13184
	s_waitcnt lgkmcnt(0)
	v_mfma_f32_16x16x32_bf16 v[104:107], v[124:127], v[120:123], v[104:107]
	ds_read_b128 v[124:127], v98 offset:17536
	s_waitcnt lgkmcnt(0)
	v_mfma_f32_16x16x32_bf16 v[108:111], v[124:127], v[120:123], v[108:111]
	ds_read_b128 v[124:127], v98 offset:21888
	s_waitcnt lgkmcnt(0)
	v_mfma_f32_16x16x32_bf16 v[112:115], v[124:127], v[120:123], v[112:115]
	ds_read_b128 v[124:127], v98 offset:26240
	s_waitcnt lgkmcnt(0)
	v_mfma_f32_16x16x32_bf16 v[116:119], v[124:127], v[120:123], v[116:119]
	ds_read_b128 v[124:127], v98 offset:30592
	s_waitcnt lgkmcnt(0)
	v_mfma_f32_16x16x32_bf16 v[2:5], v[124:127], v[120:123], v[2:5]
	global_load_dwordx4 v[120:123], v[0:1], off offset:192
	ds_read_b128 v[124:127], v98 offset:192
	s_waitcnt vmcnt(0) lgkmcnt(0)
	v_mfma_f32_16x16x32_bf16 v[6:9], v[124:127], v[120:123], v[6:9]
	ds_read_b128 v[124:127], v98 offset:4544
	s_waitcnt lgkmcnt(0)
	v_mfma_f32_16x16x32_bf16 v[54:57], v[124:127], v[120:123], v[54:57]
	ds_read_b128 v[124:127], v98 offset:8896
	s_waitcnt lgkmcnt(0)
	v_mfma_f32_16x16x32_bf16 v[58:61], v[124:127], v[120:123], v[58:61]
	ds_read_b128 v[124:127], v98 offset:13248
	s_waitcnt lgkmcnt(0)
	v_mfma_f32_16x16x32_bf16 v[104:107], v[124:127], v[120:123], v[104:107]
	ds_read_b128 v[124:127], v98 offset:17600
	s_waitcnt lgkmcnt(0)
	v_mfma_f32_16x16x32_bf16 v[108:111], v[124:127], v[120:123], v[108:111]
	ds_read_b128 v[124:127], v98 offset:21952
	s_waitcnt lgkmcnt(0)
	v_mfma_f32_16x16x32_bf16 v[112:115], v[124:127], v[120:123], v[112:115]
	ds_read_b128 v[124:127], v98 offset:26304
	s_waitcnt lgkmcnt(0)
	v_mfma_f32_16x16x32_bf16 v[116:119], v[124:127], v[120:123], v[116:119]
	ds_read_b128 v[124:127], v98 offset:30656
	s_waitcnt lgkmcnt(0)
;     ...
;       {
;         const int tl = wid * 16 + fr;
;         const float bias = sb[g * 128 + tl];
;         float* mx = (float*)(shm + 36864);
; #pragma unroll
;         for (int ns = 0; ns < 8; ++ns) {
;           f32x4 v = acc[ns];
;           v[0] += bias; v[1] += bias; v[2] += bias; v[3] += bias;
;           *(f32x4*)(mx + tl * 132 + ns * 16 + fq * 4) = v;
;         }
;       }
;       __syncthreads();
	v_mfma_f32_16x16x32_bf16 v[0:3], v[124:127], v[120:123], v[2:5]
	s_nop 2
	v_lshl_add_u64 v[4:5], v[52:53], 2, s[14:15]
	global_load_dword v10, v[4:5], off
	v_add_u32_e32 v52, 0x80, v52
	s_waitcnt vmcnt(0)
	v_pk_add_f32 v[8:9], v[8:9], v[10:11] op_sel_hi:[1,0]
	v_pk_add_f32 v[6:7], v[6:7], v[10:11] op_sel_hi:[1,0]
	ds_write_b128 v99, v[6:9] offset:36864
	v_pk_add_f32 v[6:7], v[56:57], v[10:11] op_sel_hi:[1,0]
	v_pk_add_f32 v[4:5], v[54:55], v[10:11] op_sel_hi:[1,0]
	ds_write_b128 v99, v[4:7] offset:36928
	v_pk_add_f32 v[6:7], v[60:61], v[10:11] op_sel_hi:[1,0]
	v_pk_add_f32 v[4:5], v[58:59], v[10:11] op_sel_hi:[1,0]
	ds_write_b128 v99, v[4:7] offset:36992
	v_pk_add_f32 v[6:7], v[106:107], v[10:11] op_sel_hi:[1,0]
	v_pk_add_f32 v[4:5], v[104:105], v[10:11] op_sel_hi:[1,0]
	ds_write_b128 v99, v[4:7] offset:37056
	v_pk_add_f32 v[6:7], v[110:111], v[10:11] op_sel_hi:[1,0]
	v_pk_add_f32 v[4:5], v[108:109], v[10:11] op_sel_hi:[1,0]
	ds_write_b128 v99, v[4:7] offset:37120
	v_pk_add_f32 v[6:7], v[114:115], v[10:11] op_sel_hi:[1,0]
	v_pk_add_f32 v[4:5], v[112:113], v[10:11] op_sel_hi:[1,0]
	ds_write_b128 v99, v[4:7] offset:37184
	v_pk_add_f32 v[6:7], v[118:119], v[10:11] op_sel_hi:[1,0]
	v_pk_add_f32 v[4:5], v[116:117], v[10:11] op_sel_hi:[1,0]
	v_pk_add_f32 v[2:3], v[10:11], v[2:3] op_sel_hi:[0,1]
	v_pk_add_f32 v[0:1], v[10:11], v[0:1] op_sel_hi:[0,1]
	v_lshl_add_u64 v[8:9], s[18:19], 0, v[34:35]
	ds_write_b128 v99, v[4:7] offset:37248
	ds_write_b128 v99, v[0:3] offset:37312
	s_waitcnt lgkmcnt(0)
	s_barrier
; DI float bflo(unsigned v) { return __uint_as_float(v << 16); }
; DI float bfhi(unsigned v) { return __uint_as_float(v & 0xffff0000u); }
;     ...
;       {
;         const float* mx = (const float*)(shm + 36864);
; #pragma unroll
;         for (int i = 0; i < 4; ++i) {
;           const int chunk = tid + i * 512, tl = chunk >> 4, c8 = (chunk & 15) * 8, tt = T0 + tl;
;           const f32x4 m0 = *(const f32x4*)(mx + tl * 132 + c8), m1 = *(const f32x4*)(mx + tl * 132 + c8 + 4);
;           const i32x4 u = *(const i32x4*)(projA + (size_t)tt * 1024 + g * 128 + c8);
;           u16* d = actA + (size_t)tt * 512 + g * 128 + c8;
;           const i32x4 zg = *(const i32x4*)d;
;           i32x4 o;
;           o[0] = (int)pack2(bflo((unsigned)u[0]) * m0[0] * bflo((unsigned)zg[0]), bfhi((unsigned)u[0]) * m0[1] * bfhi((unsigned)zg[0]));
;           o[1] = (int)pack2(bflo((unsigned)u[1]) * m0[2] * bflo((unsigned)zg[1]), bfhi((unsigned)u[1]) * m0[3] * bfhi((unsigned)zg[1]));
;           o[2] = (int)pack2(bflo((unsigned)u[2]) * m1[0] * bflo((unsigned)zg[2]), bfhi((unsigned)u[2]) * m1[1] * bfhi((unsigned)zg[2]));
;           o[3] = (int)pack2(bflo((unsigned)u[3]) * m1[2] * bflo((unsigned)zg[3]), bfhi((unsigned)u[3]) * m1[3] * bfhi((unsigned)zg[3]));
;           if (!dry) *(i32x4*)d = o;
;         }
;       }
;       __syncthreads();
;     }
	ds_read_b128 v[4:7], v100 offset:36864
	ds_read_b128 v[0:3], v100 offset:36880
	global_load_dwordx4 v[8:11], v[8:9], off
	v_lshl_add_u64 v[58:59], s[18:19], 0, v[50:51]
	global_load_dwordx4 v[54:57], v[58:59], off
	s_waitcnt vmcnt(0) lgkmcnt(0)
	v_lshlrev_b32_e32 v60, 16, v8
	v_and_b32_e32 v61, 0xffff0000, v8
	v_lshlrev_b32_e32 v8, 16, v9
	v_and_b32_e32 v9, 0xffff0000, v9
	v_pk_mul_f32 v[4:5], v[4:5], v[60:61]
	v_lshlrev_b32_e32 v60, 16, v54
	v_and_b32_e32 v61, 0xffff0000, v54
	v_pk_mul_f32 v[6:7], v[6:7], v[8:9]
	v_lshlrev_b32_e32 v8, 16, v55
	v_and_b32_e32 v9, 0xffff0000, v55
	v_pk_mul_f32 v[4:5], v[4:5], v[60:61]
	v_pk_mul_f32 v[6:7], v[6:7], v[8:9]
	v_cvt_pk_bf16_f32 v4, v4, v5
	v_cvt_pk_bf16_f32 v5, v6, v7
	v_lshlrev_b32_e32 v6, 16, v10
	v_and_b32_e32 v7, 0xffff0000, v10
	v_pk_mul_f32 v[0:1], v[0:1], v[6:7]
	v_lshlrev_b32_e32 v6, 16, v56
	v_and_b32_e32 v7, 0xffff0000, v56
	v_pk_mul_f32 v[0:1], v[0:1], v[6:7]
	v_lshl_add_u64 v[8:9], s[18:19], 0, v[36:37]
	v_cvt_pk_bf16_f32 v6, v0, v1
	v_lshlrev_b32_e32 v0, 16, v11
	v_and_b32_e32 v1, 0xffff0000, v11
	v_pk_mul_f32 v[0:1], v[2:3], v[0:1]
	v_lshlrev_b32_e32 v2, 16, v57
	v_and_b32_e32 v3, 0xffff0000, v57
	v_pk_mul_f32 v[0:1], v[0:1], v[2:3]
	s_nop 0
	v_cvt_pk_bf16_f32 v7, v0, v1
	global_store_dwordx4 v[58:59], v[4:7], off
	ds_read_b128 v[0:3], v101 offset:36864
	ds_read_b128 v[4:7], v101 offset:36880
	global_load_dwordx4 v[8:11], v[8:9], off
	v_lshl_add_u64 v[58:59], s[18:19], 0, v[48:49]
	global_load_dwordx4 v[54:57], v[58:59], off
	s_waitcnt vmcnt(0) lgkmcnt(0)
	v_lshlrev_b32_e32 v60, 16, v8
	v_and_b32_e32 v61, 0xffff0000, v8
	v_lshlrev_b32_e32 v8, 16, v9
	v_and_b32_e32 v9, 0xffff0000, v9
	v_pk_mul_f32 v[0:1], v[0:1], v[60:61]
	v_lshlrev_b32_e32 v60, 16, v54
	v_and_b32_e32 v61, 0xffff0000, v54
	v_pk_mul_f32 v[2:3], v[2:3], v[8:9]
	v_lshlrev_b32_e32 v8, 16, v55
	v_and_b32_e32 v9, 0xffff0000, v55
	v_pk_mul_f32 v[0:1], v[0:1], v[60:61]
	v_pk_mul_f32 v[2:3], v[2:3], v[8:9]
	v_cvt_pk_bf16_f32 v0, v0, v1
	v_cvt_pk_bf16_f32 v1, v2, v3
	v_lshlrev_b32_e32 v2, 16, v10
	v_and_b32_e32 v3, 0xffff0000, v10
	v_pk_mul_f32 v[2:3], v[4:5], v[2:3]
	v_lshlrev_b32_e32 v4, 16, v56
	v_and_b32_e32 v5, 0xffff0000, v56
	v_pk_mul_f32 v[2:3], v[2:3], v[4:5]
	v_lshlrev_b32_e32 v4, 16, v11
	v_and_b32_e32 v5, 0xffff0000, v11
	v_pk_mul_f32 v[4:5], v[6:7], v[4:5]
	v_lshlrev_b32_e32 v6, 16, v57
	v_and_b32_e32 v7, 0xffff0000, v57
	v_pk_mul_f32 v[4:5], v[4:5], v[6:7]
	v_cvt_pk_bf16_f32 v2, v2, v3
	v_cvt_pk_bf16_f32 v3, v4, v5
	global_store_dwordx4 v[58:59], v[0:3], off
	v_lshl_add_u64 v[8:9], s[18:19], 0, v[38:39]
	ds_read_b128 v[4:7], v102 offset:36864
	ds_read_b128 v[0:3], v102 offset:36880
	global_load_dwordx4 v[8:11], v[8:9], off
	v_lshl_add_u64 v[58:59], s[18:19], 0, v[46:47]
	global_load_dwordx4 v[54:57], v[58:59], off
	s_waitcnt vmcnt(0) lgkmcnt(0)
	v_lshlrev_b32_e32 v60, 16, v8
	v_and_b32_e32 v61, 0xffff0000, v8
	v_lshlrev_b32_e32 v8, 16, v9
	v_and_b32_e32 v9, 0xffff0000, v9
	v_pk_mul_f32 v[4:5], v[4:5], v[60:61]
	v_lshlrev_b32_e32 v60, 16, v54
	v_and_b32_e32 v61, 0xffff0000, v54
	v_pk_mul_f32 v[6:7], v[6:7], v[8:9]
	v_lshlrev_b32_e32 v8, 16, v55
	v_and_b32_e32 v9, 0xffff0000, v55
	v_pk_mul_f32 v[4:5], v[4:5], v[60:61]
	v_pk_mul_f32 v[6:7], v[6:7], v[8:9]
	v_cvt_pk_bf16_f32 v4, v4, v5
	v_cvt_pk_bf16_f32 v5, v6, v7
	v_lshlrev_b32_e32 v6, 16, v10
	v_and_b32_e32 v7, 0xffff0000, v10
	v_pk_mul_f32 v[0:1], v[0:1], v[6:7]
	v_lshlrev_b32_e32 v6, 16, v56
	v_and_b32_e32 v7, 0xffff0000, v56
	v_pk_mul_f32 v[0:1], v[0:1], v[6:7]
	v_lshl_add_u64 v[8:9], s[18:19], 0, v[40:41]
	v_cvt_pk_bf16_f32 v6, v0, v1
	v_lshlrev_b32_e32 v0, 16, v11
	v_and_b32_e32 v1, 0xffff0000, v11
	v_pk_mul_f32 v[0:1], v[2:3], v[0:1]
	v_lshlrev_b32_e32 v2, 16, v57
	v_and_b32_e32 v3, 0xffff0000, v57
	v_pk_mul_f32 v[0:1], v[0:1], v[2:3]
	s_nop 0
	v_cvt_pk_bf16_f32 v7, v0, v1
	global_store_dwordx4 v[58:59], v[4:7], off
	ds_read_b128 v[4:7], v103 offset:36864
	ds_read_b128 v[0:3], v103 offset:36880
	global_load_dwordx4 v[8:11], v[8:9], off
	v_lshl_add_u64 v[58:59], s[18:19], 0, v[44:45]
	global_load_dwordx4 v[54:57], v[58:59], off
	s_add_u32 s18, s18, 0x100
	s_addc_u32 s19, s19, 0
	s_cmpk_eq_i32 s16, 0x800
	s_waitcnt vmcnt(0) lgkmcnt(0)
	v_lshlrev_b32_e32 v60, 16, v8
	v_and_b32_e32 v61, 0xffff0000, v8
	v_lshlrev_b32_e32 v8, 16, v9
	v_and_b32_e32 v9, 0xffff0000, v9
	v_pk_mul_f32 v[4:5], v[4:5], v[60:61]
	v_lshlrev_b32_e32 v60, 16, v54
	v_and_b32_e32 v61, 0xffff0000, v54
	v_pk_mul_f32 v[6:7], v[6:7], v[8:9]
	v_lshlrev_b32_e32 v8, 16, v55
	v_and_b32_e32 v9, 0xffff0000, v55
	v_pk_mul_f32 v[4:5], v[4:5], v[60:61]
	v_pk_mul_f32 v[6:7], v[6:7], v[8:9]
	v_cvt_pk_bf16_f32 v4, v4, v5
	v_cvt_pk_bf16_f32 v5, v6, v7
	v_lshlrev_b32_e32 v6, 16, v10
	v_and_b32_e32 v7, 0xffff0000, v10
	v_pk_mul_f32 v[0:1], v[0:1], v[6:7]
	v_lshlrev_b32_e32 v6, 16, v56
	v_and_b32_e32 v7, 0xffff0000, v56
	v_pk_mul_f32 v[0:1], v[0:1], v[6:7]
	s_nop 0
	v_cvt_pk_bf16_f32 v6, v0, v1
	v_lshlrev_b32_e32 v0, 16, v11
	v_and_b32_e32 v1, 0xffff0000, v11
	v_pk_mul_f32 v[0:1], v[2:3], v[0:1]
	v_lshlrev_b32_e32 v2, 16, v57
	v_and_b32_e32 v3, 0xffff0000, v57
	v_pk_mul_f32 v[0:1], v[0:1], v[2:3]
	s_nop 0
	v_cvt_pk_bf16_f32 v7, v0, v1
	global_store_dwordx4 v[58:59], v[4:7], off
	s_waitcnt lgkmcnt(0)
	s_barrier
	s_cbranch_scc0 .LBB0_781
	s_add_i32 s4, s4, s72
	v_add_u32_e32 v16, s81, v16
	v_add_u32_e32 v18, s81, v18
	v_add_u32_e32 v20, s81, v20
	v_add_u32_e32 v22, s81, v22
	s_cmpk_gt_i32 s4, 0xff
	v_add_u32_e32 v30, s81, v30
	s_cbranch_scc0 .LBB0_778
	v_readlane_b32 s8, v253, 2
	v_readlane_b32 s50, v252, 18
	v_readlane_b32 s9, v253, 3
	v_readlane_b32 s51, v252, 19
	s_movk_i32 s42, 0xfc0
	v_readlane_b32 s46, v252, 31
	s_mov_b64 s[34:35], 0x20000
	s_mov_b64 s[36:37], 0x8000
	s_mov_b64 s[38:39], 0x18000
	v_readlane_b32 s10, v253, 4
	v_readlane_b32 s11, v253, 5
	v_readlane_b32 s12, v253, 6
	v_readlane_b32 s13, v253, 7
	v_readlane_b32 s14, v253, 8
	v_readlane_b32 s15, v253, 9
	v_readlane_b32 s16, v253, 10
	v_readlane_b32 s17, v253, 11
	v_readlane_b32 s18, v253, 12
	v_readlane_b32 s19, v253, 13
	v_readlane_b32 s20, v253, 14
	v_readlane_b32 s21, v253, 15
	v_readlane_b32 s22, v253, 16
	v_readlane_b32 s23, v253, 17

; DI float bflo(unsigned v) { return __uint_as_float(v << 16); }
; DI float bfhi(unsigned v) { return __uint_as_float(v & 0xffff0000u); }
; DI void phase_pooled(const Params& P) {
;     ...
;     for (int j = 1; j < win; ++j) {
;       if (s0 - j >= 0) {
;         const i32x4 v = *(const i32x4*)(base - (size_t)j * 512);
; #pragma unroll
;         for (int e = 0; e < 4; ++e) { run[2 * e] += bflo((unsigned)v[e]); run[2 * e + 1] += bfhi((unsigned)v[e]); }
;       }
;     }
.LBB0_789:
	v_cmp_le_u32_e32 vcc, s12, v29
	s_and_saveexec_b64 s[10:11], vcc
	s_cbranch_execz .LBB0_788
	global_load_dwordx4 v[10:13], v[6:7], off
	s_waitcnt vmcnt(0) lgkmcnt(0)
	v_lshlrev_b32_e32 v22, 16, v10
	v_and_b32_e32 v23, 0xffff0000, v10
	v_lshlrev_b32_e32 v10, 16, v11
	v_and_b32_e32 v11, 0xffff0000, v11
	v_pk_add_f32 v[16:17], v[16:17], v[10:11]
	v_lshlrev_b32_e32 v10, 16, v12
	v_and_b32_e32 v11, 0xffff0000, v12
	v_pk_add_f32 v[18:19], v[18:19], v[10:11]
	v_lshlrev_b32_e32 v10, 16, v13
	v_and_b32_e32 v11, 0xffff0000, v13
	v_pk_add_f32 v[14:15], v[14:15], v[22:23]
	v_pk_add_f32 v[20:21], v[20:21], v[10:11]
	s_branch .LBB0_788

; DI float bflo(unsigned v) { return __uint_as_float(v << 16); }
; DI float bfhi(unsigned v) { return __uint_as_float(v & 0xffff0000u); }
; DI void phase_pooled(const Params& P) {
;     ...
; #pragma unroll 4
;     for (int i = 0; i < 16; ++i) {
;       const i32x4 v = *(const i32x4*)(base + (size_t)i * 512);
;       float x0[8];
; #pragma unroll
;       for (int e = 0; e < 4; ++e) {
;         x0[2 * e] = bflo((unsigned)v[e]); x0[2 * e + 1] = bfhi((unsigned)v[e]);
;         run[2 * e] += x0[2 * e]; run[2 * e + 1] += x0[2 * e + 1];
;       }
;       const int s = s0 + i;
;       const float inv = 1.f / (float)min(s + 1, win);
;       i32x4 o;
; #pragma unroll
;       for (int e = 0; e < 4; ++e) o[e] = (int)pack2(run[2 * e] * inv - x0[2 * e], run[2 * e + 1] * inv - x0[2 * e + 1]);
;       *(i32x4*)(pooled + (size_t)(t0 + i) * 512 + c8 * 8) = o;
;       if (s - win + 1 >= 0) {
;         const i32x4 w = *(const i32x4*)(base + (size_t)(i - win + 1) * 512);
; #pragma unroll
;         for (int e = 0; e < 4; ++e) { run[2 * e] -= bflo((unsigned)w[e]); run[2 * e + 1] -= bfhi((unsigned)w[e]); }
;       }
;     }
.LBB0_793:
	v_lshl_add_u64 v[10:11], v[6:7], 0, s[8:9]
	v_add_co_u32_e32 v12, vcc, 0x1d000000, v10
	s_nop 1
	v_addc_co_u32_e32 v13, vcc, 0, v11, vcc
	global_load_dwordx4 v[30:33], v[12:13], off
	s_waitcnt vmcnt(0) lgkmcnt(0)
	v_lshlrev_b32_e32 v12, 16, v30
	v_and_b32_e32 v13, 0xffff0000, v30
	v_lshlrev_b32_e32 v34, 16, v32
	v_and_b32_e32 v35, 0xffff0000, v32
	v_lshlrev_b32_e32 v36, 16, v33
	v_and_b32_e32 v37, 0xffff0000, v33
	v_add_u32_e32 v30, 1, v29
	v_pk_add_f32 v[22:23], v[14:15], v[12:13]
	v_pk_add_f32 v[14:15], v[18:19], v[34:35]
	v_pk_add_f32 v[18:19], v[20:21], v[36:37]
	v_min_i32_e32 v20, v30, v27
	v_cvt_f32_u32_e32 v20, v20
	v_lshlrev_b32_e32 v24, 16, v31
	v_and_b32_e32 v25, 0xffff0000, v31
	v_pk_add_f32 v[16:17], v[16:17], v[24:25]
	v_div_scale_f32 v21, s[10:11], v20, v20, 1.0
	v_rcp_f32_e32 v31, v21
	s_nop 0
	v_fma_f32 v32, -v21, v31, 1.0
	v_fmac_f32_e32 v31, v32, v31
	v_div_scale_f32 v32, vcc, 1.0, v20, 1.0
	v_mul_f32_e32 v33, v32, v31
	v_fma_f32 v38, -v21, v33, v32
	v_fmac_f32_e32 v33, v38, v31
	v_fma_f32 v21, -v21, v33, v32
	v_div_fmas_f32 v21, v21, v31, v33
	v_div_fixup_f32 v20, v21, v20, 1.0
	v_pk_fma_f32 v[12:13], v[20:21], v[22:23], v[12:13] op_sel_hi:[0,1,1] neg_lo:[0,0,1] neg_hi:[0,0,1]
	v_cvt_pk_bf16_f32 v32, v12, v13
	v_pk_fma_f32 v[12:13], v[20:21], v[16:17], v[24:25] op_sel_hi:[0,1,1] neg_lo:[0,0,1] neg_hi:[0,0,1]
	v_cvt_pk_bf16_f32 v33, v12, v13
	v_pk_fma_f32 v[12:13], v[20:21], v[14:15], v[34:35] op_sel_hi:[0,1,1] neg_lo:[0,0,1] neg_hi:[0,0,1]
	v_cvt_pk_bf16_f32 v34, v12, v13
	v_pk_fma_f32 v[12:13], v[20:21], v[18:19], v[36:37] op_sel_hi:[0,1,1] neg_lo:[0,0,1] neg_hi:[0,0,1]
	v_cvt_pk_bf16_f32 v35, v12, v13
	v_add_co_u32_e32 v12, vcc, 0xf000000, v10
	s_nop 1
	v_addc_co_u32_e32 v13, vcc, 0, v11, vcc
	global_store_dwordx4 v[12:13], v[32:35], off
	v_cmp_ge_u32_e32 vcc, v29, v27
	v_lshl_add_u64 v[12:13], v[8:9], 0, s[8:9]
	s_and_saveexec_b64 s[10:11], vcc
	s_cbranch_execz .LBB0_795
	v_add_co_u32_e32 v20, vcc, 0x1d000000, v12
	s_nop 1
	v_addc_co_u32_e32 v21, vcc, 0, v13, vcc
	global_load_dwordx4 v[32:35], v[20:21], off offset:1024
	s_waitcnt vmcnt(0) lgkmcnt(0)
	v_lshlrev_b32_e32 v20, 16, v32
	v_and_b32_e32 v21, 0xffff0000, v32
	v_pk_add_f32 v[22:23], v[22:23], v[20:21] neg_lo:[0,1] neg_hi:[0,1]
	v_lshlrev_b32_e32 v20, 16, v33
	v_and_b32_e32 v21, 0xffff0000, v33
	v_pk_add_f32 v[16:17], v[16:17], v[20:21] neg_lo:[0,1] neg_hi:[0,1]
	v_lshlrev_b32_e32 v20, 16, v34
	v_and_b32_e32 v21, 0xffff0000, v34
	v_pk_add_f32 v[14:15], v[14:15], v[20:21] neg_lo:[0,1] neg_hi:[0,1]
	v_lshlrev_b32_e32 v20, 16, v35
	v_and_b32_e32 v21, 0xffff0000, v35
	v_pk_add_f32 v[18:19], v[18:19], v[20:21] neg_lo:[0,1] neg_hi:[0,1]
.LBB0_795:
	s_or_b64 exec, exec, s[10:11]
	v_add_co_u32_e32 v20, vcc, 0x1d000000, v10
	v_add_u32_e32 v31, 2, v29
	s_nop 0
	v_addc_co_u32_e32 v21, vcc, 0, v11, vcc
	global_load_dwordx4 v[32:35], v[20:21], off offset:1024
	s_waitcnt vmcnt(0) lgkmcnt(0)
	v_lshlrev_b32_e32 v40, 16, v34
	v_and_b32_e32 v41, 0xffff0000, v34
	v_pk_add_f32 v[20:21], v[14:15], v[40:41]
	v_lshlrev_b32_e32 v14, 16, v35
	v_and_b32_e32 v15, 0xffff0000, v35
	v_pk_add_f32 v[24:25], v[18:19], v[14:15]
	v_min_i32_e32 v18, v31, v27
	v_cvt_f32_u32_e32 v18, v18
	v_lshlrev_b32_e32 v36, 16, v32
	v_and_b32_e32 v37, 0xffff0000, v32
	v_lshlrev_b32_e32 v38, 16, v33
	v_div_scale_f32 v19, s[10:11], v18, v18, 1.0
	v_rcp_f32_e32 v32, v19
	v_and_b32_e32 v39, 0xffff0000, v33
	v_pk_add_f32 v[22:23], v[22:23], v[36:37]
	v_pk_add_f32 v[16:17], v[16:17], v[38:39]
	v_fma_f32 v33, -v19, v32, 1.0
	v_fmac_f32_e32 v32, v33, v32
	v_div_scale_f32 v33, vcc, 1.0, v18, 1.0
	v_mul_f32_e32 v34, v33, v32
	v_fma_f32 v35, -v19, v34, v33
	v_fmac_f32_e32 v34, v35, v32
	v_fma_f32 v19, -v19, v34, v33
	v_div_fmas_f32 v19, v19, v32, v34
	v_div_fixup_f32 v18, v19, v18, 1.0
	v_pk_fma_f32 v[32:33], v[18:19], v[22:23], v[36:37] op_sel_hi:[0,1,1] neg_lo:[0,0,1] neg_hi:[0,0,1]
	v_pk_fma_f32 v[34:35], v[18:19], v[16:17], v[38:39] op_sel_hi:[0,1,1] neg_lo:[0,0,1] neg_hi:[0,0,1]
	v_cvt_pk_bf16_f32 v32, v32, v33
	v_cvt_pk_bf16_f32 v33, v34, v35
	v_pk_fma_f32 v[34:35], v[18:19], v[20:21], v[40:41] op_sel_hi:[0,1,1] neg_lo:[0,0,1] neg_hi:[0,0,1]
	v_pk_fma_f32 v[14:15], v[18:19], v[24:25], v[14:15] op_sel_hi:[0,1,1] neg_lo:[0,0,1] neg_hi:[0,0,1]
	v_cvt_pk_bf16_f32 v34, v34, v35
	v_cvt_pk_bf16_f32 v35, v14, v15
	v_add_co_u32_e32 v14, vcc, 0xf000000, v10
	s_nop 1
	v_addc_co_u32_e32 v15, vcc, 0, v11, vcc
	v_cmp_gt_i32_e32 vcc, v30, v28
	global_store_dwordx4 v[14:15], v[32:35], off offset:1024
	s_and_saveexec_b64 s[10:11], vcc
	s_cbranch_execz .LBB0_797
	v_add_co_u32_e32 v14, vcc, 0x1d000000, v12
	s_nop 1
	v_addc_co_u32_e32 v15, vcc, 0, v13, vcc
	global_load_dwordx4 v[32:35], v[14:15], off offset:2048
	s_waitcnt vmcnt(0) lgkmcnt(0)
	v_lshlrev_b32_e32 v14, 16, v32
	v_and_b32_e32 v15, 0xffff0000, v32
	v_pk_add_f32 v[22:23], v[22:23], v[14:15] neg_lo:[0,1] neg_hi:[0,1]
	v_lshlrev_b32_e32 v14, 16, v33
	v_and_b32_e32 v15, 0xffff0000, v33
	v_pk_add_f32 v[16:17], v[16:17], v[14:15] neg_lo:[0,1] neg_hi:[0,1]
	v_lshlrev_b32_e32 v14, 16, v34
	v_and_b32_e32 v15, 0xffff0000, v34
	v_pk_add_f32 v[20:21], v[20:21], v[14:15] neg_lo:[0,1] neg_hi:[0,1]
	v_lshlrev_b32_e32 v14, 16, v35
	v_and_b32_e32 v15, 0xffff0000, v35
	v_pk_add_f32 v[24:25], v[24:25], v[14:15] neg_lo:[0,1] neg_hi:[0,1]
; DI float bflo(unsigned v) { return __uint_as_float(v << 16); }
; DI float bfhi(unsigned v) { return __uint_as_float(v & 0xffff0000u); }
; DI void phase_pooled(const Params& P) {
;     ...
; #pragma unroll 4
;     for (int i = 0; i < 16; ++i) {
;       const i32x4 v = *(const i32x4*)(base + (size_t)i * 512);
;       float x0[8];
; #pragma unroll
;       for (int e = 0; e < 4; ++e) {
;         x0[2 * e] = bflo((unsigned)v[e]); x0[2 * e + 1] = bfhi((unsigned)v[e]);
;         run[2 * e] += x0[2 * e]; run[2 * e + 1] += x0[2 * e + 1];
;       }
;       const int s = s0 + i;
;       const float inv = 1.f / (float)min(s + 1, win);
;       i32x4 o;
; #pragma unroll
;       for (int e = 0; e < 4; ++e) o[e] = (int)pack2(run[2 * e] * inv - x0[2 * e], run[2 * e + 1] * inv - x0[2 * e + 1]);
;       *(i32x4*)(pooled + (size_t)(t0 + i) * 512 + c8 * 8) = o;
;       if (s - win + 1 >= 0) {
;         const i32x4 w = *(const i32x4*)(base + (size_t)(i - win + 1) * 512);
; #pragma unroll
;         for (int e = 0; e < 4; ++e) { run[2 * e] -= bflo((unsigned)w[e]); run[2 * e + 1] -= bfhi((unsigned)w[e]); }
;       }
;     }
.LBB0_797:
	s_or_b64 exec, exec, s[10:11]
	v_add_co_u32_e32 v14, vcc, 0x1d000000, v10
	s_nop 1
	v_addc_co_u32_e32 v15, vcc, 0, v11, vcc
	global_load_dwordx4 v[32:35], v[14:15], off offset:2048
	s_waitcnt vmcnt(0) lgkmcnt(0)
	v_lshlrev_b32_e32 v36, 16, v32
	v_and_b32_e32 v37, 0xffff0000, v32
	v_pk_add_f32 v[14:15], v[22:23], v[36:37]
	v_add_u32_e32 v22, 3, v29
	v_min_i32_e32 v23, v22, v27
	v_cvt_f32_u32_e32 v23, v23
	v_lshlrev_b32_e32 v40, 16, v34
	v_and_b32_e32 v41, 0xffff0000, v34
	v_lshlrev_b32_e32 v42, 16, v35
	v_and_b32_e32 v43, 0xffff0000, v35
	v_pk_add_f32 v[18:19], v[20:21], v[40:41]
	v_pk_add_f32 v[20:21], v[24:25], v[42:43]
	v_div_scale_f32 v24, s[10:11], v23, v23, 1.0
	v_rcp_f32_e32 v25, v24
	v_lshlrev_b32_e32 v38, 16, v33
	v_and_b32_e32 v39, 0xffff0000, v33
	v_pk_add_f32 v[16:17], v[16:17], v[38:39]
	v_fma_f32 v30, -v24, v25, 1.0
	v_fmac_f32_e32 v25, v30, v25
	v_div_scale_f32 v30, vcc, 1.0, v23, 1.0
	v_mul_f32_e32 v32, v30, v25
	v_fma_f32 v33, -v24, v32, v30
	v_fmac_f32_e32 v32, v33, v25
	v_fma_f32 v24, -v24, v32, v30
	v_div_fmas_f32 v24, v24, v25, v32
	v_div_fixup_f32 v24, v24, v23, 1.0
	v_pk_fma_f32 v[32:33], v[24:25], v[14:15], v[36:37] op_sel_hi:[0,1,1] neg_lo:[0,0,1] neg_hi:[0,0,1]
	v_pk_fma_f32 v[34:35], v[24:25], v[16:17], v[38:39] op_sel_hi:[0,1,1] neg_lo:[0,0,1] neg_hi:[0,0,1]
	v_cvt_pk_bf16_f32 v32, v32, v33
	v_cvt_pk_bf16_f32 v33, v34, v35
	v_pk_fma_f32 v[34:35], v[24:25], v[18:19], v[40:41] op_sel_hi:[0,1,1] neg_lo:[0,0,1] neg_hi:[0,0,1]
	v_pk_fma_f32 v[24:25], v[24:25], v[20:21], v[42:43] op_sel_hi:[0,1,1] neg_lo:[0,0,1] neg_hi:[0,0,1]
	v_cvt_pk_bf16_f32 v34, v34, v35
	v_cvt_pk_bf16_f32 v35, v24, v25
	v_add_co_u32_e32 v24, vcc, 0xf000000, v10
	s_nop 1
	v_addc_co_u32_e32 v25, vcc, 0, v11, vcc
	v_cmp_ge_u32_e32 vcc, v31, v27
	global_store_dwordx4 v[24:25], v[32:35], off offset:2048
	s_and_saveexec_b64 s[10:11], vcc
	s_cbranch_execz .LBB0_799
	v_add_co_u32_e32 v24, vcc, 0x1d000000, v12
	s_nop 1
	v_addc_co_u32_e32 v25, vcc, 0, v13, vcc
	global_load_dwordx4 v[30:33], v[24:25], off offset:3072
	s_waitcnt vmcnt(0) lgkmcnt(0)
	v_lshlrev_b32_e32 v24, 16, v30
	v_and_b32_e32 v25, 0xffff0000, v30
	v_pk_add_f32 v[14:15], v[14:15], v[24:25] neg_lo:[0,1] neg_hi:[0,1]
	v_lshlrev_b32_e32 v24, 16, v31
	v_and_b32_e32 v25, 0xffff0000, v31
	v_pk_add_f32 v[16:17], v[16:17], v[24:25] neg_lo:[0,1] neg_hi:[0,1]
	v_lshlrev_b32_e32 v24, 16, v32
	v_and_b32_e32 v25, 0xffff0000, v32
	v_pk_add_f32 v[18:19], v[18:19], v[24:25] neg_lo:[0,1] neg_hi:[0,1]
	v_lshlrev_b32_e32 v24, 16, v33
	v_and_b32_e32 v25, 0xffff0000, v33
	v_pk_add_f32 v[20:21], v[20:21], v[24:25] neg_lo:[0,1] neg_hi:[0,1]
.LBB0_799:
	s_or_b64 exec, exec, s[10:11]
	v_add_co_u32_e32 v24, vcc, 0x1d000000, v10
	v_add_u32_e32 v29, 4, v29
	s_nop 0
	v_addc_co_u32_e32 v25, vcc, 0, v11, vcc
	global_load_dwordx4 v[30:33], v[24:25], off offset:3072
	v_min_i32_e32 v23, v29, v27
	v_cvt_f32_u32_e32 v23, v23
	s_waitcnt vmcnt(0) lgkmcnt(0)
	v_lshlrev_b32_e32 v24, 16, v30
	v_and_b32_e32 v25, 0xffff0000, v30
	v_div_scale_f32 v30, s[10:11], v23, v23, 1.0
	v_lshlrev_b32_e32 v34, 16, v31
	v_and_b32_e32 v35, 0xffff0000, v31
	v_rcp_f32_e32 v31, v30
	v_lshlrev_b32_e32 v36, 16, v32
	v_and_b32_e32 v37, 0xffff0000, v32
	v_lshlrev_b32_e32 v38, 16, v33
	v_fma_f32 v32, -v30, v31, 1.0
	v_fmac_f32_e32 v31, v32, v31
	v_div_scale_f32 v32, vcc, 1.0, v23, 1.0
	v_and_b32_e32 v39, 0xffff0000, v33
	v_mul_f32_e32 v33, v32, v31
	v_fma_f32 v40, -v30, v33, v32
	v_fmac_f32_e32 v33, v40, v31
	v_fma_f32 v30, -v30, v33, v32
	v_div_fmas_f32 v30, v30, v31, v33
	v_pk_add_f32 v[14:15], v[14:15], v[24:25]
	v_div_fixup_f32 v40, v30, v23, 1.0
	v_pk_add_f32 v[16:17], v[16:17], v[34:35]
	v_pk_fma_f32 v[24:25], v[40:41], v[14:15], v[24:25] op_sel_hi:[0,1,1] neg_lo:[0,0,1] neg_hi:[0,0,1]
	v_pk_add_f32 v[18:19], v[18:19], v[36:37]
	v_cvt_pk_bf16_f32 v30, v24, v25
	v_pk_fma_f32 v[24:25], v[40:41], v[16:17], v[34:35] op_sel_hi:[0,1,1] neg_lo:[0,0,1] neg_hi:[0,0,1]
	v_pk_add_f32 v[20:21], v[20:21], v[38:39]
	v_cvt_pk_bf16_f32 v31, v24, v25
	v_pk_fma_f32 v[24:25], v[40:41], v[18:19], v[36:37] op_sel_hi:[0,1,1] neg_lo:[0,0,1] neg_hi:[0,0,1]
	v_add_co_u32_e32 v10, vcc, 0xf000000, v10
	v_cvt_pk_bf16_f32 v32, v24, v25
	v_pk_fma_f32 v[24:25], v[40:41], v[20:21], v[38:39] op_sel_hi:[0,1,1] neg_lo:[0,0,1] neg_hi:[0,0,1]
	v_addc_co_u32_e32 v11, vcc, 0, v11, vcc
	v_cvt_pk_bf16_f32 v33, v24, v25
	v_cmp_gt_i32_e32 vcc, v22, v28
	global_store_dwordx4 v[10:11], v[30:33], off offset:3072
	s_and_saveexec_b64 s[10:11], vcc
	s_cbranch_execz .LBB0_792
	v_add_co_u32_e32 v10, vcc, 0x1d001000, v12
	s_nop 1
	v_addc_co_u32_e32 v11, vcc, 0, v13, vcc
	global_load_dwordx4 v[10:13], v[10:11], off
	s_waitcnt vmcnt(0) lgkmcnt(0)
	v_lshlrev_b32_e32 v22, 16, v10
	v_and_b32_e32 v23, 0xffff0000, v10
	v_lshlrev_b32_e32 v10, 16, v11
	v_and_b32_e32 v11, 0xffff0000, v11
	v_pk_add_f32 v[16:17], v[16:17], v[10:11] neg_lo:[0,1] neg_hi:[0,1]
	v_lshlrev_b32_e32 v10, 16, v12
	v_and_b32_e32 v11, 0xffff0000, v12
	v_pk_add_f32 v[18:19], v[18:19], v[10:11] neg_lo:[0,1] neg_hi:[0,1]
	v_lshlrev_b32_e32 v10, 16, v13
	v_and_b32_e32 v11, 0xffff0000, v13
	v_pk_add_f32 v[14:15], v[14:15], v[22:23] neg_lo:[0,1] neg_hi:[0,1]
	v_pk_add_f32 v[20:21], v[20:21], v[10:11] neg_lo:[0,1] neg_hi:[0,1]
	s_branch .LBB0_792

; DI float bflo(unsigned v) { return __uint_as_float(v << 16); }
; DI float bfhi(unsigned v) { return __uint_as_float(v & 0xffff0000u); }
; DI int tid_() { int t = threadIdx.x; asm volatile("" : "+v"(t)); return t; }
; DI void phase_pool_gemm(const Params& P, char* shm) {
;     ...
; #pragma unroll 4
;     for (int i = 0; i < 16; ++i) {
;       const int chunk = tid_() + i * 512, row = chunk >> 5, c8 = (chunk & 31) * 8;
;       const i32x4 v = *(const i32x4*)(shm + row * 528 + c8 * 2);
;       u16* d = actB + (size_t)(brow + row) * 512 + bcol + c8;
;       const i32x4 g = *(const i32x4*)d;
;       i32x4 o;
; #pragma unroll
;       for (int e = 0; e < 4; ++e)
;         o[e] = (int)pack2(bflo((unsigned)v[e]) * bflo((unsigned)g[e]), bfhi((unsigned)v[e]) * bfhi((unsigned)g[e]));
;       *(i32x4*)d = o;
;     }
;     __syncthreads();
.LBB0_822:
	s_nop 0
	v_mov_b32_e32 v0, v135
	s_nop 0
	v_add_u32_e32 v1, s1, v0
	v_lshlrev_b32_e32 v0, 4, v0
	v_ashrrev_i32_e32 v4, 5, v1
	v_and_b32_e32 v132, 0x1f0, v0
	v_mad_u64_u32 v[0:1], s[6:7], v4, s68, v[132:133]
	v_add_u32_e32 v4, s0, v4
	v_ashrrev_i32_e32 v5, 31, v4
	v_lshlrev_b64 v[4:5], 10, v[4:5]
	v_lshl_add_u64 v[4:5], s[4:5], 0, v[4:5]
	v_lshl_add_u64 v[8:9], v[4:5], 0, v[132:133]
	global_load_dwordx4 v[4:7], v[8:9], off
	ds_read_b128 v[0:3], v0
	s_waitcnt lgkmcnt(0)
	v_lshlrev_b32_e32 v10, 16, v0
	v_and_b32_e32 v11, 0xffff0000, v0
	s_waitcnt vmcnt(0)
	v_lshlrev_b32_e32 v12, 16, v4
	v_and_b32_e32 v13, 0xffff0000, v4
	v_pk_mul_f32 v[10:11], v[10:11], v[12:13]
	v_lshlrev_b32_e32 v4, 16, v5
	v_cvt_pk_bf16_f32 v0, v10, v11
	v_lshlrev_b32_e32 v10, 16, v1
	v_and_b32_e32 v11, 0xffff0000, v1
	v_and_b32_e32 v5, 0xffff0000, v5
	v_pk_mul_f32 v[4:5], v[10:11], v[4:5]
	v_lshlrev_b32_e32 v10, 16, v6
	v_cvt_pk_bf16_f32 v1, v4, v5
	v_lshlrev_b32_e32 v4, 16, v2
	v_and_b32_e32 v5, 0xffff0000, v2
	v_and_b32_e32 v11, 0xffff0000, v6
	v_pk_mul_f32 v[4:5], v[4:5], v[10:11]
	v_lshlrev_b32_e32 v6, 16, v7
	v_cvt_pk_bf16_f32 v2, v4, v5
	v_lshlrev_b32_e32 v4, 16, v3
	v_and_b32_e32 v5, 0xffff0000, v3
	v_and_b32_e32 v7, 0xffff0000, v7
	v_pk_mul_f32 v[4:5], v[4:5], v[6:7]
	s_nop 0
	v_cvt_pk_bf16_f32 v3, v4, v5
	global_store_dwordx4 v[8:9], v[0:3], off
	s_nop 1
	v_mov_b32_e32 v0, v135
	s_nop 0
	v_add_u32_e32 v1, s1, v0
	v_add_u32_e32 v1, 0x200, v1
	v_lshlrev_b32_e32 v0, 4, v0
	v_ashrrev_i32_e32 v4, 5, v1
	v_and_b32_e32 v132, 0x1f0, v0
	v_mad_u64_u32 v[0:1], s[6:7], v4, s68, v[132:133]
	v_add_u32_e32 v4, s0, v4
	v_ashrrev_i32_e32 v5, 31, v4
	v_lshlrev_b64 v[4:5], 10, v[4:5]
	v_lshl_add_u64 v[4:5], s[4:5], 0, v[4:5]
	v_lshl_add_u64 v[8:9], v[4:5], 0, v[132:133]
	global_load_dwordx4 v[4:7], v[8:9], off
	ds_read_b128 v[0:3], v0
	s_waitcnt lgkmcnt(0)
	v_lshlrev_b32_e32 v10, 16, v0
	v_and_b32_e32 v11, 0xffff0000, v0
	s_waitcnt vmcnt(0)
	v_lshlrev_b32_e32 v12, 16, v4
	v_and_b32_e32 v13, 0xffff0000, v4
	v_pk_mul_f32 v[10:11], v[10:11], v[12:13]
	v_lshlrev_b32_e32 v4, 16, v5
	v_cvt_pk_bf16_f32 v0, v10, v11
	v_lshlrev_b32_e32 v10, 16, v1
	v_and_b32_e32 v11, 0xffff0000, v1
	v_and_b32_e32 v5, 0xffff0000, v5
	v_pk_mul_f32 v[4:5], v[10:11], v[4:5]
	v_lshlrev_b32_e32 v10, 16, v6
	v_cvt_pk_bf16_f32 v1, v4, v5
	v_lshlrev_b32_e32 v4, 16, v2
	v_and_b32_e32 v5, 0xffff0000, v2
	v_and_b32_e32 v11, 0xffff0000, v6
	v_pk_mul_f32 v[4:5], v[4:5], v[10:11]
	v_lshlrev_b32_e32 v6, 16, v7
	v_cvt_pk_bf16_f32 v2, v4, v5
	v_lshlrev_b32_e32 v4, 16, v3
	v_and_b32_e32 v5, 0xffff0000, v3
	v_and_b32_e32 v7, 0xffff0000, v7
	v_pk_mul_f32 v[4:5], v[4:5], v[6:7]
	s_nop 0
	v_cvt_pk_bf16_f32 v3, v4, v5
	global_store_dwordx4 v[8:9], v[0:3], off
	s_nop 1
	v_mov_b32_e32 v0, v135
	s_nop 0
	v_add_u32_e32 v1, s1, v0
	v_add_u32_e32 v1, 0x400, v1
	v_lshlrev_b32_e32 v0, 4, v0
	v_ashrrev_i32_e32 v4, 5, v1
	v_and_b32_e32 v132, 0x1f0, v0
	v_mad_u64_u32 v[0:1], s[6:7], v4, s68, v[132:133]
	v_add_u32_e32 v4, s0, v4
	v_ashrrev_i32_e32 v5, 31, v4
	v_lshlrev_b64 v[4:5], 10, v[4:5]
	v_lshl_add_u64 v[4:5], s[4:5], 0, v[4:5]
	v_lshl_add_u64 v[8:9], v[4:5], 0, v[132:133]
	global_load_dwordx4 v[4:7], v[8:9], off
	ds_read_b128 v[0:3], v0
	s_waitcnt lgkmcnt(0)
	v_lshlrev_b32_e32 v10, 16, v0
	v_and_b32_e32 v11, 0xffff0000, v0
	s_waitcnt vmcnt(0)
	v_lshlrev_b32_e32 v12, 16, v4
	v_and_b32_e32 v13, 0xffff0000, v4
	v_pk_mul_f32 v[10:11], v[10:11], v[12:13]
	v_lshlrev_b32_e32 v4, 16, v5
	v_cvt_pk_bf16_f32 v0, v10, v11
	v_lshlrev_b32_e32 v10, 16, v1
	v_and_b32_e32 v11, 0xffff0000, v1
	v_and_b32_e32 v5, 0xffff0000, v5
	v_pk_mul_f32 v[4:5], v[10:11], v[4:5]
	v_lshlrev_b32_e32 v10, 16, v6
	v_cvt_pk_bf16_f32 v1, v4, v5
	v_lshlrev_b32_e32 v4, 16, v2
	v_and_b32_e32 v5, 0xffff0000, v2
	v_and_b32_e32 v11, 0xffff0000, v6
	v_pk_mul_f32 v[4:5], v[4:5], v[10:11]
	v_lshlrev_b32_e32 v6, 16, v7
	v_cvt_pk_bf16_f32 v2, v4, v5
	v_lshlrev_b32_e32 v4, 16, v3
	v_and_b32_e32 v5, 0xffff0000, v3
	v_and_b32_e32 v7, 0xffff0000, v7
	v_pk_mul_f32 v[4:5], v[4:5], v[6:7]
	s_nop 0
	v_cvt_pk_bf16_f32 v3, v4, v5
	global_store_dwordx4 v[8:9], v[0:3], off
	s_nop 1
	v_mov_b32_e32 v0, v135
	s_nop 0
	v_add_u32_e32 v1, s1, v0
	v_add_u32_e32 v1, 0x600, v1
	v_lshlrev_b32_e32 v0, 4, v0
	v_ashrrev_i32_e32 v4, 5, v1
	v_and_b32_e32 v132, 0x1f0, v0
	v_mad_u64_u32 v[0:1], s[6:7], v4, s68, v[132:133]
	v_add_u32_e32 v4, s0, v4
	v_ashrrev_i32_e32 v5, 31, v4
	v_lshlrev_b64 v[4:5], 10, v[4:5]
	v_lshl_add_u64 v[4:5], s[4:5], 0, v[4:5]
	v_lshl_add_u64 v[8:9], v[4:5], 0, v[132:133]
	global_load_dwordx4 v[4:7], v[8:9], off
	ds_read_b128 v[0:3], v0
	s_addk_i32 s1, 0x800
	s_cmpk_eq_i32 s1, 0x2000
	s_waitcnt lgkmcnt(0)
	v_lshlrev_b32_e32 v10, 16, v0
	v_and_b32_e32 v11, 0xffff0000, v0
	s_waitcnt vmcnt(0)
	v_lshlrev_b32_e32 v12, 16, v4
	v_and_b32_e32 v13, 0xffff0000, v4
	v_pk_mul_f32 v[10:11], v[10:11], v[12:13]
	v_lshlrev_b32_e32 v4, 16, v5
	v_cvt_pk_bf16_f32 v0, v10, v11
	v_lshlrev_b32_e32 v10, 16, v1
	v_and_b32_e32 v11, 0xffff0000, v1
	v_and_b32_e32 v5, 0xffff0000, v5
	v_pk_mul_f32 v[4:5], v[10:11], v[4:5]
	v_lshlrev_b32_e32 v10, 16, v6
	v_cvt_pk_bf16_f32 v1, v4, v5
	v_lshlrev_b32_e32 v4, 16, v2
	v_and_b32_e32 v5, 0xffff0000, v2
	v_and_b32_e32 v11, 0xffff0000, v6
	v_pk_mul_f32 v[4:5], v[4:5], v[10:11]
	v_lshlrev_b32_e32 v6, 16, v7
	v_cvt_pk_bf16_f32 v2, v4, v5
	v_lshlrev_b32_e32 v4, 16, v3
	v_and_b32_e32 v5, 0xffff0000, v3
	v_and_b32_e32 v7, 0xffff0000, v7
	v_pk_mul_f32 v[4:5], v[4:5], v[6:7]
	s_nop 0
	v_cvt_pk_bf16_f32 v3, v4, v5
	global_store_dwordx4 v[8:9], v[0:3], off
	s_cbranch_scc0 .LBB0_822
	s_add_i32 s16, s16, s72
	s_cmpk_gt_i32 s16, 0xff
	s_waitcnt lgkmcnt(0)
	s_barrier
	s_cbranch_scc0 .LBB0_817

; DI int tid_() { int t = threadIdx.x; asm volatile("" : "+v"(t)); return t; }
; DI void phase_outproj(const Params& P, char* shm) {
;     ...
; #pragma unroll
;     for (int m = 0; m < 8; ++m)
; #pragma unroll
;       for (int n = 0; n < 2; ++n) {
;         const int row = wr * 128 + m * 16 + fr, col = wc * 32 + n * 16 + fq * 4;
;         u32x2 o = {pack2(sum[m][n][0], sum[m][n][1]), pack2(sum[m][n][2], sum[m][n][3])};
;         *(u32x2*)(shm + row * 272 + col * 2) = o;
;       }
;     __syncthreads();
; #pragma unroll
;     for (int i = 0; i < 8; ++i) {
;       const int chunk = tid_() + i * 512, row = chunk >> 4, c8 = (chunk & 15) * 8;
;       const i32x4 v = *(const i32x4*)(shm + row * 272 + c8 * 2);
;       *(i32x4*)(merged + (size_t)(brow + row) * DM + bcol + c8) = v;
;     }
;     __syncthreads();
.LBB0_840:
	v_cvt_pk_bf16_f32 v0, v190, v191
	v_cvt_pk_bf16_f32 v1, v198, v199
	v_cvt_pk_bf16_f32 v2, v192, v193
	v_cvt_pk_bf16_f32 v3, v200, v201
	ds_write2_b64 v129, v[0:1], v[2:3] offset1:4
	v_cvt_pk_bf16_f32 v0, v186, v187
	v_cvt_pk_bf16_f32 v1, v194, v195
	v_cvt_pk_bf16_f32 v2, v188, v189
	v_cvt_pk_bf16_f32 v3, v196, v197
	v_add_u32_e32 v4, 0x1000, v129
	ds_write2_b64 v4, v[0:1], v[2:3] offset0:32 offset1:36
	v_cvt_pk_bf16_f32 v0, v178, v179
	v_cvt_pk_bf16_f32 v1, v182, v183
	v_cvt_pk_bf16_f32 v2, v180, v181
	v_cvt_pk_bf16_f32 v3, v184, v185
	v_add_u32_e32 v4, 0x2000, v129
	ds_write2_b64 v4, v[0:1], v[2:3] offset0:64 offset1:68
	v_cvt_pk_bf16_f32 v0, v170, v171
	v_cvt_pk_bf16_f32 v1, v174, v175
	v_cvt_pk_bf16_f32 v2, v172, v173
	v_cvt_pk_bf16_f32 v3, v176, v177
	v_add_u32_e32 v4, 0x3000, v129
	ds_write2_b64 v4, v[0:1], v[2:3] offset0:96 offset1:100
	v_cvt_pk_bf16_f32 v0, v162, v163
	v_cvt_pk_bf16_f32 v1, v166, v167
	v_cvt_pk_bf16_f32 v2, v164, v165
	v_cvt_pk_bf16_f32 v3, v168, v169
	v_add_u32_e32 v4, 0x4000, v129
	ds_write2_b64 v4, v[0:1], v[2:3] offset0:128 offset1:132
	v_cvt_pk_bf16_f32 v0, v154, v155
	v_cvt_pk_bf16_f32 v1, v158, v159
	v_cvt_pk_bf16_f32 v2, v156, v157
	v_cvt_pk_bf16_f32 v3, v160, v161
	v_add_u32_e32 v4, 0x5000, v129
	ds_write2_b64 v4, v[0:1], v[2:3] offset0:160 offset1:164
	v_cvt_pk_bf16_f32 v0, v146, v147
	v_cvt_pk_bf16_f32 v1, v150, v151
	v_cvt_pk_bf16_f32 v2, v148, v149
	v_cvt_pk_bf16_f32 v3, v152, v153
	v_add_u32_e32 v4, 0x6000, v129
	ds_write2_b64 v4, v[0:1], v[2:3] offset0:192 offset1:196
	v_cvt_pk_bf16_f32 v0, v138, v139
	v_cvt_pk_bf16_f32 v1, v142, v143
	v_cvt_pk_bf16_f32 v2, v140, v141
	v_cvt_pk_bf16_f32 v3, v144, v145
	v_add_u32_e32 v4, 0x7000, v129
	ds_write2_b64 v4, v[0:1], v[2:3] offset0:224 offset1:228
	v_mov_b32_e32 v0, v135
	s_waitcnt vmcnt(0) lgkmcnt(0)
	s_barrier
	s_lshl_b64 s[4:5], s[4:5], 1
	v_ashrrev_i32_e32 v4, 4, v0
	v_lshlrev_b32_e32 v0, 4, v0
	v_and_b32_e32 v132, 0xf0, v0
	v_mad_u64_u32 v[0:1], s[8:9], v4, s71, v[132:133]
	ds_read_b128 v[0:3], v0
	v_add_u32_e32 v4, s0, v4
	s_add_u32 s4, s30, s4
	v_ashrrev_i32_e32 v5, 31, v4
	s_addc_u32 s5, s31, s5
	v_lshlrev_b64 v[4:5], 11, v[4:5]
	v_lshl_add_u64 v[4:5], s[4:5], 0, v[4:5]
	v_lshl_add_u64 v[4:5], v[4:5], 0, v[132:133]
	s_waitcnt lgkmcnt(0)
	global_store_dwordx4 v[4:5], v[0:3], off
	s_add_i32 s38, s38, s72
	s_cmpk_lt_i32 s38, 0x400
	v_mov_b32_e32 v0, v135
	s_nop 0
	v_add_u32_e32 v1, 0x200, v0
	v_lshlrev_b32_e32 v0, 4, v0
	v_ashrrev_i32_e32 v4, 4, v1
	v_and_b32_e32 v132, 0xf0, v0
	v_mad_u64_u32 v[0:1], s[8:9], v4, s71, v[132:133]
	ds_read_b128 v[0:3], v0
	v_add_u32_e32 v4, s0, v4
	v_ashrrev_i32_e32 v5, 31, v4
	v_lshlrev_b64 v[4:5], 11, v[4:5]
	v_lshl_add_u64 v[4:5], s[4:5], 0, v[4:5]
	v_lshl_add_u64 v[4:5], v[4:5], 0, v[132:133]
	s_waitcnt lgkmcnt(0)
	global_store_dwordx4 v[4:5], v[0:3], off
	s_nop 1
	v_mov_b32_e32 v0, v135
	s_nop 0
	v_add_u32_e32 v1, 0x400, v0
	v_lshlrev_b32_e32 v0, 4, v0
	v_ashrrev_i32_e32 v4, 4, v1
	v_and_b32_e32 v132, 0xf0, v0
	v_mad_u64_u32 v[0:1], s[8:9], v4, s71, v[132:133]
	ds_read_b128 v[0:3], v0
	v_add_u32_e32 v4, s0, v4
	v_ashrrev_i32_e32 v5, 31, v4
	v_lshlrev_b64 v[4:5], 11, v[4:5]
	v_lshl_add_u64 v[4:5], s[4:5], 0, v[4:5]
	v_lshl_add_u64 v[4:5], v[4:5], 0, v[132:133]
	s_waitcnt lgkmcnt(0)
	global_store_dwordx4 v[4:5], v[0:3], off
	s_nop 1
	v_mov_b32_e32 v0, v135
	s_nop 0
	v_add_u32_e32 v1, 0x600, v0
	v_lshlrev_b32_e32 v0, 4, v0
	v_ashrrev_i32_e32 v4, 4, v1
	v_and_b32_e32 v132, 0xf0, v0
	v_mad_u64_u32 v[0:1], s[8:9], v4, s71, v[132:133]
	ds_read_b128 v[0:3], v0
	v_add_u32_e32 v4, s0, v4
	v_ashrrev_i32_e32 v5, 31, v4
	v_lshlrev_b64 v[4:5], 11, v[4:5]
	v_lshl_add_u64 v[4:5], s[4:5], 0, v[4:5]
	v_lshl_add_u64 v[4:5], v[4:5], 0, v[132:133]
	s_waitcnt lgkmcnt(0)
	global_store_dwordx4 v[4:5], v[0:3], off
	s_nop 1
	v_mov_b32_e32 v0, v135
	s_nop 0
	v_add_u32_e32 v1, 0x800, v0
	v_lshlrev_b32_e32 v0, 4, v0
	v_ashrrev_i32_e32 v4, 4, v1
	v_and_b32_e32 v132, 0xf0, v0
	v_mad_u64_u32 v[0:1], s[8:9], v4, s71, v[132:133]
	ds_read_b128 v[0:3], v0
	v_add_u32_e32 v4, s0, v4
	v_ashrrev_i32_e32 v5, 31, v4
	v_lshlrev_b64 v[4:5], 11, v[4:5]
	v_lshl_add_u64 v[4:5], s[4:5], 0, v[4:5]
	v_lshl_add_u64 v[4:5], v[4:5], 0, v[132:133]
	s_waitcnt lgkmcnt(0)
	global_store_dwordx4 v[4:5], v[0:3], off
	s_nop 1
	v_mov_b32_e32 v0, v135
	s_nop 0
	v_add_u32_e32 v1, 0xa00, v0
	v_lshlrev_b32_e32 v0, 4, v0
	v_ashrrev_i32_e32 v4, 4, v1
	v_and_b32_e32 v132, 0xf0, v0
	v_mad_u64_u32 v[0:1], s[8:9], v4, s71, v[132:133]
	ds_read_b128 v[0:3], v0
	v_add_u32_e32 v4, s0, v4
	v_ashrrev_i32_e32 v5, 31, v4
	v_lshlrev_b64 v[4:5], 11, v[4:5]
	v_lshl_add_u64 v[4:5], s[4:5], 0, v[4:5]
	v_lshl_add_u64 v[4:5], v[4:5], 0, v[132:133]
	s_waitcnt lgkmcnt(0)
	global_store_dwordx4 v[4:5], v[0:3], off
	s_nop 1
	v_mov_b32_e32 v0, v135
	s_nop 0
	v_add_u32_e32 v1, 0xc00, v0
	v_lshlrev_b32_e32 v0, 4, v0
	v_ashrrev_i32_e32 v4, 4, v1
	v_and_b32_e32 v132, 0xf0, v0
	v_mad_u64_u32 v[0:1], s[8:9], v4, s71, v[132:133]
	ds_read_b128 v[0:3], v0
	v_add_u32_e32 v4, s0, v4
	v_ashrrev_i32_e32 v5, 31, v4
	v_lshlrev_b64 v[4:5], 11, v[4:5]
	v_lshl_add_u64 v[4:5], s[4:5], 0, v[4:5]
	v_lshl_add_u64 v[4:5], v[4:5], 0, v[132:133]
	s_waitcnt lgkmcnt(0)
	global_store_dwordx4 v[4:5], v[0:3], off
	s_nop 1
	v_mov_b32_e32 v0, v135
	s_nop 0
	v_add_u32_e32 v1, 0xe00, v0
	v_lshlrev_b32_e32 v0, 4, v0
	v_ashrrev_i32_e32 v4, 4, v1
	v_and_b32_e32 v132, 0xf0, v0
	v_mad_u64_u32 v[0:1], s[8:9], v4, s71, v[132:133]
	ds_read_b128 v[0:3], v0
	v_add_u32_e32 v4, s0, v4
	v_ashrrev_i32_e32 v5, 31, v4
	v_lshlrev_b64 v[4:5], 11, v[4:5]
	v_lshl_add_u64 v[4:5], s[4:5], 0, v[4:5]
	v_lshl_add_u64 v[4:5], v[4:5], 0, v[132:133]
	s_waitcnt lgkmcnt(0)
	global_store_dwordx4 v[4:5], v[0:3], off
	s_waitcnt lgkmcnt(0)
	s_barrier
	s_cbranch_scc0 .LBB0_855

; DI void phase_outproj(const Params& P, char* shm) {
;     ...
;     O_ISSUE(0, 0, 0);
;     O_ISSUE(0, 1, 1);
;     asm volatile("s_waitcnt vmcnt(6)" ::: "memory");
;     asm volatile("s_waitcnt lgkmcnt(0)" ::: "memory");
;     __builtin_amdgcn_s_barrier();
;     int cur = 0, nxt = 2;
.LBB0_844:
	s_mul_i32 s98, s11, 0xc000
	v_or_b32_e32 v92, s98, v220
	v_add_u32_e32 v96, s98, v219
	ds_read_b128 v[12:15], v92 offset:32768
	ds_read_b128 v[28:31], v92 offset:34816
	ds_read_b128 v[36:39], v96
	ds_read_b128 v[40:43], v96 offset:2048
	ds_read_b128 v[48:51], v96 offset:4096
	ds_read_b128 v[52:55], v96 offset:6144
	ds_read_b128 v[60:63], v96 offset:8192
	ds_read_b128 v[68:71], v96 offset:10240
	ds_read_b128 v[72:75], v96 offset:12288
	ds_read_b128 v[80:83], v96 offset:14336
	s_cmp_eq_u32 s19, 0
	s_cbranch_scc1 .Lpg844_first
	v_mfma_f32_16x16x32_bf16 v[124:127], v[84:87], v[108:111], v[124:127]
	s_cmp_lt_u32 s19, 14
	s_cselect_b64 vcc, -1, 0
	s_and_b64 s[20:21], vcc, exec
	s_cselect_b32 s22, 2, -14
	v_mfma_f32_16x16x32_bf16 v[120:123], v[104:107], v[108:111], v[120:123]
	s_cselect_b32 s21, s9, s13
	s_cselect_b32 s20, s8, s12
	s_add_i32 s24, s22, s19
	s_mul_i32 s22, s45, 0xc000
	v_mfma_f32_16x16x32_bf16 v[112:115], v[84:87], v[116:119], v[112:115]
	v_add_u32_e32 v93, s22, v217
	v_cndmask_b32_e32 v97, v218, v128, vcc
	v_readfirstlane_b32 s22, v93
	v_lshl_add_u32 v94, s24, 6, v97
	v_mfma_f32_16x16x32_bf16 v[100:103], v[104:107], v[116:119], v[100:103]
	s_mov_b32 m0, s22
	s_and_b64 s[22:23], vcc, exec
	v_ashrrev_i32_e32 v95, 31, v94
	s_cselect_b32 s22, 10, 9
	v_mfma_f32_16x16x32_bf16 v[88:91], v[84:87], v[222:225], v[88:91]
	v_lshlrev_b64 v[94:95], 1, v[94:95]
	s_lshl_b32 s23, 1, s22
	v_lshl_add_u64 v[98:99], s[20:21], 0, v[94:95]
	s_add_i32 s23, s24, s23
	v_mfma_f32_16x16x32_bf16 v[76:79], v[104:107], v[222:225], v[76:79]
	global_load_lds_dwordx4 v[98:99], off
	v_lshl_add_u32 v98, s23, 6, v97
	v_add_u32_e32 v248, 0x2000, v93
	v_ashrrev_i32_e32 v99, 31, v98
	v_mfma_f32_16x16x32_bf16 v[64:67], v[84:87], v[226:229], v[64:67]
	v_readfirstlane_b32 s23, v248
	v_lshlrev_b64 v[98:99], 1, v[98:99]
	s_mov_b32 m0, s23
	s_lshl_b32 s23, 2, s22
	v_mfma_f32_16x16x32_bf16 v[56:59], v[104:107], v[226:229], v[56:59]
	v_lshl_add_u64 v[246:247], s[20:21], 0, v[98:99]
	s_add_i32 s23, s24, s23
	global_load_lds_dwordx4 v[246:247], off
	v_lshl_add_u32 v246, s23, 6, v97
	v_mfma_f32_16x16x32_bf16 v[44:47], v[84:87], v[230:233], v[44:47]
	v_add_u32_e32 v248, 0x4000, v93
	v_ashrrev_i32_e32 v247, 31, v246
	v_readfirstlane_b32 s23, v248
	s_lshl_b32 s22, 3, s22
	v_mfma_f32_16x16x32_bf16 v[32:35], v[104:107], v[230:233], v[32:35]
	v_lshl_add_u64 v[246:247], v[246:247], 1, s[20:21]
	s_mov_b32 m0, s23
	s_add_i32 s24, s24, s22
	global_load_lds_dwordx4 v[246:247], off
	v_mfma_f32_16x16x32_bf16 v[24:27], v[84:87], v[234:237], v[24:27]
	v_lshl_add_u32 v246, s24, 6, v97
	v_ashrrev_i32_e32 v247, 31, v246
	v_add_u32_e32 v97, 0x6000, v93
	v_lshl_add_u64 v[246:247], v[246:247], 1, s[20:21]
	v_mfma_f32_16x16x32_bf16 v[20:23], v[104:107], v[234:237], v[20:23]
	v_readfirstlane_b32 s20, v97
	s_mov_b32 m0, s20
	s_and_b64 s[20:21], vcc, exec
	global_load_lds_dwordx4 v[246:247], off
	v_mfma_f32_16x16x32_bf16 v[16:19], v[84:87], v[238:241], v[16:19]
	v_add_u32_e32 v246, 0x8000, v93
	s_cselect_b32 s21, s17, s15
	s_cselect_b32 s20, s16, s14
	v_readfirstlane_b32 s22, v246
	v_mfma_f32_16x16x32_bf16 v[8:11], v[104:107], v[238:241], v[8:11]
	v_lshl_add_u64 v[94:95], s[20:21], 0, v[94:95]
	s_mov_b32 m0, s22
	s_nop 0
	global_load_lds_dwordx4 v[94:95], off
	v_mfma_f32_16x16x32_bf16 v[4:7], v[84:87], v[242:245], v[4:7]
	v_lshl_add_u64 v[94:95], s[20:21], 0, v[98:99]
	v_add_u32_e32 v98, 0xa000, v93
	s_nop 0
	v_readfirstlane_b32 s20, v98
	v_mfma_f32_16x16x32_bf16 v[0:3], v[104:107], v[242:245], v[0:3]
	s_mov_b32 m0, s20
	global_load_lds_dwordx4 v[94:95], off
	s_branch .Lpg844_main
.Lpg844_first:
	s_cmp_lt_u32 s19, 14
	s_cselect_b64 vcc, -1, 0
	s_and_b64 s[20:21], vcc, exec
	s_cselect_b32 s22, 2, -14
	s_cselect_b32 s21, s9, s13
	s_cselect_b32 s20, s8, s12
	s_add_i32 s24, s22, s19
	s_mul_i32 s22, s45, 0xc000
	v_add_u32_e32 v93, s22, v217
	v_cndmask_b32_e32 v97, v218, v128, vcc
	v_readfirstlane_b32 s22, v93
	v_lshl_add_u32 v94, s24, 6, v97
	s_mov_b32 m0, s22
	s_and_b64 s[22:23], vcc, exec
	v_ashrrev_i32_e32 v95, 31, v94
	s_cselect_b32 s22, 10, 9
	v_lshlrev_b64 v[94:95], 1, v[94:95]
	s_lshl_b32 s23, 1, s22
	v_lshl_add_u64 v[98:99], s[20:21], 0, v[94:95]
	s_add_i32 s23, s24, s23
	global_load_lds_dwordx4 v[98:99], off
	v_lshl_add_u32 v98, s23, 6, v97
	v_add_u32_e32 v248, 0x2000, v93
	v_ashrrev_i32_e32 v99, 31, v98
	v_readfirstlane_b32 s23, v248
	v_lshlrev_b64 v[98:99], 1, v[98:99]
	s_mov_b32 m0, s23
	s_lshl_b32 s23, 2, s22
	v_lshl_add_u64 v[246:247], s[20:21], 0, v[98:99]
	s_add_i32 s23, s24, s23
	global_load_lds_dwordx4 v[246:247], off
	v_lshl_add_u32 v246, s23, 6, v97
	v_add_u32_e32 v248, 0x4000, v93
	v_ashrrev_i32_e32 v247, 31, v246
	v_readfirstlane_b32 s23, v248
	s_lshl_b32 s22, 3, s22
	v_lshl_add_u64 v[246:247], v[246:247], 1, s[20:21]
	s_mov_b32 m0, s23
	s_add_i32 s24, s24, s22
	global_load_lds_dwordx4 v[246:247], off
	v_lshl_add_u32 v246, s24, 6, v97
	v_ashrrev_i32_e32 v247, 31, v246
	v_add_u32_e32 v97, 0x6000, v93
	v_lshl_add_u64 v[246:247], v[246:247], 1, s[20:21]
	v_readfirstlane_b32 s20, v97
	s_mov_b32 m0, s20
	s_and_b64 s[20:21], vcc, exec
	global_load_lds_dwordx4 v[246:247], off
	v_add_u32_e32 v246, 0x8000, v93
	s_cselect_b32 s21, s17, s15
	s_cselect_b32 s20, s16, s14
	v_readfirstlane_b32 s22, v246
	v_lshl_add_u64 v[94:95], s[20:21], 0, v[94:95]
	s_mov_b32 m0, s22
	s_nop 0
	global_load_lds_dwordx4 v[94:95], off
	v_lshl_add_u64 v[94:95], s[20:21], 0, v[98:99]
	v_add_u32_e32 v98, 0xa000, v93
	s_nop 0
	v_readfirstlane_b32 s20, v98
	s_mov_b32 m0, s20
	global_load_lds_dwordx4 v[94:95], off
; DI void phase_outproj(const Params& P, char* shm) {
;     ...
; #pragma clang loop unroll(disable)
;     for (int x = 0; x < 4; ++x) {
; #pragma unroll
;       for (int m = 0; m < 8; ++m) { acc[m][0] = f32x4{0.f, 0.f, 0.f, 0.f}; acc[m][1] = f32x4{0.f, 0.f, 0.f, 0.f}; }
; #pragma clang loop unroll(disable)
;       for (int r = 0; r < 16; ++r) {
;         O_ISSUE(x, r + 2, nxt);
;         O_COMPUTE();
;         asm volatile("s_waitcnt vmcnt(6)" ::: "memory");
;         O_ROTATE();
;       }
.Lpg844_main:
	s_waitcnt lgkmcnt(7)
	v_mfma_f32_16x16x32_bf16 v[124:127], v[12:15], v[36:39], v[124:127]
	ds_read_b128 v[84:87], v92 offset:33792
	v_mfma_f32_16x16x32_bf16 v[120:123], v[28:31], v[36:39], v[120:123]
	ds_read_b128 v[104:107], v92 offset:35840
	s_waitcnt lgkmcnt(8)
	v_mfma_f32_16x16x32_bf16 v[112:115], v[12:15], v[40:43], v[112:115]
	v_mfma_f32_16x16x32_bf16 v[100:103], v[28:31], v[40:43], v[100:103]
	ds_read_b128 v[108:111], v96 offset:1024
	s_waitcnt lgkmcnt(8)
	v_mfma_f32_16x16x32_bf16 v[88:91], v[12:15], v[48:51], v[88:91]
	ds_read_b128 v[116:119], v96 offset:3072
	v_mfma_f32_16x16x32_bf16 v[76:79], v[28:31], v[48:51], v[76:79]
	s_waitcnt lgkmcnt(8)
	v_mfma_f32_16x16x32_bf16 v[64:67], v[12:15], v[52:55], v[64:67]
	ds_read_b128 v[222:225], v96 offset:5120
	v_mfma_f32_16x16x32_bf16 v[56:59], v[28:31], v[52:55], v[56:59]
	ds_read_b128 v[226:229], v96 offset:7168
	s_waitcnt lgkmcnt(9)
	v_mfma_f32_16x16x32_bf16 v[44:47], v[12:15], v[60:63], v[44:47]
	v_mfma_f32_16x16x32_bf16 v[32:35], v[28:31], v[60:63], v[32:35]
	ds_read_b128 v[230:233], v96 offset:9216
	s_waitcnt lgkmcnt(9)
	v_mfma_f32_16x16x32_bf16 v[24:27], v[12:15], v[68:71], v[24:27]
	ds_read_b128 v[234:237], v96 offset:11264
	v_mfma_f32_16x16x32_bf16 v[20:23], v[28:31], v[68:71], v[20:23]
	s_waitcnt lgkmcnt(9)
	v_mfma_f32_16x16x32_bf16 v[16:19], v[12:15], v[72:75], v[16:19]
	ds_read_b128 v[238:241], v96 offset:13312
	v_mfma_f32_16x16x32_bf16 v[8:11], v[28:31], v[72:75], v[8:11]
	ds_read_b128 v[242:245], v96 offset:15360
	s_waitcnt lgkmcnt(10)
	v_mfma_f32_16x16x32_bf16 v[4:7], v[12:15], v[80:83], v[4:7]
	v_mfma_f32_16x16x32_bf16 v[0:3], v[28:31], v[80:83], v[0:3]
	s_waitcnt lgkmcnt(0)
	s_add_i32 s20, s11, 1
	s_cmp_lg_u32 s11, 2
	s_waitcnt vmcnt(6)
	s_cselect_b32 s11, s20, 0
	s_add_i32 s20, s45, 1
	s_waitcnt lgkmcnt(0)
	s_cmp_lg_u32 s45, 2
	s_cselect_b32 s45, s20, 0
	s_add_i32 s19, s19, 1
	s_cmp_eq_u32 s19, 16
	s_barrier
	s_cbranch_scc0 .LBB0_844
	v_mfma_f32_16x16x32_bf16 v[124:127], v[84:87], v[108:111], v[124:127]
	v_mfma_f32_16x16x32_bf16 v[120:123], v[104:107], v[108:111], v[120:123]
	v_mfma_f32_16x16x32_bf16 v[112:115], v[84:87], v[116:119], v[112:115]
	v_mfma_f32_16x16x32_bf16 v[100:103], v[104:107], v[116:119], v[100:103]
	v_mfma_f32_16x16x32_bf16 v[88:91], v[84:87], v[222:225], v[88:91]
	v_mfma_f32_16x16x32_bf16 v[76:79], v[104:107], v[222:225], v[76:79]
	v_mfma_f32_16x16x32_bf16 v[64:67], v[84:87], v[226:229], v[64:67]
	v_mfma_f32_16x16x32_bf16 v[56:59], v[104:107], v[226:229], v[56:59]
	v_mfma_f32_16x16x32_bf16 v[44:47], v[84:87], v[230:233], v[44:47]
	v_mfma_f32_16x16x32_bf16 v[32:35], v[104:107], v[230:233], v[32:35]
	v_mfma_f32_16x16x32_bf16 v[24:27], v[84:87], v[234:237], v[24:27]
	v_mfma_f32_16x16x32_bf16 v[20:23], v[104:107], v[234:237], v[20:23]
	v_mfma_f32_16x16x32_bf16 v[16:19], v[84:87], v[238:241], v[16:19]
	v_mfma_f32_16x16x32_bf16 v[8:11], v[104:107], v[238:241], v[8:11]
	v_mfma_f32_16x16x32_bf16 v[4:7], v[84:87], v[242:245], v[4:7]
	v_mfma_f32_16x16x32_bf16 v[0:3], v[104:107], v[242:245], v[0:3]
	s_nop 7
	s_nop 1
	s_cmp_lg_u32 s46, 3
	s_cselect_b64 s[16:17], -1, 0
	s_add_i32 s18, s44, s18
	s_ashr_i32 s19, s18, 31
	s_lshl_b64 s[18:19], s[18:19], 11
	s_add_u32 s18, s6, s18
	v_mov_b32_e32 v12, 0
	s_addc_u32 s19, s7, s19
	s_mov_b32 s47, 0
	s_mov_b32 s48, 0
	v_mov_b32_e32 v13, v12
	v_mov_b32_e32 v14, v12
	v_mov_b32_e32 v15, v12
	v_mov_b32_e32 v28, v12
	v_mov_b32_e32 v29, v12
	v_mov_b32_e32 v30, v12
	v_mov_b32_e32 v31, v12
	v_mov_b32_e32 v36, v12
	v_mov_b32_e32 v37, v12
	v_mov_b32_e32 v38, v12
	v_mov_b32_e32 v39, v12
	v_mov_b32_e32 v40, v12
	v_mov_b32_e32 v41, v12
	v_mov_b32_e32 v42, v12
	v_mov_b32_e32 v43, v12
	v_mov_b32_e32 v48, v12
	v_mov_b32_e32 v49, v12
	v_mov_b32_e32 v50, v12
	v_mov_b32_e32 v51, v12
	v_mov_b32_e32 v52, v12
	v_mov_b32_e32 v53, v12
	v_mov_b32_e32 v54, v12
	v_mov_b32_e32 v55, v12
	v_mov_b32_e32 v60, v12
	v_mov_b32_e32 v61, v12
	v_mov_b32_e32 v62, v12
	v_mov_b32_e32 v63, v12
	v_mov_b32_e32 v68, v12
	v_mov_b32_e32 v69, v12
	v_mov_b32_e32 v70, v12
	v_mov_b32_e32 v71, v12
	v_mov_b32_e32 v72, v12
	v_mov_b32_e32 v73, v12
	v_mov_b32_e32 v74, v12
	v_mov_b32_e32 v75, v12
	v_mov_b32_e32 v80, v12
	v_mov_b32_e32 v81, v12
	v_mov_b32_e32 v82, v12
	v_mov_b32_e32 v83, v12
	v_mov_b32_e32 v84, v12
	v_mov_b32_e32 v85, v12
	v_mov_b32_e32 v86, v12
	v_mov_b32_e32 v87, v12
	v_mov_b32_e32 v92, v12
	v_mov_b32_e32 v93, v12
	v_mov_b32_e32 v94, v12
	v_mov_b32_e32 v95, v12
	v_mov_b32_e32 v96, v12
	v_mov_b32_e32 v97, v12
	v_mov_b32_e32 v98, v12
	v_mov_b32_e32 v99, v12
	v_mov_b32_e32 v104, v12
	v_mov_b32_e32 v105, v12
	v_mov_b32_e32 v106, v12
	v_mov_b32_e32 v107, v12
	v_mov_b32_e32 v108, v12
	v_mov_b32_e32 v109, v12
	v_mov_b32_e32 v110, v12
	v_mov_b32_e32 v111, v12
	v_mov_b32_e32 v116, v12
	v_mov_b32_e32 v117, v12
	v_mov_b32_e32 v118, v12
	v_mov_b32_e32 v119, v12
	s_branch .LBB0_847

; DI int tid_() { int t = threadIdx.x; asm volatile("" : "+v"(t)); return t; }
; DI void phase_wo(const Params& P, const float* xin, char* shm) {
;     ...
; #pragma unroll
;     for (int ps = 0; ps < 2; ++ps) {
;       if (wr == ps) {
; #pragma unroll
;         for (int m = 0; m < 8; ++m)
; #pragma unroll
;           for (int n = 0; n < 4; ++n) {
;             const int row = m * 16 + fr, col = wc * 64 + n * 16 + fq * 4;
;             *(f32x4*)(shm + row * 1040 + col * 4) = acc[m][n];
;           }
;       }
;       __syncthreads();
; #pragma unroll 4
;       for (int i = 0; i < 16; ++i) {
;         const int chunk = tid_() + i * 512, row = chunk >> 6, c4 = (chunk & 63) * 4;
;         const f32x4 v = *(const f32x4*)(shm + row * 1040 + c4 * 4);
;         const size_t off = (size_t)(brow + ps * 128 + row) * DM + bcol + c4;
;         const f32x4 xv = *(const f32x4*)(xin + off);
;         *(f32x4*)(P.out + off) = xv + v;
;       }
;       __syncthreads();
;     }
.LBB0_879:
	s_nop 0
	v_mov_b32_e32 v148, v135
	s_nop 0
	v_add_u32_e32 v149, s11, v148
	v_ashrrev_i32_e32 v152, 6, v149
	v_lshlrev_b32_e32 v148, 2, v148
	v_and_b32_e32 v154, 0xfc, v148
	v_mul_lo_u32 v148, v152, s93
	v_add_u32_e32 v152, s10, v152
	v_ashrrev_i32_e32 v153, 31, v152
	v_lshlrev_b64 v[152:153], 10, v[152:153]
	v_lshl_add_u64 v[152:153], v[152:153], 0, s[8:9]
	v_or_b32_e32 v152, v152, v154
	v_lshlrev_b64 v[156:157], 2, v[152:153]
	v_lshl_add_u64 v[152:153], s[6:7], 0, v[156:157]
	v_lshl_add_u32 v148, v154, 2, v148
	global_load_dwordx4 v[152:155], v[152:153], off
	ds_read_b128 v[148:151], v148
	s_waitcnt vmcnt(0) lgkmcnt(0)
	v_pk_add_f32 v[150:151], v[150:151], v[154:155]
	v_pk_add_f32 v[148:149], v[148:149], v[152:153]
	v_lshl_add_u64 v[152:153], s[4:5], 0, v[156:157]
	global_store_dwordx4 v[152:153], v[148:151], off
	s_nop 1
	v_mov_b32_e32 v148, v135
	s_nop 0
	v_add_u32_e32 v149, s11, v148
	v_add_u32_e32 v149, 0x200, v149
	v_ashrrev_i32_e32 v152, 6, v149
	v_lshlrev_b32_e32 v148, 2, v148
	v_and_b32_e32 v154, 0xfc, v148
	v_mul_lo_u32 v148, v152, s93
	v_add_u32_e32 v152, s10, v152
	v_ashrrev_i32_e32 v153, 31, v152
	v_lshlrev_b64 v[152:153], 10, v[152:153]
	v_lshl_add_u64 v[152:153], v[152:153], 0, s[8:9]
	v_or_b32_e32 v152, v152, v154
	v_lshlrev_b64 v[156:157], 2, v[152:153]
	v_lshl_add_u64 v[152:153], s[6:7], 0, v[156:157]
	v_lshl_add_u32 v148, v154, 2, v148
	global_load_dwordx4 v[152:155], v[152:153], off
	ds_read_b128 v[148:151], v148
	s_waitcnt vmcnt(0) lgkmcnt(0)
	v_pk_add_f32 v[150:151], v[150:151], v[154:155]
	v_pk_add_f32 v[148:149], v[148:149], v[152:153]
	v_lshl_add_u64 v[152:153], s[4:5], 0, v[156:157]
	global_store_dwordx4 v[152:153], v[148:151], off
	s_nop 1
	v_mov_b32_e32 v148, v135
	s_nop 0
	v_add_u32_e32 v149, s11, v148
	v_add_u32_e32 v149, 0x400, v149
	v_ashrrev_i32_e32 v152, 6, v149
	v_lshlrev_b32_e32 v148, 2, v148
	v_and_b32_e32 v154, 0xfc, v148
	v_mul_lo_u32 v148, v152, s93
	v_add_u32_e32 v152, s10, v152
	v_ashrrev_i32_e32 v153, 31, v152
	v_lshlrev_b64 v[152:153], 10, v[152:153]
	v_lshl_add_u64 v[152:153], v[152:153], 0, s[8:9]
	v_or_b32_e32 v152, v152, v154
	v_lshlrev_b64 v[156:157], 2, v[152:153]
	v_lshl_add_u64 v[152:153], s[6:7], 0, v[156:157]
	v_lshl_add_u32 v148, v154, 2, v148
	global_load_dwordx4 v[152:155], v[152:153], off
	ds_read_b128 v[148:151], v148
	s_waitcnt vmcnt(0) lgkmcnt(0)
	v_pk_add_f32 v[150:151], v[150:151], v[154:155]
	v_pk_add_f32 v[148:149], v[148:149], v[152:153]
	v_lshl_add_u64 v[152:153], s[4:5], 0, v[156:157]
	global_store_dwordx4 v[152:153], v[148:151], off
	s_nop 1
	v_mov_b32_e32 v148, v135
	s_nop 0
	v_add_u32_e32 v149, s11, v148
	v_add_u32_e32 v149, 0x600, v149
	v_ashrrev_i32_e32 v152, 6, v149
	v_lshlrev_b32_e32 v148, 2, v148
	v_and_b32_e32 v154, 0xfc, v148
	v_mul_lo_u32 v148, v152, s93
	v_add_u32_e32 v152, s10, v152
	v_ashrrev_i32_e32 v153, 31, v152
	v_lshlrev_b64 v[152:153], 10, v[152:153]
	v_lshl_add_u64 v[152:153], v[152:153], 0, s[8:9]
	v_or_b32_e32 v152, v152, v154
	v_lshlrev_b64 v[156:157], 2, v[152:153]
	v_lshl_add_u64 v[152:153], s[6:7], 0, v[156:157]
	v_lshl_add_u32 v148, v154, 2, v148
	global_load_dwordx4 v[152:155], v[152:153], off
	ds_read_b128 v[148:151], v148
	s_addk_i32 s11, 0x800
	s_cmpk_eq_i32 s11, 0x2000
	s_waitcnt vmcnt(0) lgkmcnt(0)
	v_pk_add_f32 v[150:151], v[150:151], v[154:155]
	v_pk_add_f32 v[148:149], v[148:149], v[152:153]
	v_lshl_add_u64 v[152:153], s[4:5], 0, v[156:157]
	global_store_dwordx4 v[152:153], v[148:151], off
	s_cbranch_scc0 .LBB0_879
	s_waitcnt lgkmcnt(0)
	s_barrier
	s_and_saveexec_b64 s[12:13], s[0:1]
	s_cbranch_execz .LBB0_882
	ds_write_b128 v128, v[124:127]
	ds_write_b128 v128, v[120:123] offset:64
	ds_write_b128 v128, v[116:119] offset:128
	ds_write_b128 v128, v[112:115] offset:192
	ds_write_b128 v128, v[108:111] offset:16640
	ds_write_b128 v128, v[104:107] offset:16704
	ds_write_b128 v128, v[100:103] offset:16768
	ds_write_b128 v128, v[96:99] offset:16832
	ds_write_b128 v128, v[92:95] offset:33280
	ds_write_b128 v128, v[88:91] offset:33344
	ds_write_b128 v128, v[84:87] offset:33408
	ds_write_b128 v128, v[80:83] offset:33472
	ds_write_b128 v128, v[76:79] offset:49920
	ds_write_b128 v128, v[72:75] offset:49984
	ds_write_b128 v128, v[68:71] offset:50048
	ds_write_b128 v128, v[64:67] offset:50112
	ds_write_b128 v129, v[60:63]
	ds_write_b128 v130, v[56:59]
	ds_write_b128 v131, v[52:55]
	ds_write_b128 v132, v[48:51]
	ds_write_b128 v136, v[44:47]
	ds_write_b128 v137, v[40:43]
	ds_write_b128 v138, v[36:39]
	ds_write_b128 v139, v[32:35]
	ds_write_b128 v140, v[28:31]
	ds_write_b128 v141, v[24:27]
	ds_write_b128 v142, v[16:19]
	ds_write_b128 v143, v[12:15]
	ds_write_b128 v144, v[8:11]
	ds_write_b128 v145, v[4:7]
	ds_write_b128 v146, v[0:3]
	ds_write_b128 v147, v[20:23]

; DI int tid_() { int t = threadIdx.x; asm volatile("" : "+v"(t)); return t; }
; DI void phase_wo(const Params& P, const float* xin, char* shm) {
;     ...
; #pragma unroll 4
;       for (int i = 0; i < 16; ++i) {
;         const int chunk = tid_() + i * 512, row = chunk >> 6, c4 = (chunk & 63) * 4;
;         const f32x4 v = *(const f32x4*)(shm + row * 1040 + c4 * 4);
;         const size_t off = (size_t)(brow + ps * 128 + row) * DM + bcol + c4;
;         const f32x4 xv = *(const f32x4*)(xin + off);
;         *(f32x4*)(P.out + off) = xv + v;
;       }
;       __syncthreads();
;     }
;   }
.LBB0_883:
	s_nop 0
	v_mov_b32_e32 v0, v135
	s_nop 0
	v_add_u32_e32 v1, s11, v0
	v_ashrrev_i32_e32 v4, 6, v1
	v_lshlrev_b32_e32 v0, 2, v0
	v_and_b32_e32 v6, 0xfc, v0
	v_mul_lo_u32 v0, v4, s93
	v_add_u32_e32 v4, s10, v4
	v_ashrrev_i32_e32 v5, 31, v4
	v_lshlrev_b64 v[4:5], 10, v[4:5]
	v_lshl_add_u64 v[4:5], v[4:5], 0, s[8:9]
	v_or_b32_e32 v4, v4, v6
	v_lshlrev_b64 v[8:9], 2, v[4:5]
	v_lshl_add_u64 v[4:5], s[6:7], 0, v[8:9]
	v_lshl_add_u32 v0, v6, 2, v0
	global_load_dwordx4 v[4:7], v[4:5], off
	ds_read_b128 v[0:3], v0
	s_waitcnt vmcnt(0) lgkmcnt(0)
	v_pk_add_f32 v[2:3], v[2:3], v[6:7]
	v_pk_add_f32 v[0:1], v[0:1], v[4:5]
	v_lshl_add_u64 v[4:5], s[4:5], 0, v[8:9]
	global_store_dwordx4 v[4:5], v[0:3], off
	s_nop 1
	v_mov_b32_e32 v0, v135
	s_nop 0
	v_add_u32_e32 v1, s11, v0
	v_add_u32_e32 v1, 0x200, v1
	v_ashrrev_i32_e32 v4, 6, v1
	v_lshlrev_b32_e32 v0, 2, v0
	v_and_b32_e32 v6, 0xfc, v0
	v_mul_lo_u32 v0, v4, s93
	v_add_u32_e32 v4, s10, v4
	v_ashrrev_i32_e32 v5, 31, v4
	v_lshlrev_b64 v[4:5], 10, v[4:5]
	v_lshl_add_u64 v[4:5], v[4:5], 0, s[8:9]
	v_or_b32_e32 v4, v4, v6
	v_lshlrev_b64 v[8:9], 2, v[4:5]
	v_lshl_add_u64 v[4:5], s[6:7], 0, v[8:9]
	v_lshl_add_u32 v0, v6, 2, v0
	global_load_dwordx4 v[4:7], v[4:5], off
	ds_read_b128 v[0:3], v0
	s_waitcnt vmcnt(0) lgkmcnt(0)
	v_pk_add_f32 v[2:3], v[2:3], v[6:7]
	v_pk_add_f32 v[0:1], v[0:1], v[4:5]
	v_lshl_add_u64 v[4:5], s[4:5], 0, v[8:9]
	global_store_dwordx4 v[4:5], v[0:3], off
	s_nop 1
	v_mov_b32_e32 v0, v135
	s_nop 0
	v_add_u32_e32 v1, s11, v0
	v_add_u32_e32 v1, 0x400, v1
	v_ashrrev_i32_e32 v4, 6, v1
	v_lshlrev_b32_e32 v0, 2, v0
	v_and_b32_e32 v6, 0xfc, v0
	v_mul_lo_u32 v0, v4, s93
	v_add_u32_e32 v4, s10, v4
	v_ashrrev_i32_e32 v5, 31, v4
	v_lshlrev_b64 v[4:5], 10, v[4:5]
	v_lshl_add_u64 v[4:5], v[4:5], 0, s[8:9]
	v_or_b32_e32 v4, v4, v6
	v_lshlrev_b64 v[8:9], 2, v[4:5]
	v_lshl_add_u64 v[4:5], s[6:7], 0, v[8:9]
	v_lshl_add_u32 v0, v6, 2, v0
	global_load_dwordx4 v[4:7], v[4:5], off
	ds_read_b128 v[0:3], v0
	s_waitcnt vmcnt(0) lgkmcnt(0)
	v_pk_add_f32 v[2:3], v[2:3], v[6:7]
	v_pk_add_f32 v[0:1], v[0:1], v[4:5]
	v_lshl_add_u64 v[4:5], s[4:5], 0, v[8:9]
	global_store_dwordx4 v[4:5], v[0:3], off
	s_nop 1
	v_mov_b32_e32 v0, v135
	s_nop 0
	v_add_u32_e32 v1, s11, v0
	v_add_u32_e32 v1, 0x600, v1
	v_ashrrev_i32_e32 v4, 6, v1
	v_lshlrev_b32_e32 v0, 2, v0
	v_and_b32_e32 v6, 0xfc, v0
	v_mul_lo_u32 v0, v4, s93
	v_add_u32_e32 v4, s10, v4
	v_ashrrev_i32_e32 v5, 31, v4
	v_lshlrev_b64 v[4:5], 10, v[4:5]
	v_lshl_add_u64 v[4:5], v[4:5], 0, s[8:9]
	v_or_b32_e32 v4, v4, v6
	v_lshlrev_b64 v[8:9], 2, v[4:5]
	v_lshl_add_u64 v[4:5], s[6:7], 0, v[8:9]
	v_lshl_add_u32 v0, v6, 2, v0
	global_load_dwordx4 v[4:7], v[4:5], off
	ds_read_b128 v[0:3], v0
	s_addk_i32 s11, 0x800
	s_cmpk_lg_i32 s11, 0x2000
	s_waitcnt vmcnt(0) lgkmcnt(0)
	v_pk_add_f32 v[2:3], v[2:3], v[6:7]
	v_pk_add_f32 v[0:1], v[0:1], v[4:5]
	v_lshl_add_u64 v[4:5], s[4:5], 0, v[8:9]
	global_store_dwordx4 v[4:5], v[0:3], off
	s_cbranch_scc1 .LBB0_883
	s_add_i32 s20, s20, s72
	s_cmpk_gt_i32 s20, 0x1ff
	s_waitcnt lgkmcnt(0)
	s_barrier
	s_cbranch_scc0 .LBB0_872

; DI void phase_norm(const float* xin, u16* hb) {
;     ...
;   for (int t = gw; t < T_TOK; t += nw) {
;     const float* r = xin + (size_t)t * DM;
;     float4 v[4];
;     float ss = 0.f;
; #pragma unroll
;     for (int i = 0; i < 4; ++i) {
;       v[i] = *(const float4*)(r + i * 256 + lane * 4);
;       ss += v[i].x * v[i].x + v[i].y * v[i].y + v[i].z * v[i].z + v[i].w * v[i].w;
;     }
; #pragma unroll
;     for (int o = 32; o > 0; o >>= 1) ss += __shfl_xor(ss, o);
;     const float rs = rsqrtf(ss * (1.f / DM) + EPS);
; #pragma unroll
;     for (int i = 0; i < 4; ++i) {
;       u32x2 o = {pack2(v[i].x * rs, v[i].y * rs), pack2(v[i].z * rs, v[i].w * rs)};
;       *(u32x2*)(hb + (size_t)t * DM + i * 256 + lane * 4) = o;
;     }
;   }
.LBB0_901:
	global_load_dwordx4 v[6:9], v[4:5], off
	global_load_dwordx4 v[10:13], v[4:5], off offset:1024
	v_add_u32_e32 v0, s84, v0
	s_waitcnt vmcnt(0) lgkmcnt(0)
	v_mov_b32_e32 v20, v7
	v_mov_b32_e32 v21, v11
	v_mov_b32_e32 v18, v6
	v_mov_b32_e32 v19, v10
	v_pk_mul_f32 v[20:21], v[20:21], v[20:21]
	v_mov_b32_e32 v14, v8
	v_mov_b32_e32 v15, v12
	v_pk_fma_f32 v[18:19], v[18:19], v[18:19], v[20:21]
	v_mov_b32_e32 v16, v9
	v_mov_b32_e32 v17, v13
	v_pk_fma_f32 v[14:15], v[14:15], v[14:15], v[18:19]
	s_nop 0
	v_pk_fma_f32 v[22:23], v[16:17], v[16:17], v[14:15]
	global_load_dwordx4 v[14:17], v[4:5], off offset:2048
	global_load_dwordx4 v[18:21], v[4:5], off offset:3072
	v_add_f32_e32 v1, v22, v23
	v_lshl_add_u64 v[4:5], v[4:5], 0, s[12:13]
	s_waitcnt vmcnt(0) lgkmcnt(0)
	v_mov_b32_e32 v30, v15
	v_mov_b32_e32 v31, v19
	v_mov_b32_e32 v28, v14
	v_mov_b32_e32 v29, v18
	v_pk_mul_f32 v[30:31], v[30:31], v[30:31]
	v_mov_b32_e32 v24, v16
	v_mov_b32_e32 v25, v20
	v_pk_fma_f32 v[28:29], v[28:29], v[28:29], v[30:31]
	v_mov_b32_e32 v26, v17
	v_mov_b32_e32 v27, v21
	v_pk_fma_f32 v[24:25], v[24:25], v[24:25], v[28:29]
	s_nop 0
	v_pk_fma_f32 v[24:25], v[26:27], v[26:27], v[24:25]
	s_nop 0
	v_add_f32_e32 v1, v1, v24
	v_add_f32_e32 v1, v1, v25
	ds_bpermute_b32 v22, v211, v1
	s_waitcnt lgkmcnt(0)
	v_add_f32_e32 v1, v1, v22
	ds_bpermute_b32 v22, v212, v1
	s_waitcnt lgkmcnt(0)
	v_add_f32_e32 v1, v1, v22
	ds_bpermute_b32 v22, v213, v1
	s_waitcnt lgkmcnt(0)
	v_add_f32_e32 v1, v1, v22
	ds_bpermute_b32 v22, v214, v1
	s_waitcnt lgkmcnt(0)
	v_add_f32_e32 v1, v1, v22
	ds_bpermute_b32 v22, v215, v1
	s_waitcnt lgkmcnt(0)
	v_add_f32_e32 v1, v1, v22
	ds_bpermute_b32 v22, v216, v1
	s_waitcnt lgkmcnt(0)
	v_add_f32_e32 v1, v1, v22
	v_fmamk_f32 v1, v1, 0x3a800000, v134
	v_cmp_gt_f32_e32 vcc, s33, v1
	v_mul_f32_e32 v22, 0x4b800000, v1
	s_nop 0
	v_cndmask_b32_e32 v1, v1, v22, vcc
	v_rsq_f32_e32 v1, v1
	s_nop 0
	v_mul_f32_e32 v22, 0x45800000, v1
	v_cndmask_b32_e32 v22, v1, v22, vcc
	v_pk_mul_f32 v[6:7], v[6:7], v[22:23] op_sel_hi:[1,0]
	v_pk_mul_f32 v[8:9], v[8:9], v[22:23] op_sel_hi:[1,0]
	v_cvt_pk_bf16_f32 v6, v6, v7
	v_cvt_pk_bf16_f32 v7, v8, v9
	global_store_dwordx2 v[2:3], v[6:7], off
	v_pk_mul_f32 v[6:7], v[10:11], v[22:23] op_sel_hi:[1,0]
	v_pk_mul_f32 v[8:9], v[12:13], v[22:23] op_sel_hi:[1,0]
	v_cvt_pk_bf16_f32 v6, v6, v7
	v_cvt_pk_bf16_f32 v7, v8, v9
	global_store_dwordx2 v[2:3], v[6:7], off offset:512
	v_pk_mul_f32 v[6:7], v[14:15], v[22:23] op_sel_hi:[1,0]
	v_pk_mul_f32 v[8:9], v[16:17], v[22:23] op_sel_hi:[1,0]
	v_cvt_pk_bf16_f32 v6, v6, v7
	v_cvt_pk_bf16_f32 v7, v8, v9
	global_store_dwordx2 v[2:3], v[6:7], off offset:1024
	v_pk_mul_f32 v[6:7], v[18:19], v[22:23] op_sel_hi:[1,0]
	v_pk_mul_f32 v[8:9], v[20:21], v[22:23] op_sel_hi:[1,0]
	v_cvt_pk_bf16_f32 v6, v6, v7
	v_cvt_pk_bf16_f32 v7, v8, v9
	v_cmp_lt_i32_e32 vcc, s60, v0
	global_store_dwordx2 v[2:3], v[6:7], off offset:1536
	v_lshl_add_u64 v[2:3], v[2:3], 0, s[10:11]
	s_or_b64 s[4:5], vcc, s[4:5]
	s_andn2_b64 exec, exec, s[4:5]
	s_cbranch_execnz .LBB0_901

; DI int tid_() { int t = threadIdx.x; asm volatile("" : "+v"(t)); return t; }
; DI void phase_ple(const Params& P, char* shm) {
;     ...
; #pragma unroll 4
;     for (int i = 0; i < 16; ++i) {
;       const int chunk = tid_() + i * 512, row = chunk >> 5, c4 = (chunk & 31) * 4;
;       const f32x4 v = *(const f32x4*)(shm + row * 528 + c4 * 4);
;       float* d = P.out + (size_t)(brow + row) * DM + bcol + c4;
;       *(f32x4*)d = *(const f32x4*)d + v;
;     }
;     __syncthreads();
;   }
.LBB0_935:
	s_nop 0
	v_mov_b32_e32 v0, v135
	s_nop 0
	v_add_u32_e32 v1, s5, v0
	v_lshlrev_b32_e32 v0, 4, v0
	v_ashrrev_i32_e32 v4, 5, v1
	v_and_b32_e32 v132, 0x1f0, v0
	v_mad_u64_u32 v[0:1], s[8:9], v4, s68, v[132:133]
	v_add_u32_e32 v4, s4, v4
	v_ashrrev_i32_e32 v5, 31, v4
	v_lshlrev_b64 v[4:5], 12, v[4:5]
	v_lshl_add_u64 v[4:5], s[6:7], 0, v[4:5]
	v_lshl_add_u64 v[8:9], v[4:5], 0, v[132:133]
	global_load_dwordx4 v[4:7], v[8:9], off
	ds_read_b128 v[0:3], v0
	s_waitcnt vmcnt(0) lgkmcnt(0)
	v_pk_add_f32 v[2:3], v[2:3], v[6:7]
	v_pk_add_f32 v[0:1], v[0:1], v[4:5]
	global_store_dwordx4 v[8:9], v[0:3], off
	s_nop 1
	v_mov_b32_e32 v0, v135
	s_nop 0
	v_add_u32_e32 v1, s5, v0
	v_add_u32_e32 v1, 0x200, v1
	v_lshlrev_b32_e32 v0, 4, v0
	v_ashrrev_i32_e32 v4, 5, v1
	v_and_b32_e32 v132, 0x1f0, v0
	v_mad_u64_u32 v[0:1], s[8:9], v4, s68, v[132:133]
	v_add_u32_e32 v4, s4, v4
	v_ashrrev_i32_e32 v5, 31, v4
	v_lshlrev_b64 v[4:5], 12, v[4:5]
	v_lshl_add_u64 v[4:5], s[6:7], 0, v[4:5]
	v_lshl_add_u64 v[8:9], v[4:5], 0, v[132:133]
	global_load_dwordx4 v[4:7], v[8:9], off
	ds_read_b128 v[0:3], v0
	s_waitcnt vmcnt(0) lgkmcnt(0)
	v_pk_add_f32 v[2:3], v[2:3], v[6:7]
	v_pk_add_f32 v[0:1], v[0:1], v[4:5]
	global_store_dwordx4 v[8:9], v[0:3], off
	s_nop 1
	v_mov_b32_e32 v0, v135
	s_nop 0
	v_add_u32_e32 v1, s5, v0
	v_add_u32_e32 v1, 0x400, v1
	v_lshlrev_b32_e32 v0, 4, v0
	v_ashrrev_i32_e32 v4, 5, v1
	v_and_b32_e32 v132, 0x1f0, v0
	v_mad_u64_u32 v[0:1], s[8:9], v4, s68, v[132:133]
	v_add_u32_e32 v4, s4, v4
	v_ashrrev_i32_e32 v5, 31, v4
	v_lshlrev_b64 v[4:5], 12, v[4:5]
	v_lshl_add_u64 v[4:5], s[6:7], 0, v[4:5]
	v_lshl_add_u64 v[8:9], v[4:5], 0, v[132:133]
	global_load_dwordx4 v[4:7], v[8:9], off
	ds_read_b128 v[0:3], v0
	s_waitcnt vmcnt(0) lgkmcnt(0)
	v_pk_add_f32 v[2:3], v[2:3], v[6:7]
	v_pk_add_f32 v[0:1], v[0:1], v[4:5]
	global_store_dwordx4 v[8:9], v[0:3], off
	s_nop 1
	v_mov_b32_e32 v0, v135
	s_nop 0
	v_add_u32_e32 v1, s5, v0
	v_add_u32_e32 v1, 0x600, v1
	v_lshlrev_b32_e32 v0, 4, v0
	v_ashrrev_i32_e32 v4, 5, v1
	v_and_b32_e32 v132, 0x1f0, v0
	v_mad_u64_u32 v[0:1], s[8:9], v4, s68, v[132:133]
	v_add_u32_e32 v4, s4, v4
	v_ashrrev_i32_e32 v5, 31, v4
	v_lshlrev_b64 v[4:5], 12, v[4:5]
	v_lshl_add_u64 v[4:5], s[6:7], 0, v[4:5]
	v_lshl_add_u64 v[8:9], v[4:5], 0, v[132:133]
	global_load_dwordx4 v[4:7], v[8:9], off
	ds_read_b128 v[0:3], v0
	s_addk_i32 s5, 0x800
	s_cmpk_eq_i32 s5, 0x2000
	s_waitcnt vmcnt(0) lgkmcnt(0)
	v_pk_add_f32 v[2:3], v[2:3], v[6:7]
	v_pk_add_f32 v[0:1], v[0:1], v[4:5]
	global_store_dwordx4 v[8:9], v[0:3], off
	s_cbranch_scc0 .LBB0_935
	s_add_i32 s24, s24, s72
	s_cmpk_gt_i32 s24, 0x3ff
	s_waitcnt lgkmcnt(0)
	s_barrier
	s_cbranch_scc0 .LBB0_918

; __global__ void __launch_bounds__(512) fwd_megakernel(Params P) {
;   __shared__ __attribute__((aligned(1024))) char shm[148480];
	.amdhsa_kernel _Z14fwd_megakernel6Params
		.amdhsa_group_segment_fixed_size 148480
		.amdhsa_private_segment_fixed_size 0
		.amdhsa_kernarg_size 472
		.amdhsa_user_sgpr_count 2
		.amdhsa_user_sgpr_dispatch_ptr 0
		.amdhsa_user_sgpr_queue_ptr 0
		.amdhsa_user_sgpr_kernarg_segment_ptr 1
		.amdhsa_user_sgpr_dispatch_id 0
		.amdhsa_user_sgpr_kernarg_preload_length 0
		.amdhsa_user_sgpr_kernarg_preload_offset 0
		.amdhsa_user_sgpr_private_segment_size 0
		.amdhsa_uses_dynamic_stack 0
		.amdhsa_enable_private_segment 0
		.amdhsa_system_sgpr_workgroup_id_x 1
		.amdhsa_system_sgpr_workgroup_id_y 0
		.amdhsa_system_sgpr_workgroup_id_z 0
		.amdhsa_system_sgpr_workgroup_info 0
		.amdhsa_system_vgpr_workitem_id 2
		.amdhsa_next_free_vgpr 254
		.amdhsa_next_free_sgpr 102
		.amdhsa_accum_offset 256
		.amdhsa_reserve_vcc 1
		.amdhsa_float_round_mode_32 0
		.amdhsa_float_round_mode_16_64 0
		.amdhsa_float_denorm_mode_32 3
		.amdhsa_float_denorm_mode_16_64 3
		.amdhsa_dx10_clamp 1
		.amdhsa_ieee_mode 1
		.amdhsa_fp16_overflow 0
		.amdhsa_tg_split 0
		.amdhsa_exception_fp_ieee_invalid_op 0
		.amdhsa_exception_fp_denorm_src 0
		.amdhsa_exception_fp_ieee_div_zero 0
		.amdhsa_exception_fp_ieee_overflow 0
		.amdhsa_exception_fp_ieee_underflow 0
		.amdhsa_exception_fp_ieee_inexact 0
		.amdhsa_exception_int_div_zero 0
	.end_amdhsa_kernel

amdhsa.kernels:
  - .agpr_count:     0
    .args:
      - .offset:         0
        .size:           216
        .value_kind:     by_value
      - .offset:         216
        .size:           4
        .value_kind:     hidden_block_count_x
      - .offset:         220
        .size:           4
        .value_kind:     hidden_block_count_y
      - .offset:         224
        .size:           4
        .value_kind:     hidden_block_count_z
      - .offset:         228
        .size:           2
        .value_kind:     hidden_group_size_x
      - .offset:         230
        .size:           2
        .value_kind:     hidden_group_size_y
      - .offset:         232
        .size:           2
        .value_kind:     hidden_group_size_z
      - .offset:         234
        .size:           2
        .value_kind:     hidden_remainder_x
      - .offset:         236
        .size:           2
        .value_kind:     hidden_remainder_y
      - .offset:         238
        .size:           2
        .value_kind:     hidden_remainder_z
      - .offset:         256
        .size:           8
        .value_kind:     hidden_global_offset_x
      - .offset:         264
        .size:           8
        .value_kind:     hidden_global_offset_y
      - .offset:         272
        .size:           8
        .value_kind:     hidden_global_offset_z
      - .offset:         280
        .size:           2
        .value_kind:     hidden_grid_dims
      - .offset:         304
        .size:           8
        .value_kind:     hidden_multigrid_sync_arg
    .group_segment_fixed_size: 148480
    .kernarg_segment_align: 8
    .kernarg_segment_size: 472
    .language:       OpenCL C
    .language_version:
      - 2
      - 0
    .max_flat_workgroup_size: 512
    .name:           _Z14fwd_megakernel6Params
    .private_segment_fixed_size: 0
    .sgpr_count:     108
    .sgpr_spill_count: 116
    .symbol:         _Z14fwd_megakernel6Params.kd
    .uniform_work_group_size: 1
    .uses_dynamic_stack: false
    .vgpr_count:     254
    .vgpr_spill_count: 0
    .wavefront_size: 64
